# strategy 7: all 16 K-loop LDS-DMA pieces per iteration addressed as SGPR base + 32-bit VGPR offset (saved bases + precomputed +0x80 offsets), no per-piece 64-bit VALU add; on top of v35
# speedup vs baseline: 1.0171x; 1.0036x over previous
; #define PG8_STAGE(bufoff, gbase, voff) do { _Pragma("unroll") for (int _i = 0; _i < 2; ++_i) \
;         __builtin_amdgcn_global_load_lds((const unsigned*)((const char*)(gbase) + (voff)[_i]), (PG8_LAS unsigned*)(lds + (bufoff) + ldsw + _i * 8192), 16, 0, 0); } while (0)
; #define PG8_LDA(dst, b, h) do { _Pragma("unroll") for (int m = 0; m < 4; ++m) _Pragma("unroll") for (int k = 0; k < 2; ++k) dst[m][k] = *(const PG8_LAS bf16x8*)(lds + PG8_SA(b, h) + aoff + m * 2048 + k * 1024); } while (0)
; #define PG8_LDB(dst, b, h) do { _Pragma("unroll") for (int n = 0; n < 2; ++n) _Pragma("unroll") for (int k = 0; k < 2; ++k) dst[n][k] = *(const PG8_LAS bf16x8*)(lds + PG8_SB(b, h) + boff + n * 2048 + k * 1024); } while (0)
; #define PG8_SCHED __builtin_amdgcn_sched_barrier(0)
; template <class Epi, class Sched, bool ALIGN_EPI = false, bool SP2 = false>
; __device__ __forceinline__ void gemm_phase(PG8_LAS unsigned char* lds, const Gemm g, const Sched& S, const Epi& E) {
;     ...
; #pragma unroll
;     for (int a = 0; a < 2; ++a)
; #pragma unroll
;         for (int b = 0; b < 2; ++b)
; #pragma unroll
;             for (int m = 0; m < 4; ++m)
; #pragma unroll
;                 for (int n = 0; n < 2; ++n) acc[a][b][m][n] = (f32x4){0.f, 0.f, 0.f, 0.f};
;     ...
;         const bool has_next = S.next(ui + 1, nxt);
;         const char* nA = has_next ? (const char*)g.A + (size_t)nxt.pm * tstep : cA; const char* nB = has_next ? (const char*)g.Bt + (size_t)nxt.pn * tstep : cB;
;         for (int t = 0; t < nt; t += 2) {
;             const bool last = (t == nt - 2);
;             const char* a1 = cA + (size_t)(t + 1) * kstep;
;             const char* a2 = last ? nA : cA + (size_t)(t + 2) * kstep; const char* b2 = last ? nB : cB + (size_t)(t + 2) * kstep;
;             const char* a3 = a2 + kstep; const char* b3 = b2 + kstep;
;             if (last && has_next) S.a_ready(nxt);
;             if constexpr (SP2) {
;             PG8_LDB(B0, 0, 0); PG8_LDB(B1, 0, 1); PG8_SCHED; PG8_LDA(At, 0, 0); PG8_STAGE(PG8_SA(1, 1), a1 + hstep, voffA);
.LBB0_65:
	s_ashr_i32 s35, s34, 31
	s_lshl_b64 s[36:37], s[34:35], 20
	s_add_u32 s36, s24, s36
	s_addc_u32 s37, s25, s37
	s_and_b64 s[38:39], s[4:5], exec
	s_cselect_b32 s35, s37, s41
	s_cselect_b32 s63, s36, s40
	s_ashr_i32 s31, s30, 31
	s_lshl_b64 s[38:39], s[30:31], 20
	s_add_u32 s38, s46, s38
	s_addc_u32 s39, s47, s39
	s_and_b64 s[44:45], s[4:5], exec
	s_cselect_b32 s31, s39, s43
	s_cselect_b32 s64, s38, s42
	s_add_u32 s40, s40, 0x80080
	s_addc_u32 s41, s41, 0
	s_add_u32 s65, s42, 0x100
	v_mov_b32_e32 v0, 0
	s_addc_u32 s67, s43, 0
	s_mov_b32 s68, -2
	v_mov_b32_e32 v1, v0
	v_mov_b32_e32 v2, v0
	v_mov_b32_e32 v3, v0
	v_mov_b32_e32 v4, v0
	v_mov_b32_e32 v5, v0
	v_mov_b32_e32 v6, v0
	v_mov_b32_e32 v7, v0
	v_mov_b32_e32 v8, v0
	v_mov_b32_e32 v9, v0
	v_mov_b32_e32 v10, v0
	v_mov_b32_e32 v11, v0
	v_mov_b32_e32 v12, v0
	v_mov_b32_e32 v13, v0
	v_mov_b32_e32 v14, v0
	v_mov_b32_e32 v15, v0
	v_mov_b32_e32 v24, v0
	v_mov_b32_e32 v25, v0
	v_mov_b32_e32 v26, v0
	v_mov_b32_e32 v27, v0
	v_mov_b32_e32 v28, v0
	v_mov_b32_e32 v29, v0
	v_mov_b32_e32 v30, v0
	v_mov_b32_e32 v31, v0
	v_mov_b32_e32 v40, v0
	v_mov_b32_e32 v41, v0
	v_mov_b32_e32 v42, v0
	v_mov_b32_e32 v43, v0
	v_mov_b32_e32 v44, v0
	v_mov_b32_e32 v45, v0
	v_mov_b32_e32 v46, v0
	v_mov_b32_e32 v47, v0
	v_mov_b32_e32 v16, v0
	v_mov_b32_e32 v17, v0
	v_mov_b32_e32 v18, v0
	v_mov_b32_e32 v19, v0
	v_mov_b32_e32 v20, v0
	v_mov_b32_e32 v21, v0
	v_mov_b32_e32 v22, v0
	v_mov_b32_e32 v23, v0
	v_mov_b32_e32 v32, v0
	v_mov_b32_e32 v33, v0
	v_mov_b32_e32 v34, v0
	v_mov_b32_e32 v35, v0
	v_mov_b32_e32 v36, v0
	v_mov_b32_e32 v37, v0
	v_mov_b32_e32 v38, v0
	v_mov_b32_e32 v39, v0
	v_mov_b32_e32 v48, v0
	v_mov_b32_e32 v49, v0
	v_mov_b32_e32 v50, v0
	v_mov_b32_e32 v51, v0
	v_mov_b32_e32 v52, v0
	v_mov_b32_e32 v53, v0
	v_mov_b32_e32 v54, v0
	v_mov_b32_e32 v55, v0
	v_mov_b32_e32 v56, v0
	v_mov_b32_e32 v57, v0
	v_mov_b32_e32 v58, v0
	v_mov_b32_e32 v59, v0
	v_mov_b32_e32 v60, v0
	v_mov_b32_e32 v61, v0
	v_mov_b32_e32 v62, v0
	v_mov_b32_e32 v63, v0
	v_mov_b32_e32 v64, v0
	v_mov_b32_e32 v65, v0
	v_mov_b32_e32 v66, v0
	v_mov_b32_e32 v67, v0
	v_mov_b32_e32 v68, v0
	v_mov_b32_e32 v69, v0
	v_mov_b32_e32 v70, v0
	v_mov_b32_e32 v71, v0
	v_mov_b32_e32 v72, v0
	v_mov_b32_e32 v73, v0
	v_mov_b32_e32 v74, v0
	v_mov_b32_e32 v75, v0
	v_mov_b32_e32 v76, v0
	v_mov_b32_e32 v77, v0
	v_mov_b32_e32 v78, v0
	v_mov_b32_e32 v79, v0
	v_mov_b32_e32 v88, v0
	v_mov_b32_e32 v89, v0
	v_mov_b32_e32 v90, v0
	v_mov_b32_e32 v91, v0
	v_mov_b32_e32 v92, v0
	v_mov_b32_e32 v93, v0
	v_mov_b32_e32 v94, v0
	v_mov_b32_e32 v95, v0
	v_mov_b32_e32 v104, v0
	v_mov_b32_e32 v105, v0
	v_mov_b32_e32 v106, v0
	v_mov_b32_e32 v107, v0
	v_mov_b32_e32 v108, v0
	v_mov_b32_e32 v109, v0
	v_mov_b32_e32 v110, v0
	v_mov_b32_e32 v111, v0
	v_mov_b32_e32 v80, v0
	v_mov_b32_e32 v81, v0
	v_mov_b32_e32 v82, v0
	v_mov_b32_e32 v83, v0
	v_mov_b32_e32 v84, v0
	v_mov_b32_e32 v85, v0
	v_mov_b32_e32 v86, v0
	v_mov_b32_e32 v87, v0
	v_mov_b32_e32 v96, v0
	v_mov_b32_e32 v97, v0
	v_mov_b32_e32 v98, v0
	v_mov_b32_e32 v99, v0
	v_mov_b32_e32 v100, v0
	v_mov_b32_e32 v101, v0
	v_mov_b32_e32 v102, v0
	v_mov_b32_e32 v103, v0
	v_mov_b32_e32 v112, v0
	v_mov_b32_e32 v113, v0
	v_mov_b32_e32 v114, v0
	v_mov_b32_e32 v115, v0
	v_mov_b32_e32 v116, v0
	v_mov_b32_e32 v117, v0
	v_mov_b32_e32 v118, v0
	v_mov_b32_e32 v119, v0
	v_mov_b32_e32 v120, v0
	v_mov_b32_e32 v121, v0
	v_mov_b32_e32 v122, v0
	v_mov_b32_e32 v123, v0
	v_mov_b32_e32 v124, v0
	v_mov_b32_e32 v125, v0
	v_mov_b32_e32 v126, v0
	v_mov_b32_e32 v127, v0
	v_add_u32_e32 v253, 0x80, v130
	v_add_u32_e32 v252, 0x80, v134
	v_add_u32_e32 v251, 0x80, v128
	v_add_u32_e32 v250, 0x80, v132
.LBB0_66:
	ds_read_b128 v[152:155], v149
	ds_read_b128 v[156:159], v149 offset:1024
	ds_read_b128 v[160:163], v149 offset:2048
	ds_read_b128 v[164:167], v149 offset:3072
	ds_read_b128 v[168:171], v150
	ds_read_b128 v[172:175], v150 offset:1024
	ds_read_b128 v[176:179], v150 offset:2048
	ds_read_b128 v[180:183], v150 offset:3072
	s_add_u32 s42, s40, 0xfff80080
	s_addc_u32 s43, s41, -1
	s_cmp_eq_u32 s68, 28
	s_cselect_b32 s45, s35, s43
	s_cselect_b32 s44, s63, s42
	s_cselect_b32 s43, s31, s67
	s_cselect_b32 s42, s64, s65
	s_nop 0
	s_add_i32 m0, s29, 0xc000
	ds_read_b128 v[184:187], v151
	ds_read_b128 v[188:191], v151 offset:1024
	ds_read_b128 v[192:195], v151 offset:2048
	ds_read_b128 v[196:199], v151 offset:3072
	ds_read_b128 v[200:203], v151 offset:4096
	ds_read_b128 v[204:207], v151 offset:5120
	ds_read_b128 v[208:211], v151 offset:6144
	ds_read_b128 v[212:215], v151 offset:7168
	global_load_lds_dwordx4 v136, s[40:41]
	s_nop 0
	s_add_i32 m0, s29, 0xe000
	s_nop 0
	global_load_lds_dwordx4 v138, s[40:41]
	s_waitcnt vmcnt(8)
	s_waitcnt lgkmcnt(0)
	s_barrier
; #define PG8_STAGE(bufoff, gbase, voff) do { _Pragma("unroll") for (int _i = 0; _i < 2; ++_i) \
;         __builtin_amdgcn_global_load_lds((const unsigned*)((const char*)(gbase) + (voff)[_i]), (PG8_LAS unsigned*)(lds + (bufoff) + ldsw + _i * 8192), 16, 0, 0); } while (0)
; #define PG8_LDA(dst, b, h) do { _Pragma("unroll") for (int m = 0; m < 4; ++m) _Pragma("unroll") for (int k = 0; k < 2; ++k) dst[m][k] = *(const PG8_LAS bf16x8*)(lds + PG8_SA(b, h) + aoff + m * 2048 + k * 1024); } while (0)
; #define PG8_LDB(dst, b, h) do { _Pragma("unroll") for (int n = 0; n < 2; ++n) _Pragma("unroll") for (int k = 0; k < 2; ++k) dst[n][k] = *(const PG8_LAS bf16x8*)(lds + PG8_SB(b, h) + boff + n * 2048 + k * 1024); } while (0)
; #define PG8_MMA(ai, bj, At, Bt) do { __builtin_amdgcn_s_setprio(1); _Pragma("unroll") for (int m = 0; m < 4; ++m) _Pragma("unroll") for (int n = 0; n < 2; ++n) _Pragma("unroll") for (int k = 0; k < 2; ++k) \
;         acc[ai][bj][m][n] = __builtin_amdgcn_mfma_f32_16x16x32_bf16(Bt[n][k], At[m][k], acc[ai][bj][m][n], 0, 0, 0); __builtin_amdgcn_s_setprio(0); } while (0)
; #define PG8_WAIT_V(n) asm volatile("s_waitcnt vmcnt(" #n ")" ::: "memory")
; #define PG8_WAIT_L(n) asm volatile("s_waitcnt lgkmcnt(" #n ")" ::: "memory")
; #define PG8_BAR __builtin_amdgcn_s_barrier()
; #define PG8_SCHED __builtin_amdgcn_sched_barrier(0)
; template <class Epi, class Sched, bool ALIGN_EPI = false, bool SP2 = false>
; __device__ __forceinline__ void gemm_phase(PG8_LAS unsigned char* lds, const Gemm g, const Sched& S, const Epi& E) {
;     ...
;             PG8_LDB(B0, 0, 0); PG8_LDB(B1, 0, 1); PG8_SCHED; PG8_LDA(At, 0, 0); PG8_STAGE(PG8_SA(1, 1), a1 + hstep, voffA);
;             PG8_WAIT_V(8); PG8_WAIT_L(0); PG8_BAR; PG8_MMA(0, 0, At, B0); PG8_MMA(0, 1, At, B1); PG8_BAR; PG8_SCHED;
;             PG8_LDA(At, 0, 1); PG8_STAGE(PG8_SB(0, 0), b2, voffB); PG8_STAGE(PG8_SB(0, 1), b2 + hstep, voffB); PG8_STAGE(PG8_SA(0, 0), a2, voffA);
;             PG8_WAIT_V(8); PG8_WAIT_L(0); PG8_BAR; PG8_MMA(1, 0, At, B0); PG8_MMA(1, 1, At, B1); PG8_BAR; PG8_SCHED;
	s_setprio 1
	s_waitcnt lgkmcnt(0)
	v_mfma_f32_16x16x32_bf16 v[124:127], v[152:155], v[184:187], v[124:127]
	v_mfma_f32_16x16x32_bf16 v[120:123], v[160:163], v[184:187], v[120:123]
	v_mfma_f32_16x16x32_bf16 v[116:119], v[152:155], v[192:195], v[116:119]
	v_mfma_f32_16x16x32_bf16 v[112:115], v[160:163], v[192:195], v[112:115]
	v_mfma_f32_16x16x32_bf16 v[100:103], v[152:155], v[200:203], v[100:103]
	v_mfma_f32_16x16x32_bf16 v[96:99], v[160:163], v[200:203], v[96:99]
	v_mfma_f32_16x16x32_bf16 v[84:87], v[152:155], v[208:211], v[84:87]
	v_mfma_f32_16x16x32_bf16 v[80:83], v[160:163], v[208:211], v[80:83]
	v_mfma_f32_16x16x32_bf16 v[124:127], v[156:159], v[188:191], v[124:127]
	v_mfma_f32_16x16x32_bf16 v[120:123], v[164:167], v[188:191], v[120:123]
	v_mfma_f32_16x16x32_bf16 v[116:119], v[156:159], v[196:199], v[116:119]
	v_mfma_f32_16x16x32_bf16 v[112:115], v[164:167], v[196:199], v[112:115]
	v_mfma_f32_16x16x32_bf16 v[100:103], v[156:159], v[204:207], v[100:103]
	v_mfma_f32_16x16x32_bf16 v[96:99], v[164:167], v[204:207], v[96:99]
	v_mfma_f32_16x16x32_bf16 v[84:87], v[156:159], v[212:215], v[84:87]
	v_mfma_f32_16x16x32_bf16 v[80:83], v[164:167], v[212:215], v[80:83]
	s_setprio 0
	s_setprio 1
	v_mfma_f32_16x16x32_bf16 v[108:111], v[168:171], v[184:187], v[108:111]
	v_mfma_f32_16x16x32_bf16 v[104:107], v[176:179], v[184:187], v[104:107]
	v_mfma_f32_16x16x32_bf16 v[92:95], v[168:171], v[192:195], v[92:95]
	v_mfma_f32_16x16x32_bf16 v[88:91], v[176:179], v[192:195], v[88:91]
	v_mfma_f32_16x16x32_bf16 v[76:79], v[168:171], v[200:203], v[76:79]
	v_mfma_f32_16x16x32_bf16 v[72:75], v[176:179], v[200:203], v[72:75]
	v_mfma_f32_16x16x32_bf16 v[68:71], v[168:171], v[208:211], v[68:71]
	v_mfma_f32_16x16x32_bf16 v[64:67], v[176:179], v[208:211], v[64:67]
	v_mfma_f32_16x16x32_bf16 v[108:111], v[172:175], v[188:191], v[108:111]
	v_mfma_f32_16x16x32_bf16 v[104:107], v[180:183], v[188:191], v[104:107]
	v_mfma_f32_16x16x32_bf16 v[92:95], v[172:175], v[196:199], v[92:95]
	v_mfma_f32_16x16x32_bf16 v[88:91], v[180:183], v[196:199], v[88:91]
	v_mfma_f32_16x16x32_bf16 v[76:79], v[172:175], v[204:207], v[76:79]
	v_mfma_f32_16x16x32_bf16 v[72:75], v[180:183], v[204:207], v[72:75]
	v_mfma_f32_16x16x32_bf16 v[68:71], v[172:175], v[212:215], v[68:71]
	v_mfma_f32_16x16x32_bf16 v[64:67], v[180:183], v[212:215], v[64:67]
	s_setprio 0
	s_barrier
	s_add_i32 s69, s59, s48
	s_mov_b64 s[96:97], s[42:43]
	s_nop 0
	s_mov_b32 m0, s69
	ds_read_b128 v[184:187], v151 offset:16384
	ds_read_b128 v[188:191], v151 offset:17408
	ds_read_b128 v[192:195], v151 offset:18432
	ds_read_b128 v[196:199], v151 offset:19456
	ds_read_b128 v[200:203], v151 offset:20480
	ds_read_b128 v[204:207], v151 offset:21504
	ds_read_b128 v[208:211], v151 offset:22528
	ds_read_b128 v[212:215], v151 offset:23552
	global_load_lds_dwordx4 v132, s[42:43]
	s_add_i32 m0, s69, 0x2000
	s_add_u32 s70, s42, 0x80000
	s_nop 0
	s_addc_u32 s71, s43, 0
	s_add_i32 s69, s60, s48
	global_load_lds_dwordx4 v128, s[42:43]
	s_nop 0
	s_mov_b32 m0, s69
	s_nop 0
	global_load_lds_dwordx4 v132, s[70:71]
	s_nop 0
	s_add_i32 m0, s69, 0x2000
	s_nop 0
	global_load_lds_dwordx4 v128, s[70:71]
	s_mov_b64 s[98:99], s[44:45]
	s_nop 0
	s_mov_b32 m0, s29
	s_nop 0
	global_load_lds_dwordx4 v134, s[44:45]
	s_mov_b32 m0, s51
	s_nop 0
	global_load_lds_dwordx4 v130, s[44:45]
	s_waitcnt vmcnt(8)
	s_waitcnt lgkmcnt(0)
	s_barrier
	s_setprio 1
	s_waitcnt lgkmcnt(0)
	v_mfma_f32_16x16x32_bf16 v[60:63], v[152:155], v[184:187], v[60:63]
	v_mfma_f32_16x16x32_bf16 v[56:59], v[160:163], v[184:187], v[56:59]
	v_mfma_f32_16x16x32_bf16 v[52:55], v[152:155], v[192:195], v[52:55]
	v_mfma_f32_16x16x32_bf16 v[48:51], v[160:163], v[192:195], v[48:51]
	v_mfma_f32_16x16x32_bf16 v[36:39], v[152:155], v[200:203], v[36:39]
	v_mfma_f32_16x16x32_bf16 v[32:35], v[160:163], v[200:203], v[32:35]
	v_mfma_f32_16x16x32_bf16 v[20:23], v[152:155], v[208:211], v[20:23]
	v_mfma_f32_16x16x32_bf16 v[16:19], v[160:163], v[208:211], v[16:19]
	v_mfma_f32_16x16x32_bf16 v[60:63], v[156:159], v[188:191], v[60:63]
	v_mfma_f32_16x16x32_bf16 v[56:59], v[164:167], v[188:191], v[56:59]
	v_mfma_f32_16x16x32_bf16 v[52:55], v[156:159], v[196:199], v[52:55]
	v_mfma_f32_16x16x32_bf16 v[48:51], v[164:167], v[196:199], v[48:51]
	v_mfma_f32_16x16x32_bf16 v[36:39], v[156:159], v[204:207], v[36:39]
	v_mfma_f32_16x16x32_bf16 v[32:35], v[164:167], v[204:207], v[32:35]
	v_mfma_f32_16x16x32_bf16 v[20:23], v[156:159], v[212:215], v[20:23]
	v_mfma_f32_16x16x32_bf16 v[16:19], v[164:167], v[212:215], v[16:19]
	s_setprio 0
	s_setprio 1
	v_mfma_f32_16x16x32_bf16 v[44:47], v[168:171], v[184:187], v[44:47]
	v_mfma_f32_16x16x32_bf16 v[40:43], v[176:179], v[184:187], v[40:43]
	v_mfma_f32_16x16x32_bf16 v[28:31], v[168:171], v[192:195], v[28:31]
	v_mfma_f32_16x16x32_bf16 v[24:27], v[176:179], v[192:195], v[24:27]
	v_mfma_f32_16x16x32_bf16 v[12:15], v[168:171], v[200:203], v[12:15]
	v_mfma_f32_16x16x32_bf16 v[8:11], v[176:179], v[200:203], v[8:11]
	v_mfma_f32_16x16x32_bf16 v[4:7], v[168:171], v[208:211], v[4:7]
	v_mfma_f32_16x16x32_bf16 v[0:3], v[176:179], v[208:211], v[0:3]
	v_mfma_f32_16x16x32_bf16 v[44:47], v[172:175], v[188:191], v[44:47]
	v_mfma_f32_16x16x32_bf16 v[40:43], v[180:183], v[188:191], v[40:43]
	v_mfma_f32_16x16x32_bf16 v[28:31], v[172:175], v[196:199], v[28:31]
	v_mfma_f32_16x16x32_bf16 v[24:27], v[180:183], v[196:199], v[24:27]
	v_mfma_f32_16x16x32_bf16 v[12:15], v[172:175], v[204:207], v[12:15]
	v_mfma_f32_16x16x32_bf16 v[8:11], v[180:183], v[204:207], v[8:11]
	v_mfma_f32_16x16x32_bf16 v[4:7], v[172:175], v[212:215], v[4:7]
	v_mfma_f32_16x16x32_bf16 v[0:3], v[180:183], v[212:215], v[0:3]
	s_setprio 0
	s_barrier
; #define PG8_STAGE(bufoff, gbase, voff) do { _Pragma("unroll") for (int _i = 0; _i < 2; ++_i) \
;         __builtin_amdgcn_global_load_lds((const unsigned*)((const char*)(gbase) + (voff)[_i]), (PG8_LAS unsigned*)(lds + (bufoff) + ldsw + _i * 8192), 16, 0, 0); } while (0)
; #define PG8_LDA(dst, b, h) do { _Pragma("unroll") for (int m = 0; m < 4; ++m) _Pragma("unroll") for (int k = 0; k < 2; ++k) dst[m][k] = *(const PG8_LAS bf16x8*)(lds + PG8_SA(b, h) + aoff + m * 2048 + k * 1024); } while (0)
; #define PG8_LDB(dst, b, h) do { _Pragma("unroll") for (int n = 0; n < 2; ++n) _Pragma("unroll") for (int k = 0; k < 2; ++k) dst[n][k] = *(const PG8_LAS bf16x8*)(lds + PG8_SB(b, h) + boff + n * 2048 + k * 1024); } while (0)
; #define PG8_MMA(ai, bj, At, Bt) do { __builtin_amdgcn_s_setprio(1); _Pragma("unroll") for (int m = 0; m < 4; ++m) _Pragma("unroll") for (int n = 0; n < 2; ++n) _Pragma("unroll") for (int k = 0; k < 2; ++k) \
;         acc[ai][bj][m][n] = __builtin_amdgcn_mfma_f32_16x16x32_bf16(Bt[n][k], At[m][k], acc[ai][bj][m][n], 0, 0, 0); __builtin_amdgcn_s_setprio(0); } while (0)
; #define PG8_WAIT_V(n) asm volatile("s_waitcnt vmcnt(" #n ")" ::: "memory")
; #define PG8_WAIT_L(n) asm volatile("s_waitcnt lgkmcnt(" #n ")" ::: "memory")
; #define PG8_BAR __builtin_amdgcn_s_barrier()
; #define PG8_SCHED __builtin_amdgcn_sched_barrier(0)
; template <class Epi, class Sched, bool ALIGN_EPI = false, bool SP2 = false>
; __device__ __forceinline__ void gemm_phase(PG8_LAS unsigned char* lds, const Gemm g, const Sched& S, const Epi& E) {
;     ...
;             PG8_LDB(B0, 1, 0); PG8_LDB(B1, 1, 1); PG8_SCHED; PG8_LDA(At, 1, 0); PG8_STAGE(PG8_SA(0, 1), a2 + hstep, voffA);
;             PG8_WAIT_V(8); PG8_WAIT_L(0); PG8_BAR; PG8_MMA(0, 0, At, B0); PG8_MMA(0, 1, At, B1); PG8_BAR; PG8_SCHED;
;             PG8_LDA(At, 1, 1); PG8_STAGE(PG8_SB(1, 0), b3, voffB); PG8_STAGE(PG8_SB(1, 1), b3 + hstep, voffB); PG8_STAGE(PG8_SA(1, 0), a3, voffA);
;             PG8_WAIT_V(8); PG8_WAIT_L(0); PG8_BAR; PG8_MMA(1, 0, At, B0); PG8_MMA(1, 1, At, B1); PG8_BAR; PG8_SCHED;
;     ...
;         if constexpr (ALIGN_EPI) { if (wr == 0) PG8_BAR; }
	s_add_i32 s69, 0, 0x18000
	s_add_i32 s70, 0, 0x1c000
	v_add_u32_e32 v164, s69, v147
	v_add_u32_e32 v180, s70, v147
	ds_read_b128 v[152:155], v164
	ds_read_b128 v[156:159], v164 offset:1024
	ds_read_b128 v[160:163], v164 offset:2048
	ds_read_b128 v[164:167], v164 offset:3072
	ds_read_b128 v[168:171], v180
	ds_read_b128 v[172:175], v180 offset:1024
	ds_read_b128 v[176:179], v180 offset:2048
	ds_read_b128 v[180:183], v180 offset:3072
	s_add_u32 s44, s44, 0x80000
	s_addc_u32 s45, s45, 0
	s_mov_b32 m0, s52
	s_nop 0
	ds_read_b128 v[184:187], v151 offset:32768
	ds_read_b128 v[188:191], v151 offset:33792
	ds_read_b128 v[192:195], v151 offset:34816
	ds_read_b128 v[196:199], v151 offset:35840
	ds_read_b128 v[200:203], v151 offset:36864
	ds_read_b128 v[204:207], v151 offset:37888
	ds_read_b128 v[208:211], v151 offset:38912
	ds_read_b128 v[212:215], v151 offset:39936
	global_load_lds_dwordx4 v134, s[44:45]
	s_nop 0
	s_mov_b32 m0, s53
	s_nop 0
	global_load_lds_dwordx4 v130, s[44:45]
	s_waitcnt vmcnt(8)
	s_waitcnt lgkmcnt(0)
	s_barrier
	s_setprio 1
	s_waitcnt lgkmcnt(0)
	v_mfma_f32_16x16x32_bf16 v[124:127], v[152:155], v[184:187], v[124:127]
	v_mfma_f32_16x16x32_bf16 v[120:123], v[160:163], v[184:187], v[120:123]
	v_mfma_f32_16x16x32_bf16 v[116:119], v[152:155], v[192:195], v[116:119]
	v_mfma_f32_16x16x32_bf16 v[112:115], v[160:163], v[192:195], v[112:115]
	v_mfma_f32_16x16x32_bf16 v[100:103], v[152:155], v[200:203], v[100:103]
	v_mfma_f32_16x16x32_bf16 v[96:99], v[160:163], v[200:203], v[96:99]
	v_mfma_f32_16x16x32_bf16 v[84:87], v[152:155], v[208:211], v[84:87]
	v_mfma_f32_16x16x32_bf16 v[80:83], v[160:163], v[208:211], v[80:83]
	v_mfma_f32_16x16x32_bf16 v[124:127], v[156:159], v[188:191], v[124:127]
	v_mfma_f32_16x16x32_bf16 v[120:123], v[164:167], v[188:191], v[120:123]
	v_mfma_f32_16x16x32_bf16 v[116:119], v[156:159], v[196:199], v[116:119]
	v_mfma_f32_16x16x32_bf16 v[112:115], v[164:167], v[196:199], v[112:115]
	v_mfma_f32_16x16x32_bf16 v[100:103], v[156:159], v[204:207], v[100:103]
	v_mfma_f32_16x16x32_bf16 v[96:99], v[164:167], v[204:207], v[96:99]
	v_mfma_f32_16x16x32_bf16 v[84:87], v[156:159], v[212:215], v[84:87]
	v_mfma_f32_16x16x32_bf16 v[80:83], v[164:167], v[212:215], v[80:83]
	s_setprio 0
	s_setprio 1
	v_mfma_f32_16x16x32_bf16 v[108:111], v[168:171], v[184:187], v[108:111]
	v_mfma_f32_16x16x32_bf16 v[104:107], v[176:179], v[184:187], v[104:107]
	v_mfma_f32_16x16x32_bf16 v[92:95], v[168:171], v[192:195], v[92:95]
	v_mfma_f32_16x16x32_bf16 v[88:91], v[176:179], v[192:195], v[88:91]
	v_mfma_f32_16x16x32_bf16 v[76:79], v[168:171], v[200:203], v[76:79]
	v_mfma_f32_16x16x32_bf16 v[72:75], v[176:179], v[200:203], v[72:75]
	v_mfma_f32_16x16x32_bf16 v[68:71], v[168:171], v[208:211], v[68:71]
	v_mfma_f32_16x16x32_bf16 v[64:67], v[176:179], v[208:211], v[64:67]
	v_mfma_f32_16x16x32_bf16 v[108:111], v[172:175], v[188:191], v[108:111]
	v_mfma_f32_16x16x32_bf16 v[104:107], v[180:183], v[188:191], v[104:107]
	v_mfma_f32_16x16x32_bf16 v[92:95], v[172:175], v[196:199], v[92:95]
	v_mfma_f32_16x16x32_bf16 v[88:91], v[180:183], v[196:199], v[88:91]
	v_mfma_f32_16x16x32_bf16 v[76:79], v[172:175], v[204:207], v[76:79]
	v_mfma_f32_16x16x32_bf16 v[72:75], v[180:183], v[204:207], v[72:75]
	v_mfma_f32_16x16x32_bf16 v[68:71], v[172:175], v[212:215], v[68:71]
	v_mfma_f32_16x16x32_bf16 v[64:67], v[180:183], v[212:215], v[64:67]
	s_setprio 0
	s_barrier
	s_add_i32 s44, s69, s48
	s_nop 0
	s_mov_b32 m0, s44
	ds_read_b128 v[184:187], v151 offset:49152
	ds_read_b128 v[188:191], v151 offset:50176
	ds_read_b128 v[192:195], v151 offset:51200
	ds_read_b128 v[196:199], v151 offset:52224
	ds_read_b128 v[200:203], v151 offset:53248
	ds_read_b128 v[204:207], v151 offset:54272
	ds_read_b128 v[208:211], v151 offset:55296
	ds_read_b128 v[212:215], v151 offset:56320
	global_load_lds_dwordx4 v250, s[96:97]
	s_add_i32 m0, s44, 0x2000
	s_add_u32 s42, s42, 0x80080
	s_nop 0
	s_addc_u32 s43, s43, 0
	s_add_i32 s44, s70, s48
	global_load_lds_dwordx4 v251, s[96:97]
	s_nop 0
	s_mov_b32 m0, s44
	s_nop 0
	global_load_lds_dwordx4 v132, s[42:43]
	s_nop 0
	s_add_i32 m0, s44, 0x2000
	s_nop 0
	global_load_lds_dwordx4 v128, s[42:43]
	s_nop 0
	s_mov_b32 m0, s55
	s_nop 0
	global_load_lds_dwordx4 v252, s[98:99]
	s_nop 0
	s_mov_b32 m0, s56
	s_nop 0
	global_load_lds_dwordx4 v253, s[98:99]
	s_waitcnt vmcnt(8)
	s_waitcnt lgkmcnt(0)
	s_barrier
	s_setprio 1
	s_waitcnt lgkmcnt(0)
	v_mfma_f32_16x16x32_bf16 v[60:63], v[152:155], v[184:187], v[60:63]
	v_mfma_f32_16x16x32_bf16 v[56:59], v[160:163], v[184:187], v[56:59]
	v_mfma_f32_16x16x32_bf16 v[52:55], v[152:155], v[192:195], v[52:55]
	v_mfma_f32_16x16x32_bf16 v[48:51], v[160:163], v[192:195], v[48:51]
	v_mfma_f32_16x16x32_bf16 v[36:39], v[152:155], v[200:203], v[36:39]
	v_mfma_f32_16x16x32_bf16 v[32:35], v[160:163], v[200:203], v[32:35]
	v_mfma_f32_16x16x32_bf16 v[20:23], v[152:155], v[208:211], v[20:23]
	v_mfma_f32_16x16x32_bf16 v[16:19], v[160:163], v[208:211], v[16:19]
	v_mfma_f32_16x16x32_bf16 v[60:63], v[156:159], v[188:191], v[60:63]
	v_mfma_f32_16x16x32_bf16 v[56:59], v[164:167], v[188:191], v[56:59]
	v_mfma_f32_16x16x32_bf16 v[52:55], v[156:159], v[196:199], v[52:55]
	v_mfma_f32_16x16x32_bf16 v[48:51], v[164:167], v[196:199], v[48:51]
	v_mfma_f32_16x16x32_bf16 v[36:39], v[156:159], v[204:207], v[36:39]
	v_mfma_f32_16x16x32_bf16 v[32:35], v[164:167], v[204:207], v[32:35]
	v_mfma_f32_16x16x32_bf16 v[20:23], v[156:159], v[212:215], v[20:23]
	v_mfma_f32_16x16x32_bf16 v[16:19], v[164:167], v[212:215], v[16:19]
	s_setprio 0
	s_setprio 1
	v_mfma_f32_16x16x32_bf16 v[44:47], v[168:171], v[184:187], v[44:47]
	v_mfma_f32_16x16x32_bf16 v[40:43], v[176:179], v[184:187], v[40:43]
	v_mfma_f32_16x16x32_bf16 v[28:31], v[168:171], v[192:195], v[28:31]
	v_mfma_f32_16x16x32_bf16 v[24:27], v[176:179], v[192:195], v[24:27]
	v_mfma_f32_16x16x32_bf16 v[12:15], v[168:171], v[200:203], v[12:15]
	v_mfma_f32_16x16x32_bf16 v[8:11], v[176:179], v[200:203], v[8:11]
	v_mfma_f32_16x16x32_bf16 v[4:7], v[168:171], v[208:211], v[4:7]
	v_mfma_f32_16x16x32_bf16 v[0:3], v[176:179], v[208:211], v[0:3]
	v_mfma_f32_16x16x32_bf16 v[44:47], v[172:175], v[188:191], v[44:47]
	v_mfma_f32_16x16x32_bf16 v[40:43], v[180:183], v[188:191], v[40:43]
	v_mfma_f32_16x16x32_bf16 v[28:31], v[172:175], v[196:199], v[28:31]
	v_mfma_f32_16x16x32_bf16 v[24:27], v[180:183], v[196:199], v[24:27]
	v_mfma_f32_16x16x32_bf16 v[12:15], v[172:175], v[204:207], v[12:15]
	v_mfma_f32_16x16x32_bf16 v[8:11], v[180:183], v[204:207], v[8:11]
	v_mfma_f32_16x16x32_bf16 v[4:7], v[172:175], v[212:215], v[4:7]
	v_mfma_f32_16x16x32_bf16 v[0:3], v[180:183], v[212:215], v[0:3]
	s_setprio 0
	s_barrier
	s_add_i32 s68, s68, 2
	s_add_u32 s40, s40, 0x100
	s_addc_u32 s41, s41, 0
	s_add_u32 s65, s65, 0x100
	s_addc_u32 s67, s67, 0
	s_cmp_gt_u32 s68, 29
	s_cbranch_scc0 .LBB0_66
	s_and_b64 vcc, exec, s[26:27]
	s_cbranch_vccz .LBB0_69
	s_barrier

; #define PG8_STAGE(bufoff, gbase, voff) do { _Pragma("unroll") for (int _i = 0; _i < 2; ++_i) \
;         __builtin_amdgcn_global_load_lds((const unsigned*)((const char*)(gbase) + (voff)[_i]), (PG8_LAS unsigned*)(lds + (bufoff) + ldsw + _i * 8192), 16, 0, 0); } while (0)
; #define PG8_LDA(dst, b, h) do { _Pragma("unroll") for (int m = 0; m < 4; ++m) _Pragma("unroll") for (int k = 0; k < 2; ++k) dst[m][k] = *(const PG8_LAS bf16x8*)(lds + PG8_SA(b, h) + aoff + m * 2048 + k * 1024); } while (0)
; #define PG8_LDB(dst, b, h) do { _Pragma("unroll") for (int n = 0; n < 2; ++n) _Pragma("unroll") for (int k = 0; k < 2; ++k) dst[n][k] = *(const PG8_LAS bf16x8*)(lds + PG8_SB(b, h) + boff + n * 2048 + k * 1024); } while (0)
; #define PG8_SCHED __builtin_amdgcn_sched_barrier(0)
; template <class Epi, class Sched, bool ALIGN_EPI = false, bool SP2 = false>
; __device__ __forceinline__ void gemm_phase(PG8_LAS unsigned char* lds, const Gemm g, const Sched& S, const Epi& E) {
;     ...
; #pragma unroll
;     for (int a = 0; a < 2; ++a)
; #pragma unroll
;         for (int b = 0; b < 2; ++b)
; #pragma unroll
;             for (int m = 0; m < 4; ++m)
; #pragma unroll
;                 for (int n = 0; n < 2; ++n) acc[a][b][m][n] = (f32x4){0.f, 0.f, 0.f, 0.f};
;     ...
;         const bool has_next = S.next(ui + 1, nxt);
;         const char* nA = has_next ? (const char*)g.A + (size_t)nxt.pm * tstep : cA; const char* nB = has_next ? (const char*)g.Bt + (size_t)nxt.pn * tstep : cB;
;         for (int t = 0; t < nt; t += 2) {
;             const bool last = (t == nt - 2);
;             const char* a1 = cA + (size_t)(t + 1) * kstep;
;             const char* a2 = last ? nA : cA + (size_t)(t + 2) * kstep; const char* b2 = last ? nB : cB + (size_t)(t + 2) * kstep;
;             const char* a3 = a2 + kstep; const char* b3 = b2 + kstep;
;             if (last && has_next) S.a_ready(nxt);
;             if constexpr (SP2) {
;             PG8_LDB(B0, 0, 0); PG8_LDB(B1, 0, 1); PG8_SCHED; PG8_LDA(At, 0, 0); PG8_STAGE(PG8_SA(1, 1), a1 + hstep, voffA);
.LBB0_332:
	s_ashr_i32 s51, s50, 31
	s_lshl_b64 s[52:53], s[50:51], 20
	s_add_u32 s52, s26, s52
	s_addc_u32 s53, s27, s53
	s_and_b64 s[54:55], s[6:7], exec
	s_cselect_b32 s11, s53, s59
	s_cselect_b32 s51, s52, s58
	s_ashr_i32 s49, s48, 31
	s_lshl_b64 s[54:55], s[48:49], 20
	s_add_u32 s54, s45, s54
	s_addc_u32 s55, s47, s55
	s_and_b64 s[62:63], s[6:7], exec
	s_cselect_b32 s49, s55, s61
	s_cselect_b32 s78, s54, s60
	s_add_u32 s58, s58, 0x80080
	s_addc_u32 s59, s59, 0
	s_add_u32 s79, s60, 0x100
	v_mov_b32_e32 v0, 0
	s_addc_u32 s80, s61, 0
	s_mov_b32 s81, -2
	v_mov_b32_e32 v1, v0
	s_waitcnt lgkmcnt(0)
	v_mov_b32_e32 v2, v0
	v_mov_b32_e32 v3, v0
	v_mov_b32_e32 v4, v0
	v_mov_b32_e32 v5, v0
	v_mov_b32_e32 v6, v0
	v_mov_b32_e32 v7, v0
	v_mov_b32_e32 v16, v0
	v_mov_b32_e32 v17, v0
	v_mov_b32_e32 v18, v0
	v_mov_b32_e32 v19, v0
	v_mov_b32_e32 v20, v0
	v_mov_b32_e32 v21, v0
	v_mov_b32_e32 v22, v0
	v_mov_b32_e32 v23, v0
	v_mov_b32_e32 v32, v0
	v_mov_b32_e32 v33, v0
	v_mov_b32_e32 v34, v0
	v_mov_b32_e32 v35, v0
	v_mov_b32_e32 v36, v0
	v_mov_b32_e32 v37, v0
	v_mov_b32_e32 v38, v0
	v_mov_b32_e32 v39, v0
	v_mov_b32_e32 v48, v0
	v_mov_b32_e32 v49, v0
	v_mov_b32_e32 v50, v0
	v_mov_b32_e32 v51, v0
	v_mov_b32_e32 v52, v0
	v_mov_b32_e32 v53, v0
	v_mov_b32_e32 v54, v0
	v_mov_b32_e32 v55, v0
	v_mov_b32_e32 v8, v0
	v_mov_b32_e32 v9, v0
	v_mov_b32_e32 v10, v0
	v_mov_b32_e32 v11, v0
	v_mov_b32_e32 v12, v0
	v_mov_b32_e32 v13, v0
	v_mov_b32_e32 v14, v0
	v_mov_b32_e32 v15, v0
	v_mov_b32_e32 v24, v0
	v_mov_b32_e32 v25, v0
	v_mov_b32_e32 v26, v0
	v_mov_b32_e32 v27, v0
	v_mov_b32_e32 v28, v0
	v_mov_b32_e32 v29, v0
	v_mov_b32_e32 v30, v0
	v_mov_b32_e32 v31, v0
	v_mov_b32_e32 v40, v0
	v_mov_b32_e32 v41, v0
	v_mov_b32_e32 v42, v0
	v_mov_b32_e32 v43, v0
	v_mov_b32_e32 v44, v0
	v_mov_b32_e32 v45, v0
	v_mov_b32_e32 v46, v0
	v_mov_b32_e32 v47, v0
	v_mov_b32_e32 v56, v0
	v_mov_b32_e32 v57, v0
	v_mov_b32_e32 v58, v0
	v_mov_b32_e32 v59, v0
	v_mov_b32_e32 v60, v0
	v_mov_b32_e32 v61, v0
	v_mov_b32_e32 v62, v0
	v_mov_b32_e32 v63, v0
	v_mov_b32_e32 v80, v0
	v_mov_b32_e32 v81, v0
	v_mov_b32_e32 v82, v0
	v_mov_b32_e32 v83, v0
	v_mov_b32_e32 v84, v0
	v_mov_b32_e32 v85, v0
	v_mov_b32_e32 v86, v0
	v_mov_b32_e32 v87, v0
	v_mov_b32_e32 v96, v0
	v_mov_b32_e32 v97, v0
	v_mov_b32_e32 v98, v0
	v_mov_b32_e32 v99, v0
	v_mov_b32_e32 v100, v0
	v_mov_b32_e32 v101, v0
	v_mov_b32_e32 v102, v0
	v_mov_b32_e32 v103, v0
	v_mov_b32_e32 v112, v0
	v_mov_b32_e32 v113, v0
	v_mov_b32_e32 v114, v0
	v_mov_b32_e32 v115, v0
	v_mov_b32_e32 v116, v0
	v_mov_b32_e32 v117, v0
	v_mov_b32_e32 v118, v0
	v_mov_b32_e32 v119, v0
	v_mov_b32_e32 v128, v0
	v_mov_b32_e32 v129, v0
	v_mov_b32_e32 v130, v0
	v_mov_b32_e32 v131, v0
	v_mov_b32_e32 v132, v0
	v_mov_b32_e32 v133, v0
	v_mov_b32_e32 v134, v0
	v_mov_b32_e32 v135, v0
	v_mov_b32_e32 v88, v0
	v_mov_b32_e32 v89, v0
	v_mov_b32_e32 v90, v0
	v_mov_b32_e32 v91, v0
	v_mov_b32_e32 v92, v0
	v_mov_b32_e32 v93, v0
	v_mov_b32_e32 v94, v0
	v_mov_b32_e32 v95, v0
	v_mov_b32_e32 v104, v0
	v_mov_b32_e32 v105, v0
	v_mov_b32_e32 v106, v0
	v_mov_b32_e32 v107, v0
	v_mov_b32_e32 v108, v0
	v_mov_b32_e32 v109, v0
	v_mov_b32_e32 v110, v0
	v_mov_b32_e32 v111, v0
	v_mov_b32_e32 v120, v0
	v_mov_b32_e32 v121, v0
	v_mov_b32_e32 v122, v0
	v_mov_b32_e32 v123, v0
	v_mov_b32_e32 v124, v0
	v_mov_b32_e32 v125, v0
	v_mov_b32_e32 v126, v0
	v_mov_b32_e32 v127, v0
	v_mov_b32_e32 v136, v0
	v_mov_b32_e32 v137, v0
	v_mov_b32_e32 v138, v0
	v_mov_b32_e32 v139, v0
	v_mov_b32_e32 v140, v0
	v_mov_b32_e32 v141, v0
	v_mov_b32_e32 v142, v0
	v_mov_b32_e32 v143, v0
	v_add_u32_e32 v253, 0x80, v164
	v_add_u32_e32 v252, 0x80, v160
	v_add_u32_e32 v251, 0x80, v166
	v_add_u32_e32 v250, 0x80, v162
.LBB0_333:
	ds_read_b128 v[64:67], v211
	ds_read_b128 v[68:71], v211 offset:1024
	ds_read_b128 v[72:75], v211 offset:2048
	ds_read_b128 v[76:79], v211 offset:3072
	ds_read_b128 v[144:147], v212
	ds_read_b128 v[148:151], v212 offset:1024
	ds_read_b128 v[152:155], v212 offset:2048
	ds_read_b128 v[156:159], v212 offset:3072
	s_add_u32 s60, s58, 0xfff80080
	s_addc_u32 s61, s59, -1
	s_cmp_eq_u32 s81, 28
	s_cselect_b32 s63, s11, s61
	s_cselect_b32 s62, s51, s60
	s_cselect_b32 s61, s49, s80
	s_cselect_b32 s60, s78, s79
	s_nop 0
	s_add_i32 m0, s57, 0xc000
	ds_read_b128 v[176:179], v213
	ds_read_b128 v[180:183], v213 offset:1024
	ds_read_b128 v[184:187], v213 offset:2048
	ds_read_b128 v[188:191], v213 offset:3072
	ds_read_b128 v[192:195], v213 offset:4096
	ds_read_b128 v[196:199], v213 offset:5120
	ds_read_b128 v[200:203], v213 offset:6144
	ds_read_b128 v[204:207], v213 offset:7168
	global_load_lds_dwordx4 v168, s[58:59]
	s_nop 0
	s_add_i32 m0, s57, 0xe000
	s_nop 0
	global_load_lds_dwordx4 v170, s[58:59]
	s_waitcnt vmcnt(8)
	s_waitcnt lgkmcnt(0)
	s_barrier
; #define PG8_STAGE(bufoff, gbase, voff) do { _Pragma("unroll") for (int _i = 0; _i < 2; ++_i) \
;         __builtin_amdgcn_global_load_lds((const unsigned*)((const char*)(gbase) + (voff)[_i]), (PG8_LAS unsigned*)(lds + (bufoff) + ldsw + _i * 8192), 16, 0, 0); } while (0)
; #define PG8_LDA(dst, b, h) do { _Pragma("unroll") for (int m = 0; m < 4; ++m) _Pragma("unroll") for (int k = 0; k < 2; ++k) dst[m][k] = *(const PG8_LAS bf16x8*)(lds + PG8_SA(b, h) + aoff + m * 2048 + k * 1024); } while (0)
; #define PG8_MMA(ai, bj, At, Bt) do { __builtin_amdgcn_s_setprio(1); _Pragma("unroll") for (int m = 0; m < 4; ++m) _Pragma("unroll") for (int n = 0; n < 2; ++n) _Pragma("unroll") for (int k = 0; k < 2; ++k) \
;         acc[ai][bj][m][n] = __builtin_amdgcn_mfma_f32_16x16x32_bf16(Bt[n][k], At[m][k], acc[ai][bj][m][n], 0, 0, 0); __builtin_amdgcn_s_setprio(0); } while (0)
; #define PG8_WAIT_V(n) asm volatile("s_waitcnt vmcnt(" #n ")" ::: "memory")
; #define PG8_WAIT_L(n) asm volatile("s_waitcnt lgkmcnt(" #n ")" ::: "memory")
; #define PG8_BAR __builtin_amdgcn_s_barrier()
; #define PG8_SCHED __builtin_amdgcn_sched_barrier(0)
; template <class Epi, class Sched, bool ALIGN_EPI = false, bool SP2 = false>
; __device__ __forceinline__ void gemm_phase(PG8_LAS unsigned char* lds, const Gemm g, const Sched& S, const Epi& E) {
;     ...
;             PG8_WAIT_V(8); PG8_WAIT_L(0); PG8_BAR; PG8_MMA(0, 0, At, B0); PG8_MMA(0, 1, At, B1); PG8_BAR; PG8_SCHED;
;             PG8_LDA(At, 0, 1); PG8_STAGE(PG8_SB(0, 0), b2, voffB); PG8_STAGE(PG8_SB(0, 1), b2 + hstep, voffB); PG8_STAGE(PG8_SA(0, 0), a2, voffA);
;             PG8_WAIT_V(8); PG8_WAIT_L(0); PG8_BAR; PG8_MMA(1, 0, At, B0); PG8_MMA(1, 1, At, B1); PG8_BAR; PG8_SCHED;
	s_setprio 1
	s_waitcnt lgkmcnt(0)
	v_mfma_f32_16x16x32_bf16 v[140:143], v[64:67], v[176:179], v[140:143]
	v_mfma_f32_16x16x32_bf16 v[136:139], v[72:75], v[176:179], v[136:139]
	v_mfma_f32_16x16x32_bf16 v[124:127], v[64:67], v[184:187], v[124:127]
	v_mfma_f32_16x16x32_bf16 v[120:123], v[72:75], v[184:187], v[120:123]
	v_mfma_f32_16x16x32_bf16 v[108:111], v[64:67], v[192:195], v[108:111]
	v_mfma_f32_16x16x32_bf16 v[104:107], v[72:75], v[192:195], v[104:107]
	v_mfma_f32_16x16x32_bf16 v[92:95], v[64:67], v[200:203], v[92:95]
	v_mfma_f32_16x16x32_bf16 v[88:91], v[72:75], v[200:203], v[88:91]
	v_mfma_f32_16x16x32_bf16 v[140:143], v[68:71], v[180:183], v[140:143]
	v_mfma_f32_16x16x32_bf16 v[136:139], v[76:79], v[180:183], v[136:139]
	v_mfma_f32_16x16x32_bf16 v[124:127], v[68:71], v[188:191], v[124:127]
	v_mfma_f32_16x16x32_bf16 v[120:123], v[76:79], v[188:191], v[120:123]
	v_mfma_f32_16x16x32_bf16 v[108:111], v[68:71], v[196:199], v[108:111]
	v_mfma_f32_16x16x32_bf16 v[104:107], v[76:79], v[196:199], v[104:107]
	v_mfma_f32_16x16x32_bf16 v[92:95], v[68:71], v[204:207], v[92:95]
	v_mfma_f32_16x16x32_bf16 v[88:91], v[76:79], v[204:207], v[88:91]
	s_setprio 0
	s_setprio 1
	v_mfma_f32_16x16x32_bf16 v[132:135], v[144:147], v[176:179], v[132:135]
	v_mfma_f32_16x16x32_bf16 v[128:131], v[152:155], v[176:179], v[128:131]
	v_mfma_f32_16x16x32_bf16 v[116:119], v[144:147], v[184:187], v[116:119]
	v_mfma_f32_16x16x32_bf16 v[112:115], v[152:155], v[184:187], v[112:115]
	v_mfma_f32_16x16x32_bf16 v[100:103], v[144:147], v[192:195], v[100:103]
	v_mfma_f32_16x16x32_bf16 v[96:99], v[152:155], v[192:195], v[96:99]
	v_mfma_f32_16x16x32_bf16 v[84:87], v[144:147], v[200:203], v[84:87]
	v_mfma_f32_16x16x32_bf16 v[80:83], v[152:155], v[200:203], v[80:83]
	v_mfma_f32_16x16x32_bf16 v[132:135], v[148:151], v[180:183], v[132:135]
	v_mfma_f32_16x16x32_bf16 v[128:131], v[156:159], v[180:183], v[128:131]
	v_mfma_f32_16x16x32_bf16 v[116:119], v[148:151], v[188:191], v[116:119]
	v_mfma_f32_16x16x32_bf16 v[112:115], v[156:159], v[188:191], v[112:115]
	v_mfma_f32_16x16x32_bf16 v[100:103], v[148:151], v[196:199], v[100:103]
	v_mfma_f32_16x16x32_bf16 v[96:99], v[156:159], v[196:199], v[96:99]
	v_mfma_f32_16x16x32_bf16 v[84:87], v[148:151], v[204:207], v[84:87]
	v_mfma_f32_16x16x32_bf16 v[80:83], v[156:159], v[204:207], v[80:83]
	s_setprio 0
	s_barrier
	s_add_i32 s82, s75, s64
	s_mov_b64 s[96:97], s[60:61]
	s_nop 0
	s_mov_b32 m0, s82
	ds_read_b128 v[176:179], v213 offset:16384
	ds_read_b128 v[180:183], v213 offset:17408
	ds_read_b128 v[184:187], v213 offset:18432
	ds_read_b128 v[188:191], v213 offset:19456
	ds_read_b128 v[192:195], v213 offset:20480
	ds_read_b128 v[196:199], v213 offset:21504
	ds_read_b128 v[200:203], v213 offset:22528
	ds_read_b128 v[204:207], v213 offset:23552
	global_load_lds_dwordx4 v162, s[60:61]
	s_add_i32 m0, s82, 0x2000
	s_add_u32 s82, s60, 0x80000
	s_nop 0
	s_addc_u32 s83, s61, 0
	s_add_i32 s84, s76, s64
	global_load_lds_dwordx4 v166, s[60:61]
	s_nop 0
	s_mov_b32 m0, s84
	s_nop 0
	global_load_lds_dwordx4 v162, s[82:83]
	s_nop 0
	s_add_i32 m0, s84, 0x2000
	s_nop 0
	global_load_lds_dwordx4 v166, s[82:83]
	s_mov_b64 s[98:99], s[62:63]
	s_nop 0
	s_mov_b32 m0, s57
	s_nop 0
	global_load_lds_dwordx4 v160, s[62:63]
	s_mov_b32 m0, s65
	s_nop 0
	global_load_lds_dwordx4 v164, s[62:63]
	s_waitcnt vmcnt(8)
	s_waitcnt lgkmcnt(0)
	s_barrier
	s_setprio 1
	s_waitcnt lgkmcnt(0)
	v_mfma_f32_16x16x32_bf16 v[60:63], v[64:67], v[176:179], v[60:63]
	v_mfma_f32_16x16x32_bf16 v[56:59], v[72:75], v[176:179], v[56:59]
	v_mfma_f32_16x16x32_bf16 v[44:47], v[64:67], v[184:187], v[44:47]
	v_mfma_f32_16x16x32_bf16 v[40:43], v[72:75], v[184:187], v[40:43]
	v_mfma_f32_16x16x32_bf16 v[28:31], v[64:67], v[192:195], v[28:31]
	v_mfma_f32_16x16x32_bf16 v[24:27], v[72:75], v[192:195], v[24:27]
	v_mfma_f32_16x16x32_bf16 v[12:15], v[64:67], v[200:203], v[12:15]
	v_mfma_f32_16x16x32_bf16 v[8:11], v[72:75], v[200:203], v[8:11]
	v_mfma_f32_16x16x32_bf16 v[60:63], v[68:71], v[180:183], v[60:63]
	v_mfma_f32_16x16x32_bf16 v[56:59], v[76:79], v[180:183], v[56:59]
	v_mfma_f32_16x16x32_bf16 v[44:47], v[68:71], v[188:191], v[44:47]
	v_mfma_f32_16x16x32_bf16 v[40:43], v[76:79], v[188:191], v[40:43]
	v_mfma_f32_16x16x32_bf16 v[28:31], v[68:71], v[196:199], v[28:31]
	v_mfma_f32_16x16x32_bf16 v[24:27], v[76:79], v[196:199], v[24:27]
	v_mfma_f32_16x16x32_bf16 v[12:15], v[68:71], v[204:207], v[12:15]
	v_mfma_f32_16x16x32_bf16 v[8:11], v[76:79], v[204:207], v[8:11]
	s_setprio 0
	s_setprio 1
	v_mfma_f32_16x16x32_bf16 v[52:55], v[144:147], v[176:179], v[52:55]
	v_mfma_f32_16x16x32_bf16 v[48:51], v[152:155], v[176:179], v[48:51]
	v_mfma_f32_16x16x32_bf16 v[36:39], v[144:147], v[184:187], v[36:39]
	v_mfma_f32_16x16x32_bf16 v[32:35], v[152:155], v[184:187], v[32:35]
	v_mfma_f32_16x16x32_bf16 v[20:23], v[144:147], v[192:195], v[20:23]
	v_mfma_f32_16x16x32_bf16 v[16:19], v[152:155], v[192:195], v[16:19]
	v_mfma_f32_16x16x32_bf16 v[4:7], v[144:147], v[200:203], v[4:7]
	v_mfma_f32_16x16x32_bf16 v[0:3], v[152:155], v[200:203], v[0:3]
	v_mfma_f32_16x16x32_bf16 v[52:55], v[148:151], v[180:183], v[52:55]
	v_mfma_f32_16x16x32_bf16 v[48:51], v[156:159], v[180:183], v[48:51]
	v_mfma_f32_16x16x32_bf16 v[36:39], v[148:151], v[188:191], v[36:39]
	v_mfma_f32_16x16x32_bf16 v[32:35], v[156:159], v[188:191], v[32:35]
	v_mfma_f32_16x16x32_bf16 v[20:23], v[148:151], v[196:199], v[20:23]
	v_mfma_f32_16x16x32_bf16 v[16:19], v[156:159], v[196:199], v[16:19]
	v_mfma_f32_16x16x32_bf16 v[4:7], v[148:151], v[204:207], v[4:7]
	v_mfma_f32_16x16x32_bf16 v[0:3], v[156:159], v[204:207], v[0:3]
	s_setprio 0
	s_barrier
; #define PG8_STAGE(bufoff, gbase, voff) do { _Pragma("unroll") for (int _i = 0; _i < 2; ++_i) \
;         __builtin_amdgcn_global_load_lds((const unsigned*)((const char*)(gbase) + (voff)[_i]), (PG8_LAS unsigned*)(lds + (bufoff) + ldsw + _i * 8192), 16, 0, 0); } while (0)
; #define PG8_LDA(dst, b, h) do { _Pragma("unroll") for (int m = 0; m < 4; ++m) _Pragma("unroll") for (int k = 0; k < 2; ++k) dst[m][k] = *(const PG8_LAS bf16x8*)(lds + PG8_SA(b, h) + aoff + m * 2048 + k * 1024); } while (0)
; #define PG8_LDB(dst, b, h) do { _Pragma("unroll") for (int n = 0; n < 2; ++n) _Pragma("unroll") for (int k = 0; k < 2; ++k) dst[n][k] = *(const PG8_LAS bf16x8*)(lds + PG8_SB(b, h) + boff + n * 2048 + k * 1024); } while (0)
; #define PG8_MMA(ai, bj, At, Bt) do { __builtin_amdgcn_s_setprio(1); _Pragma("unroll") for (int m = 0; m < 4; ++m) _Pragma("unroll") for (int n = 0; n < 2; ++n) _Pragma("unroll") for (int k = 0; k < 2; ++k) \
;         acc[ai][bj][m][n] = __builtin_amdgcn_mfma_f32_16x16x32_bf16(Bt[n][k], At[m][k], acc[ai][bj][m][n], 0, 0, 0); __builtin_amdgcn_s_setprio(0); } while (0)
; #define PG8_WAIT_V(n) asm volatile("s_waitcnt vmcnt(" #n ")" ::: "memory")
; #define PG8_WAIT_L(n) asm volatile("s_waitcnt lgkmcnt(" #n ")" ::: "memory")
; #define PG8_BAR __builtin_amdgcn_s_barrier()
; #define PG8_SCHED __builtin_amdgcn_sched_barrier(0)
; template <class Epi, class Sched, bool ALIGN_EPI = false, bool SP2 = false>
; __device__ __forceinline__ void gemm_phase(PG8_LAS unsigned char* lds, const Gemm g, const Sched& S, const Epi& E) {
;     ...
;             PG8_LDB(B0, 1, 0); PG8_LDB(B1, 1, 1); PG8_SCHED; PG8_LDA(At, 1, 0); PG8_STAGE(PG8_SA(0, 1), a2 + hstep, voffA);
;             PG8_WAIT_V(8); PG8_WAIT_L(0); PG8_BAR; PG8_MMA(0, 0, At, B0); PG8_MMA(0, 1, At, B1); PG8_BAR; PG8_SCHED;
;             PG8_LDA(At, 1, 1); PG8_STAGE(PG8_SB(1, 0), b3, voffB); PG8_STAGE(PG8_SB(1, 1), b3 + hstep, voffB); PG8_STAGE(PG8_SA(1, 0), a3, voffA);
;             PG8_WAIT_V(8); PG8_WAIT_L(0); PG8_BAR; PG8_MMA(1, 0, At, B0); PG8_MMA(1, 1, At, B1); PG8_BAR; PG8_SCHED;
;     ...
;         if constexpr (ALIGN_EPI) { if (wr == 0) PG8_BAR; }
	s_add_i32 s82, 0, 0x18000
	s_add_i32 s83, 0, 0x1c000
	v_add_u32_e32 v76, s82, v209
	v_add_u32_e32 v156, s83, v209
	ds_read_b128 v[64:67], v76
	ds_read_b128 v[68:71], v76 offset:1024
	ds_read_b128 v[72:75], v76 offset:2048
	ds_read_b128 v[76:79], v76 offset:3072
	ds_read_b128 v[144:147], v156
	ds_read_b128 v[148:151], v156 offset:1024
	ds_read_b128 v[152:155], v156 offset:2048
	ds_read_b128 v[156:159], v156 offset:3072
	s_add_u32 s62, s62, 0x80000
	s_addc_u32 s63, s63, 0
	s_mov_b32 m0, s67
	s_nop 0
	ds_read_b128 v[176:179], v213 offset:32768
	ds_read_b128 v[180:183], v213 offset:33792
	ds_read_b128 v[184:187], v213 offset:34816
	ds_read_b128 v[188:191], v213 offset:35840
	ds_read_b128 v[192:195], v213 offset:36864
	ds_read_b128 v[196:199], v213 offset:37888
	ds_read_b128 v[200:203], v213 offset:38912
	ds_read_b128 v[204:207], v213 offset:39936
	global_load_lds_dwordx4 v160, s[62:63]
	s_nop 0
	s_mov_b32 m0, s68
	s_nop 0
	global_load_lds_dwordx4 v164, s[62:63]
	s_waitcnt vmcnt(8)
	s_waitcnt lgkmcnt(0)
	s_barrier
	s_setprio 1
	s_waitcnt lgkmcnt(0)
	v_mfma_f32_16x16x32_bf16 v[140:143], v[64:67], v[176:179], v[140:143]
	v_mfma_f32_16x16x32_bf16 v[136:139], v[72:75], v[176:179], v[136:139]
	v_mfma_f32_16x16x32_bf16 v[124:127], v[64:67], v[184:187], v[124:127]
	v_mfma_f32_16x16x32_bf16 v[120:123], v[72:75], v[184:187], v[120:123]
	v_mfma_f32_16x16x32_bf16 v[108:111], v[64:67], v[192:195], v[108:111]
	v_mfma_f32_16x16x32_bf16 v[104:107], v[72:75], v[192:195], v[104:107]
	v_mfma_f32_16x16x32_bf16 v[92:95], v[64:67], v[200:203], v[92:95]
	v_mfma_f32_16x16x32_bf16 v[88:91], v[72:75], v[200:203], v[88:91]
	v_mfma_f32_16x16x32_bf16 v[140:143], v[68:71], v[180:183], v[140:143]
	v_mfma_f32_16x16x32_bf16 v[136:139], v[76:79], v[180:183], v[136:139]
	v_mfma_f32_16x16x32_bf16 v[124:127], v[68:71], v[188:191], v[124:127]
	v_mfma_f32_16x16x32_bf16 v[120:123], v[76:79], v[188:191], v[120:123]
	v_mfma_f32_16x16x32_bf16 v[108:111], v[68:71], v[196:199], v[108:111]
	v_mfma_f32_16x16x32_bf16 v[104:107], v[76:79], v[196:199], v[104:107]
	v_mfma_f32_16x16x32_bf16 v[92:95], v[68:71], v[204:207], v[92:95]
	v_mfma_f32_16x16x32_bf16 v[88:91], v[76:79], v[204:207], v[88:91]
	s_setprio 0
	s_setprio 1
	v_mfma_f32_16x16x32_bf16 v[132:135], v[144:147], v[176:179], v[132:135]
	v_mfma_f32_16x16x32_bf16 v[128:131], v[152:155], v[176:179], v[128:131]
	v_mfma_f32_16x16x32_bf16 v[116:119], v[144:147], v[184:187], v[116:119]
	v_mfma_f32_16x16x32_bf16 v[112:115], v[152:155], v[184:187], v[112:115]
	v_mfma_f32_16x16x32_bf16 v[100:103], v[144:147], v[192:195], v[100:103]
	v_mfma_f32_16x16x32_bf16 v[96:99], v[152:155], v[192:195], v[96:99]
	v_mfma_f32_16x16x32_bf16 v[84:87], v[144:147], v[200:203], v[84:87]
	v_mfma_f32_16x16x32_bf16 v[80:83], v[152:155], v[200:203], v[80:83]
	v_mfma_f32_16x16x32_bf16 v[132:135], v[148:151], v[180:183], v[132:135]
	v_mfma_f32_16x16x32_bf16 v[128:131], v[156:159], v[180:183], v[128:131]
	v_mfma_f32_16x16x32_bf16 v[116:119], v[148:151], v[188:191], v[116:119]
	v_mfma_f32_16x16x32_bf16 v[112:115], v[156:159], v[188:191], v[112:115]
	v_mfma_f32_16x16x32_bf16 v[100:103], v[148:151], v[196:199], v[100:103]
	v_mfma_f32_16x16x32_bf16 v[96:99], v[156:159], v[196:199], v[96:99]
	v_mfma_f32_16x16x32_bf16 v[84:87], v[148:151], v[204:207], v[84:87]
	v_mfma_f32_16x16x32_bf16 v[80:83], v[156:159], v[204:207], v[80:83]
	s_setprio 0
	s_barrier
	s_add_i32 s62, s82, s64
	s_nop 0
	s_mov_b32 m0, s62
	ds_read_b128 v[176:179], v213 offset:49152
	ds_read_b128 v[180:183], v213 offset:50176
	ds_read_b128 v[184:187], v213 offset:51200
	ds_read_b128 v[188:191], v213 offset:52224
	ds_read_b128 v[192:195], v213 offset:53248
	ds_read_b128 v[196:199], v213 offset:54272
	ds_read_b128 v[200:203], v213 offset:55296
	ds_read_b128 v[204:207], v213 offset:56320
	global_load_lds_dwordx4 v250, s[96:97]
	s_add_i32 m0, s62, 0x2000
	s_add_u32 s60, s60, 0x80080
	s_nop 0
	s_addc_u32 s61, s61, 0
	s_add_i32 s62, s83, s64
	global_load_lds_dwordx4 v251, s[96:97]
	s_nop 0
	s_mov_b32 m0, s62
	s_nop 0
	global_load_lds_dwordx4 v162, s[60:61]
	s_nop 0
	s_add_i32 m0, s62, 0x2000
	s_nop 0
	global_load_lds_dwordx4 v166, s[60:61]
	s_nop 0
	s_mov_b32 m0, s70
	s_nop 0
	global_load_lds_dwordx4 v252, s[98:99]
	s_nop 0
	s_mov_b32 m0, s71
	s_nop 0
	global_load_lds_dwordx4 v253, s[98:99]
	s_waitcnt vmcnt(8)
	s_waitcnt lgkmcnt(0)
	s_barrier
	s_setprio 1
	s_waitcnt lgkmcnt(0)
	v_mfma_f32_16x16x32_bf16 v[60:63], v[64:67], v[176:179], v[60:63]
	v_mfma_f32_16x16x32_bf16 v[56:59], v[72:75], v[176:179], v[56:59]
	v_mfma_f32_16x16x32_bf16 v[44:47], v[64:67], v[184:187], v[44:47]
	v_mfma_f32_16x16x32_bf16 v[40:43], v[72:75], v[184:187], v[40:43]
	v_mfma_f32_16x16x32_bf16 v[28:31], v[64:67], v[192:195], v[28:31]
	v_mfma_f32_16x16x32_bf16 v[24:27], v[72:75], v[192:195], v[24:27]
	v_mfma_f32_16x16x32_bf16 v[12:15], v[64:67], v[200:203], v[12:15]
	v_mfma_f32_16x16x32_bf16 v[8:11], v[72:75], v[200:203], v[8:11]
	v_mfma_f32_16x16x32_bf16 v[60:63], v[68:71], v[180:183], v[60:63]
	v_mfma_f32_16x16x32_bf16 v[56:59], v[76:79], v[180:183], v[56:59]
	v_mfma_f32_16x16x32_bf16 v[44:47], v[68:71], v[188:191], v[44:47]
	v_mfma_f32_16x16x32_bf16 v[40:43], v[76:79], v[188:191], v[40:43]
	v_mfma_f32_16x16x32_bf16 v[28:31], v[68:71], v[196:199], v[28:31]
	v_mfma_f32_16x16x32_bf16 v[24:27], v[76:79], v[196:199], v[24:27]
	v_mfma_f32_16x16x32_bf16 v[12:15], v[68:71], v[204:207], v[12:15]
	v_mfma_f32_16x16x32_bf16 v[8:11], v[76:79], v[204:207], v[8:11]
	s_setprio 0
	s_setprio 1
	v_mfma_f32_16x16x32_bf16 v[52:55], v[144:147], v[176:179], v[52:55]
	v_mfma_f32_16x16x32_bf16 v[48:51], v[152:155], v[176:179], v[48:51]
	v_mfma_f32_16x16x32_bf16 v[36:39], v[144:147], v[184:187], v[36:39]
	v_mfma_f32_16x16x32_bf16 v[32:35], v[152:155], v[184:187], v[32:35]
	v_mfma_f32_16x16x32_bf16 v[20:23], v[144:147], v[192:195], v[20:23]
	v_mfma_f32_16x16x32_bf16 v[16:19], v[152:155], v[192:195], v[16:19]
	v_mfma_f32_16x16x32_bf16 v[4:7], v[144:147], v[200:203], v[4:7]
	v_mfma_f32_16x16x32_bf16 v[0:3], v[152:155], v[200:203], v[0:3]
	v_mfma_f32_16x16x32_bf16 v[52:55], v[148:151], v[180:183], v[52:55]
	v_mfma_f32_16x16x32_bf16 v[48:51], v[156:159], v[180:183], v[48:51]
	v_mfma_f32_16x16x32_bf16 v[36:39], v[148:151], v[188:191], v[36:39]
	v_mfma_f32_16x16x32_bf16 v[32:35], v[156:159], v[188:191], v[32:35]
	v_mfma_f32_16x16x32_bf16 v[20:23], v[148:151], v[196:199], v[20:23]
	v_mfma_f32_16x16x32_bf16 v[16:19], v[156:159], v[196:199], v[16:19]
	v_mfma_f32_16x16x32_bf16 v[4:7], v[148:151], v[204:207], v[4:7]
	v_mfma_f32_16x16x32_bf16 v[0:3], v[156:159], v[204:207], v[0:3]
	s_setprio 0
	s_barrier
	s_add_i32 s81, s81, 2
	s_add_u32 s58, s58, 0x100
	s_addc_u32 s59, s59, 0
	s_add_u32 s79, s79, 0x100
	s_addc_u32 s80, s80, 0
	s_cmp_gt_u32 s81, 29
	s_cbranch_scc0 .LBB0_333
	s_and_b64 vcc, exec, s[42:43]
	s_cbranch_vccz .LBB0_336
	s_barrier

; #define PG8_STAGE(bufoff, gbase, voff) do { _Pragma("unroll") for (int _i = 0; _i < 2; ++_i) \
;         __builtin_amdgcn_global_load_lds((const unsigned*)((const char*)(gbase) + (voff)[_i]), (PG8_LAS unsigned*)(lds + (bufoff) + ldsw + _i * 8192), 16, 0, 0); } while (0)
; #define PG8_LDA(dst, b, h) do { _Pragma("unroll") for (int m = 0; m < 4; ++m) _Pragma("unroll") for (int k = 0; k < 2; ++k) dst[m][k] = *(const PG8_LAS bf16x8*)(lds + PG8_SA(b, h) + aoff + m * 2048 + k * 1024); } while (0)
; #define PG8_LDB(dst, b, h) do { _Pragma("unroll") for (int n = 0; n < 2; ++n) _Pragma("unroll") for (int k = 0; k < 2; ++k) dst[n][k] = *(const PG8_LAS bf16x8*)(lds + PG8_SB(b, h) + boff + n * 2048 + k * 1024); } while (0)
; #define PG8_SCHED __builtin_amdgcn_sched_barrier(0)
; template <class Epi, class Sched, bool ALIGN_EPI = false, bool SP2 = false>
; __device__ __forceinline__ void gemm_phase(PG8_LAS unsigned char* lds, const Gemm g, const Sched& S, const Epi& E) {
;     ...
; #pragma unroll
;     for (int a = 0; a < 2; ++a)
; #pragma unroll
;         for (int b = 0; b < 2; ++b)
; #pragma unroll
;             for (int m = 0; m < 4; ++m)
; #pragma unroll
;                 for (int n = 0; n < 2; ++n) acc[a][b][m][n] = (f32x4){0.f, 0.f, 0.f, 0.f};
;     ...
;         const bool has_next = S.next(ui + 1, nxt);
;         const char* nA = has_next ? (const char*)g.A + (size_t)nxt.pm * tstep : cA; const char* nB = has_next ? (const char*)g.Bt + (size_t)nxt.pn * tstep : cB;
;         for (int t = 0; t < nt; t += 2) {
;             const bool last = (t == nt - 2);
;             const char* a1 = cA + (size_t)(t + 1) * kstep;
;             const char* a2 = last ? nA : cA + (size_t)(t + 2) * kstep; const char* b2 = last ? nB : cB + (size_t)(t + 2) * kstep;
;             const char* a3 = a2 + kstep; const char* b3 = b2 + kstep;
;             if (last && has_next) S.a_ready(nxt);
;             if constexpr (SP2) {
;             PG8_LDB(B0, 0, 0); PG8_LDB(B1, 0, 1); PG8_SCHED; PG8_LDA(At, 0, 0); PG8_STAGE(PG8_SA(1, 1), a1 + hstep, voffA);
.LBB0_427:
	s_ashr_i32 s55, s54, 31
	s_lshl_b64 s[56:57], s[54:55], 20
	s_add_u32 s56, s24, s56
	s_addc_u32 s57, s25, s57
	s_and_b64 s[58:59], s[4:5], exec
	s_cselect_b32 s55, s57, s11
	s_cselect_b32 s81, s56, s10
	s_ashr_i32 s53, s52, 31
	s_lshl_b64 s[58:59], s[52:53], 20
	s_add_u32 s58, s62, s58
	s_addc_u32 s59, s63, s59
	s_and_b64 s[60:61], s[4:5], exec
	s_cselect_b32 s53, s59, s13
	s_cselect_b32 s82, s58, s12
	s_add_u32 s10, s10, 0x80080
	s_addc_u32 s11, s11, 0
	s_add_u32 s83, s12, 0x100
	v_mov_b32_e32 v0, 0
	s_addc_u32 s84, s13, 0
	s_mov_b32 s85, -2
	v_mov_b32_e32 v1, v0
	v_mov_b32_e32 v2, v0
	v_mov_b32_e32 v3, v0
	v_mov_b32_e32 v4, v0
	v_mov_b32_e32 v5, v0
	v_mov_b32_e32 v6, v0
	v_mov_b32_e32 v7, v0
	v_mov_b32_e32 v16, v0
	v_mov_b32_e32 v17, v0
	v_mov_b32_e32 v18, v0
	v_mov_b32_e32 v19, v0
	v_mov_b32_e32 v20, v0
	v_mov_b32_e32 v21, v0
	v_mov_b32_e32 v22, v0
	v_mov_b32_e32 v23, v0
	v_mov_b32_e32 v32, v0
	v_mov_b32_e32 v33, v0
	v_mov_b32_e32 v34, v0
	v_mov_b32_e32 v35, v0
	v_mov_b32_e32 v36, v0
	v_mov_b32_e32 v37, v0
	v_mov_b32_e32 v38, v0
	v_mov_b32_e32 v39, v0
	v_mov_b32_e32 v48, v0
	v_mov_b32_e32 v49, v0
	v_mov_b32_e32 v50, v0
	v_mov_b32_e32 v51, v0
	v_mov_b32_e32 v52, v0
	v_mov_b32_e32 v53, v0
	v_mov_b32_e32 v54, v0
	v_mov_b32_e32 v55, v0
	v_mov_b32_e32 v8, v0
	v_mov_b32_e32 v9, v0
	v_mov_b32_e32 v10, v0
	v_mov_b32_e32 v11, v0
	v_mov_b32_e32 v12, v0
	v_mov_b32_e32 v13, v0
	v_mov_b32_e32 v14, v0
	v_mov_b32_e32 v15, v0
	v_mov_b32_e32 v24, v0
	v_mov_b32_e32 v25, v0
	v_mov_b32_e32 v26, v0
	v_mov_b32_e32 v27, v0
	v_mov_b32_e32 v28, v0
	v_mov_b32_e32 v29, v0
	v_mov_b32_e32 v30, v0
	v_mov_b32_e32 v31, v0
	v_mov_b32_e32 v40, v0
	v_mov_b32_e32 v41, v0
	v_mov_b32_e32 v42, v0
	v_mov_b32_e32 v43, v0
	v_mov_b32_e32 v44, v0
	v_mov_b32_e32 v45, v0
	v_mov_b32_e32 v46, v0
	v_mov_b32_e32 v47, v0
	v_mov_b32_e32 v56, v0
	v_mov_b32_e32 v57, v0
	v_mov_b32_e32 v58, v0
	v_mov_b32_e32 v59, v0
	v_mov_b32_e32 v60, v0
	v_mov_b32_e32 v61, v0
	v_mov_b32_e32 v62, v0
	v_mov_b32_e32 v63, v0
	v_mov_b32_e32 v64, v0
	v_mov_b32_e32 v65, v0
	v_mov_b32_e32 v66, v0
	v_mov_b32_e32 v67, v0
	v_mov_b32_e32 v68, v0
	v_mov_b32_e32 v69, v0
	v_mov_b32_e32 v70, v0
	v_mov_b32_e32 v71, v0
	v_mov_b32_e32 v80, v0
	v_mov_b32_e32 v81, v0
	v_mov_b32_e32 v82, v0
	v_mov_b32_e32 v83, v0
	v_mov_b32_e32 v84, v0
	v_mov_b32_e32 v85, v0
	v_mov_b32_e32 v86, v0
	v_mov_b32_e32 v87, v0
	v_mov_b32_e32 v96, v0
	v_mov_b32_e32 v97, v0
	v_mov_b32_e32 v98, v0
	v_mov_b32_e32 v99, v0
	v_mov_b32_e32 v100, v0
	v_mov_b32_e32 v101, v0
	v_mov_b32_e32 v102, v0
	v_mov_b32_e32 v103, v0
	v_mov_b32_e32 v112, v0
	v_mov_b32_e32 v113, v0
	v_mov_b32_e32 v114, v0
	v_mov_b32_e32 v115, v0
	v_mov_b32_e32 v116, v0
	v_mov_b32_e32 v117, v0
	v_mov_b32_e32 v118, v0
	v_mov_b32_e32 v119, v0
	v_mov_b32_e32 v72, v0
	v_mov_b32_e32 v73, v0
	v_mov_b32_e32 v74, v0
	v_mov_b32_e32 v75, v0
	v_mov_b32_e32 v76, v0
	v_mov_b32_e32 v77, v0
	v_mov_b32_e32 v78, v0
	v_mov_b32_e32 v79, v0
	v_mov_b32_e32 v88, v0
	v_mov_b32_e32 v89, v0
	v_mov_b32_e32 v90, v0
	v_mov_b32_e32 v91, v0
	v_mov_b32_e32 v92, v0
	v_mov_b32_e32 v93, v0
	v_mov_b32_e32 v94, v0
	v_mov_b32_e32 v95, v0
	v_mov_b32_e32 v104, v0
	v_mov_b32_e32 v105, v0
	v_mov_b32_e32 v106, v0
	v_mov_b32_e32 v107, v0
	v_mov_b32_e32 v108, v0
	v_mov_b32_e32 v109, v0
	v_mov_b32_e32 v110, v0
	v_mov_b32_e32 v111, v0
	v_mov_b32_e32 v120, v0
	v_mov_b32_e32 v121, v0
	v_mov_b32_e32 v122, v0
	v_mov_b32_e32 v123, v0
	v_mov_b32_e32 v124, v0
	v_mov_b32_e32 v125, v0
	v_mov_b32_e32 v126, v0
	v_mov_b32_e32 v127, v0
	v_add_u32_e32 v253, 0x80, v164
	v_add_u32_e32 v252, 0x80, v160
	v_add_u32_e32 v251, 0x80, v166
	v_add_u32_e32 v250, 0x80, v162
.LBB0_428:
	ds_read_b128 v[128:131], v201
	ds_read_b128 v[132:135], v201 offset:1024
	ds_read_b128 v[136:139], v201 offset:2048
	ds_read_b128 v[140:143], v201 offset:3072
	ds_read_b128 v[144:147], v205
	ds_read_b128 v[148:151], v205 offset:1024
	ds_read_b128 v[152:155], v205 offset:2048
	ds_read_b128 v[156:159], v205 offset:3072
	s_add_u32 s12, s10, 0xfff80080
	s_addc_u32 s13, s11, -1
	s_cmp_eq_u32 s85, 28
	s_cselect_b32 s61, s55, s13
	s_cselect_b32 s60, s81, s12
	s_cselect_b32 s13, s53, s84
	s_cselect_b32 s12, s82, s83
	s_nop 0
	s_add_i32 m0, s65, 0xc000
	ds_read_b128 v[176:179], v207
	ds_read_b128 v[184:187], v207 offset:1024
	ds_read_b128 v[190:193], v207 offset:2048
	ds_read_b128 v[210:213], v207 offset:3072
	ds_read_b128 v[214:217], v207 offset:4096
	ds_read_b128 v[218:221], v207 offset:5120
	ds_read_b128 v[222:225], v207 offset:6144
	ds_read_b128 v[226:229], v207 offset:7168
	global_load_lds_dwordx4 v168, s[10:11]
	s_nop 0
	s_add_i32 m0, s65, 0xe000
	s_nop 0
	global_load_lds_dwordx4 v170, s[10:11]
	s_waitcnt vmcnt(8)
	s_waitcnt lgkmcnt(0)
	s_barrier
; #define PG8_STAGE(bufoff, gbase, voff) do { _Pragma("unroll") for (int _i = 0; _i < 2; ++_i) \
;         __builtin_amdgcn_global_load_lds((const unsigned*)((const char*)(gbase) + (voff)[_i]), (PG8_LAS unsigned*)(lds + (bufoff) + ldsw + _i * 8192), 16, 0, 0); } while (0)
; #define PG8_LDA(dst, b, h) do { _Pragma("unroll") for (int m = 0; m < 4; ++m) _Pragma("unroll") for (int k = 0; k < 2; ++k) dst[m][k] = *(const PG8_LAS bf16x8*)(lds + PG8_SA(b, h) + aoff + m * 2048 + k * 1024); } while (0)
; #define PG8_MMA(ai, bj, At, Bt) do { __builtin_amdgcn_s_setprio(1); _Pragma("unroll") for (int m = 0; m < 4; ++m) _Pragma("unroll") for (int n = 0; n < 2; ++n) _Pragma("unroll") for (int k = 0; k < 2; ++k) \
;         acc[ai][bj][m][n] = __builtin_amdgcn_mfma_f32_16x16x32_bf16(Bt[n][k], At[m][k], acc[ai][bj][m][n], 0, 0, 0); __builtin_amdgcn_s_setprio(0); } while (0)
; #define PG8_WAIT_V(n) asm volatile("s_waitcnt vmcnt(" #n ")" ::: "memory")
; #define PG8_WAIT_L(n) asm volatile("s_waitcnt lgkmcnt(" #n ")" ::: "memory")
; #define PG8_BAR __builtin_amdgcn_s_barrier()
; #define PG8_SCHED __builtin_amdgcn_sched_barrier(0)
; template <class Epi, class Sched, bool ALIGN_EPI = false, bool SP2 = false>
; __device__ __forceinline__ void gemm_phase(PG8_LAS unsigned char* lds, const Gemm g, const Sched& S, const Epi& E) {
;     ...
;             PG8_WAIT_V(8); PG8_WAIT_L(0); PG8_BAR; PG8_MMA(0, 0, At, B0); PG8_MMA(0, 1, At, B1); PG8_BAR; PG8_SCHED;
;             PG8_LDA(At, 0, 1); PG8_STAGE(PG8_SB(0, 0), b2, voffB); PG8_STAGE(PG8_SB(0, 1), b2 + hstep, voffB); PG8_STAGE(PG8_SA(0, 0), a2, voffA);
;             PG8_WAIT_V(8); PG8_WAIT_L(0); PG8_BAR; PG8_MMA(1, 0, At, B0); PG8_MMA(1, 1, At, B1); PG8_BAR; PG8_SCHED;
	s_setprio 1
	s_waitcnt lgkmcnt(0)
	v_mfma_f32_16x16x32_bf16 v[124:127], v[128:131], v[176:179], v[124:127]
	v_mfma_f32_16x16x32_bf16 v[120:123], v[136:139], v[176:179], v[120:123]
	v_mfma_f32_16x16x32_bf16 v[108:111], v[128:131], v[190:193], v[108:111]
	v_mfma_f32_16x16x32_bf16 v[104:107], v[136:139], v[190:193], v[104:107]
	v_mfma_f32_16x16x32_bf16 v[92:95], v[128:131], v[214:217], v[92:95]
	v_mfma_f32_16x16x32_bf16 v[88:91], v[136:139], v[214:217], v[88:91]
	v_mfma_f32_16x16x32_bf16 v[76:79], v[128:131], v[222:225], v[76:79]
	v_mfma_f32_16x16x32_bf16 v[72:75], v[136:139], v[222:225], v[72:75]
	v_mfma_f32_16x16x32_bf16 v[124:127], v[132:135], v[184:187], v[124:127]
	v_mfma_f32_16x16x32_bf16 v[120:123], v[140:143], v[184:187], v[120:123]
	v_mfma_f32_16x16x32_bf16 v[108:111], v[132:135], v[210:213], v[108:111]
	v_mfma_f32_16x16x32_bf16 v[104:107], v[140:143], v[210:213], v[104:107]
	v_mfma_f32_16x16x32_bf16 v[92:95], v[132:135], v[218:221], v[92:95]
	v_mfma_f32_16x16x32_bf16 v[88:91], v[140:143], v[218:221], v[88:91]
	v_mfma_f32_16x16x32_bf16 v[76:79], v[132:135], v[226:229], v[76:79]
	v_mfma_f32_16x16x32_bf16 v[72:75], v[140:143], v[226:229], v[72:75]
	s_setprio 0
	s_setprio 1
	v_mfma_f32_16x16x32_bf16 v[116:119], v[144:147], v[176:179], v[116:119]
	v_mfma_f32_16x16x32_bf16 v[112:115], v[152:155], v[176:179], v[112:115]
	v_mfma_f32_16x16x32_bf16 v[100:103], v[144:147], v[190:193], v[100:103]
	v_mfma_f32_16x16x32_bf16 v[96:99], v[152:155], v[190:193], v[96:99]
	v_mfma_f32_16x16x32_bf16 v[84:87], v[144:147], v[214:217], v[84:87]
	v_mfma_f32_16x16x32_bf16 v[80:83], v[152:155], v[214:217], v[80:83]
	v_mfma_f32_16x16x32_bf16 v[68:71], v[144:147], v[222:225], v[68:71]
	v_mfma_f32_16x16x32_bf16 v[64:67], v[152:155], v[222:225], v[64:67]
	v_mfma_f32_16x16x32_bf16 v[116:119], v[148:151], v[184:187], v[116:119]
	v_mfma_f32_16x16x32_bf16 v[112:115], v[156:159], v[184:187], v[112:115]
	v_mfma_f32_16x16x32_bf16 v[100:103], v[148:151], v[210:213], v[100:103]
	v_mfma_f32_16x16x32_bf16 v[96:99], v[156:159], v[210:213], v[96:99]
	v_mfma_f32_16x16x32_bf16 v[84:87], v[148:151], v[218:221], v[84:87]
	v_mfma_f32_16x16x32_bf16 v[80:83], v[156:159], v[218:221], v[80:83]
	v_mfma_f32_16x16x32_bf16 v[68:71], v[148:151], v[226:229], v[68:71]
	v_mfma_f32_16x16x32_bf16 v[64:67], v[156:159], v[226:229], v[64:67]
	s_setprio 0
	s_barrier
	s_add_i32 s86, s75, s64
	s_mov_b64 s[96:97], s[12:13]
	s_nop 0
	s_mov_b32 m0, s86
	ds_read_b128 v[176:179], v207 offset:16384
	ds_read_b128 v[184:187], v207 offset:17408
	ds_read_b128 v[190:193], v207 offset:18432
	ds_read_b128 v[210:213], v207 offset:19456
	ds_read_b128 v[214:217], v207 offset:20480
	ds_read_b128 v[218:221], v207 offset:21504
	ds_read_b128 v[222:225], v207 offset:22528
	ds_read_b128 v[226:229], v207 offset:23552
	global_load_lds_dwordx4 v162, s[12:13]
	s_add_i32 m0, s86, 0x2000
	s_add_u32 s86, s12, 0x80000
	s_nop 0
	s_addc_u32 s87, s13, 0
	s_add_i32 s88, s76, s64
	global_load_lds_dwordx4 v166, s[12:13]
	s_nop 0
	s_mov_b32 m0, s88
	s_nop 0
	global_load_lds_dwordx4 v162, s[86:87]
	s_nop 0
	s_add_i32 m0, s88, 0x2000
	s_nop 0
	global_load_lds_dwordx4 v166, s[86:87]
	s_mov_b64 s[98:99], s[60:61]
	s_nop 0
	s_mov_b32 m0, s65
	s_nop 0
	global_load_lds_dwordx4 v160, s[60:61]
	s_mov_b32 m0, s67
	s_nop 0
	global_load_lds_dwordx4 v164, s[60:61]
	s_waitcnt vmcnt(8)
	s_waitcnt lgkmcnt(0)
	s_barrier
	s_setprio 1
	s_waitcnt lgkmcnt(0)
	v_mfma_f32_16x16x32_bf16 v[60:63], v[128:131], v[176:179], v[60:63]
	v_mfma_f32_16x16x32_bf16 v[56:59], v[136:139], v[176:179], v[56:59]
	v_mfma_f32_16x16x32_bf16 v[44:47], v[128:131], v[190:193], v[44:47]
	v_mfma_f32_16x16x32_bf16 v[40:43], v[136:139], v[190:193], v[40:43]
	v_mfma_f32_16x16x32_bf16 v[28:31], v[128:131], v[214:217], v[28:31]
	v_mfma_f32_16x16x32_bf16 v[24:27], v[136:139], v[214:217], v[24:27]
	v_mfma_f32_16x16x32_bf16 v[12:15], v[128:131], v[222:225], v[12:15]
	v_mfma_f32_16x16x32_bf16 v[8:11], v[136:139], v[222:225], v[8:11]
	v_mfma_f32_16x16x32_bf16 v[60:63], v[132:135], v[184:187], v[60:63]
	v_mfma_f32_16x16x32_bf16 v[56:59], v[140:143], v[184:187], v[56:59]
	v_mfma_f32_16x16x32_bf16 v[44:47], v[132:135], v[210:213], v[44:47]
	v_mfma_f32_16x16x32_bf16 v[40:43], v[140:143], v[210:213], v[40:43]
	v_mfma_f32_16x16x32_bf16 v[28:31], v[132:135], v[218:221], v[28:31]
	v_mfma_f32_16x16x32_bf16 v[24:27], v[140:143], v[218:221], v[24:27]
	v_mfma_f32_16x16x32_bf16 v[12:15], v[132:135], v[226:229], v[12:15]
	v_mfma_f32_16x16x32_bf16 v[8:11], v[140:143], v[226:229], v[8:11]
	s_setprio 0
	s_setprio 1
	v_mfma_f32_16x16x32_bf16 v[52:55], v[144:147], v[176:179], v[52:55]
	v_mfma_f32_16x16x32_bf16 v[48:51], v[152:155], v[176:179], v[48:51]
	v_mfma_f32_16x16x32_bf16 v[36:39], v[144:147], v[190:193], v[36:39]
	v_mfma_f32_16x16x32_bf16 v[32:35], v[152:155], v[190:193], v[32:35]
	v_mfma_f32_16x16x32_bf16 v[20:23], v[144:147], v[214:217], v[20:23]
	v_mfma_f32_16x16x32_bf16 v[16:19], v[152:155], v[214:217], v[16:19]
	v_mfma_f32_16x16x32_bf16 v[4:7], v[144:147], v[222:225], v[4:7]
	v_mfma_f32_16x16x32_bf16 v[0:3], v[152:155], v[222:225], v[0:3]
	v_mfma_f32_16x16x32_bf16 v[52:55], v[148:151], v[184:187], v[52:55]
	v_mfma_f32_16x16x32_bf16 v[48:51], v[156:159], v[184:187], v[48:51]
	v_mfma_f32_16x16x32_bf16 v[36:39], v[148:151], v[210:213], v[36:39]
	v_mfma_f32_16x16x32_bf16 v[32:35], v[156:159], v[210:213], v[32:35]
	v_mfma_f32_16x16x32_bf16 v[20:23], v[148:151], v[218:221], v[20:23]
	v_mfma_f32_16x16x32_bf16 v[16:19], v[156:159], v[218:221], v[16:19]
	v_mfma_f32_16x16x32_bf16 v[4:7], v[148:151], v[226:229], v[4:7]
	v_mfma_f32_16x16x32_bf16 v[0:3], v[156:159], v[226:229], v[0:3]
	s_setprio 0
	s_barrier
; #define PG8_STAGE(bufoff, gbase, voff) do { _Pragma("unroll") for (int _i = 0; _i < 2; ++_i) \
;         __builtin_amdgcn_global_load_lds((const unsigned*)((const char*)(gbase) + (voff)[_i]), (PG8_LAS unsigned*)(lds + (bufoff) + ldsw + _i * 8192), 16, 0, 0); } while (0)
; #define PG8_LDA(dst, b, h) do { _Pragma("unroll") for (int m = 0; m < 4; ++m) _Pragma("unroll") for (int k = 0; k < 2; ++k) dst[m][k] = *(const PG8_LAS bf16x8*)(lds + PG8_SA(b, h) + aoff + m * 2048 + k * 1024); } while (0)
; #define PG8_LDB(dst, b, h) do { _Pragma("unroll") for (int n = 0; n < 2; ++n) _Pragma("unroll") for (int k = 0; k < 2; ++k) dst[n][k] = *(const PG8_LAS bf16x8*)(lds + PG8_SB(b, h) + boff + n * 2048 + k * 1024); } while (0)
; #define PG8_MMA(ai, bj, At, Bt) do { __builtin_amdgcn_s_setprio(1); _Pragma("unroll") for (int m = 0; m < 4; ++m) _Pragma("unroll") for (int n = 0; n < 2; ++n) _Pragma("unroll") for (int k = 0; k < 2; ++k) \
;         acc[ai][bj][m][n] = __builtin_amdgcn_mfma_f32_16x16x32_bf16(Bt[n][k], At[m][k], acc[ai][bj][m][n], 0, 0, 0); __builtin_amdgcn_s_setprio(0); } while (0)
; #define PG8_WAIT_V(n) asm volatile("s_waitcnt vmcnt(" #n ")" ::: "memory")
; #define PG8_WAIT_L(n) asm volatile("s_waitcnt lgkmcnt(" #n ")" ::: "memory")
; #define PG8_BAR __builtin_amdgcn_s_barrier()
; #define PG8_SCHED __builtin_amdgcn_sched_barrier(0)
; template <class Epi, class Sched, bool ALIGN_EPI = false, bool SP2 = false>
; __device__ __forceinline__ void gemm_phase(PG8_LAS unsigned char* lds, const Gemm g, const Sched& S, const Epi& E) {
;     ...
;             PG8_LDB(B0, 1, 0); PG8_LDB(B1, 1, 1); PG8_SCHED; PG8_LDA(At, 1, 0); PG8_STAGE(PG8_SA(0, 1), a2 + hstep, voffA);
;             PG8_WAIT_V(8); PG8_WAIT_L(0); PG8_BAR; PG8_MMA(0, 0, At, B0); PG8_MMA(0, 1, At, B1); PG8_BAR; PG8_SCHED;
;             PG8_LDA(At, 1, 1); PG8_STAGE(PG8_SB(1, 0), b3, voffB); PG8_STAGE(PG8_SB(1, 1), b3 + hstep, voffB); PG8_STAGE(PG8_SA(1, 0), a3, voffA);
;             PG8_WAIT_V(8); PG8_WAIT_L(0); PG8_BAR; PG8_MMA(1, 0, At, B0); PG8_MMA(1, 1, At, B1); PG8_BAR; PG8_SCHED;
;     ...
;         if constexpr (ALIGN_EPI) { if (wr == 0) PG8_BAR; }
	s_add_i32 s86, 0, 0x18000
	s_add_i32 s87, 0, 0x1c000
	v_add_u32_e32 v140, s86, v189
	v_add_u32_e32 v156, s87, v189
	ds_read_b128 v[128:131], v140
	ds_read_b128 v[132:135], v140 offset:1024
	ds_read_b128 v[136:139], v140 offset:2048
	ds_read_b128 v[140:143], v140 offset:3072
	ds_read_b128 v[144:147], v156
	ds_read_b128 v[148:151], v156 offset:1024
	ds_read_b128 v[152:155], v156 offset:2048
	ds_read_b128 v[156:159], v156 offset:3072
	s_add_u32 s60, s60, 0x80000
	s_addc_u32 s61, s61, 0
	s_mov_b32 m0, s68
	s_nop 0
	ds_read_b128 v[176:179], v207 offset:32768
	ds_read_b128 v[184:187], v207 offset:33792
	ds_read_b128 v[190:193], v207 offset:34816
	ds_read_b128 v[210:213], v207 offset:35840
	ds_read_b128 v[214:217], v207 offset:36864
	ds_read_b128 v[218:221], v207 offset:37888
	ds_read_b128 v[222:225], v207 offset:38912
	ds_read_b128 v[226:229], v207 offset:39936
	global_load_lds_dwordx4 v160, s[60:61]
	s_nop 0
	s_mov_b32 m0, s69
	s_nop 0
	global_load_lds_dwordx4 v164, s[60:61]
	s_waitcnt vmcnt(8)
	s_waitcnt lgkmcnt(0)
	s_barrier
	s_setprio 1
	s_waitcnt lgkmcnt(0)
	v_mfma_f32_16x16x32_bf16 v[124:127], v[128:131], v[176:179], v[124:127]
	v_mfma_f32_16x16x32_bf16 v[120:123], v[136:139], v[176:179], v[120:123]
	v_mfma_f32_16x16x32_bf16 v[108:111], v[128:131], v[190:193], v[108:111]
	v_mfma_f32_16x16x32_bf16 v[104:107], v[136:139], v[190:193], v[104:107]
	v_mfma_f32_16x16x32_bf16 v[92:95], v[128:131], v[214:217], v[92:95]
	v_mfma_f32_16x16x32_bf16 v[88:91], v[136:139], v[214:217], v[88:91]
	v_mfma_f32_16x16x32_bf16 v[76:79], v[128:131], v[222:225], v[76:79]
	v_mfma_f32_16x16x32_bf16 v[72:75], v[136:139], v[222:225], v[72:75]
	v_mfma_f32_16x16x32_bf16 v[124:127], v[132:135], v[184:187], v[124:127]
	v_mfma_f32_16x16x32_bf16 v[120:123], v[140:143], v[184:187], v[120:123]
	v_mfma_f32_16x16x32_bf16 v[108:111], v[132:135], v[210:213], v[108:111]
	v_mfma_f32_16x16x32_bf16 v[104:107], v[140:143], v[210:213], v[104:107]
	v_mfma_f32_16x16x32_bf16 v[92:95], v[132:135], v[218:221], v[92:95]
	v_mfma_f32_16x16x32_bf16 v[88:91], v[140:143], v[218:221], v[88:91]
	v_mfma_f32_16x16x32_bf16 v[76:79], v[132:135], v[226:229], v[76:79]
	v_mfma_f32_16x16x32_bf16 v[72:75], v[140:143], v[226:229], v[72:75]
	s_setprio 0
	s_setprio 1
	v_mfma_f32_16x16x32_bf16 v[116:119], v[144:147], v[176:179], v[116:119]
	v_mfma_f32_16x16x32_bf16 v[112:115], v[152:155], v[176:179], v[112:115]
	v_mfma_f32_16x16x32_bf16 v[100:103], v[144:147], v[190:193], v[100:103]
	v_mfma_f32_16x16x32_bf16 v[96:99], v[152:155], v[190:193], v[96:99]
	v_mfma_f32_16x16x32_bf16 v[84:87], v[144:147], v[214:217], v[84:87]
	v_mfma_f32_16x16x32_bf16 v[80:83], v[152:155], v[214:217], v[80:83]
	v_mfma_f32_16x16x32_bf16 v[68:71], v[144:147], v[222:225], v[68:71]
	v_mfma_f32_16x16x32_bf16 v[64:67], v[152:155], v[222:225], v[64:67]
	v_mfma_f32_16x16x32_bf16 v[116:119], v[148:151], v[184:187], v[116:119]
	v_mfma_f32_16x16x32_bf16 v[112:115], v[156:159], v[184:187], v[112:115]
	v_mfma_f32_16x16x32_bf16 v[100:103], v[148:151], v[210:213], v[100:103]
	v_mfma_f32_16x16x32_bf16 v[96:99], v[156:159], v[210:213], v[96:99]
	v_mfma_f32_16x16x32_bf16 v[84:87], v[148:151], v[218:221], v[84:87]
	v_mfma_f32_16x16x32_bf16 v[80:83], v[156:159], v[218:221], v[80:83]
	v_mfma_f32_16x16x32_bf16 v[68:71], v[148:151], v[226:229], v[68:71]
	v_mfma_f32_16x16x32_bf16 v[64:67], v[156:159], v[226:229], v[64:67]
	s_setprio 0
	s_barrier
	s_add_i32 s60, s86, s64
	s_nop 0
	s_mov_b32 m0, s60
	ds_read_b128 v[176:179], v207 offset:49152
	ds_read_b128 v[184:187], v207 offset:50176
	ds_read_b128 v[190:193], v207 offset:51200
	ds_read_b128 v[210:213], v207 offset:52224
	ds_read_b128 v[214:217], v207 offset:53248
	ds_read_b128 v[218:221], v207 offset:54272
	ds_read_b128 v[222:225], v207 offset:55296
	ds_read_b128 v[226:229], v207 offset:56320
	global_load_lds_dwordx4 v250, s[96:97]
	s_add_i32 m0, s60, 0x2000
	s_add_u32 s12, s12, 0x80080
	s_nop 0
	s_addc_u32 s13, s13, 0
	s_add_i32 s60, s87, s64
	global_load_lds_dwordx4 v251, s[96:97]
	s_nop 0
	s_mov_b32 m0, s60
	s_nop 0
	global_load_lds_dwordx4 v162, s[12:13]
	s_nop 0
	s_add_i32 m0, s60, 0x2000
	s_nop 0
	global_load_lds_dwordx4 v166, s[12:13]
	s_nop 0
	s_mov_b32 m0, s71
	s_nop 0
	global_load_lds_dwordx4 v252, s[98:99]
	s_nop 0
	s_mov_b32 m0, s72
	s_nop 0
	global_load_lds_dwordx4 v253, s[98:99]
	s_waitcnt vmcnt(8)
	s_waitcnt lgkmcnt(0)
	s_barrier
	s_setprio 1
	s_waitcnt lgkmcnt(0)
	v_mfma_f32_16x16x32_bf16 v[60:63], v[128:131], v[176:179], v[60:63]
	v_mfma_f32_16x16x32_bf16 v[56:59], v[136:139], v[176:179], v[56:59]
	v_mfma_f32_16x16x32_bf16 v[44:47], v[128:131], v[190:193], v[44:47]
	v_mfma_f32_16x16x32_bf16 v[40:43], v[136:139], v[190:193], v[40:43]
	v_mfma_f32_16x16x32_bf16 v[28:31], v[128:131], v[214:217], v[28:31]
	v_mfma_f32_16x16x32_bf16 v[24:27], v[136:139], v[214:217], v[24:27]
	v_mfma_f32_16x16x32_bf16 v[12:15], v[128:131], v[222:225], v[12:15]
	v_mfma_f32_16x16x32_bf16 v[8:11], v[136:139], v[222:225], v[8:11]
	v_mfma_f32_16x16x32_bf16 v[60:63], v[132:135], v[184:187], v[60:63]
	v_mfma_f32_16x16x32_bf16 v[56:59], v[140:143], v[184:187], v[56:59]
	v_mfma_f32_16x16x32_bf16 v[44:47], v[132:135], v[210:213], v[44:47]
	v_mfma_f32_16x16x32_bf16 v[40:43], v[140:143], v[210:213], v[40:43]
	v_mfma_f32_16x16x32_bf16 v[28:31], v[132:135], v[218:221], v[28:31]
	v_mfma_f32_16x16x32_bf16 v[24:27], v[140:143], v[218:221], v[24:27]
	v_mfma_f32_16x16x32_bf16 v[12:15], v[132:135], v[226:229], v[12:15]
	v_mfma_f32_16x16x32_bf16 v[8:11], v[140:143], v[226:229], v[8:11]
	s_setprio 0
	s_setprio 1
	v_mfma_f32_16x16x32_bf16 v[52:55], v[144:147], v[176:179], v[52:55]
	v_mfma_f32_16x16x32_bf16 v[48:51], v[152:155], v[176:179], v[48:51]
	v_mfma_f32_16x16x32_bf16 v[36:39], v[144:147], v[190:193], v[36:39]
	v_mfma_f32_16x16x32_bf16 v[32:35], v[152:155], v[190:193], v[32:35]
	v_mfma_f32_16x16x32_bf16 v[20:23], v[144:147], v[214:217], v[20:23]
	v_mfma_f32_16x16x32_bf16 v[16:19], v[152:155], v[214:217], v[16:19]
	v_mfma_f32_16x16x32_bf16 v[4:7], v[144:147], v[222:225], v[4:7]
	v_mfma_f32_16x16x32_bf16 v[0:3], v[152:155], v[222:225], v[0:3]
	v_mfma_f32_16x16x32_bf16 v[52:55], v[148:151], v[184:187], v[52:55]
	v_mfma_f32_16x16x32_bf16 v[48:51], v[156:159], v[184:187], v[48:51]
	v_mfma_f32_16x16x32_bf16 v[36:39], v[148:151], v[210:213], v[36:39]
	v_mfma_f32_16x16x32_bf16 v[32:35], v[156:159], v[210:213], v[32:35]
	v_mfma_f32_16x16x32_bf16 v[20:23], v[148:151], v[218:221], v[20:23]
	v_mfma_f32_16x16x32_bf16 v[16:19], v[156:159], v[218:221], v[16:19]
	v_mfma_f32_16x16x32_bf16 v[4:7], v[148:151], v[226:229], v[4:7]
	v_mfma_f32_16x16x32_bf16 v[0:3], v[156:159], v[226:229], v[0:3]
	s_setprio 0
	s_barrier
	s_add_i32 s85, s85, 2
	s_add_u32 s10, s10, 0x100
	s_addc_u32 s11, s11, 0
	s_add_u32 s83, s83, 0x100
	s_addc_u32 s84, s84, 0
	s_cmp_gt_u32 s85, 29
	s_cbranch_scc0 .LBB0_428
	s_and_b64 vcc, exec, s[42:43]
	s_cbranch_vccz .LBB0_431
	s_barrier

; #define PG8_STAGE(bufoff, gbase, voff) do { _Pragma("unroll") for (int _i = 0; _i < 2; ++_i) \
;         __builtin_amdgcn_global_load_lds((const unsigned*)((const char*)(gbase) + (voff)[_i]), (PG8_LAS unsigned*)(lds + (bufoff) + ldsw + _i * 8192), 16, 0, 0); } while (0)
; #define PG8_LDA(dst, b, h) do { _Pragma("unroll") for (int m = 0; m < 4; ++m) _Pragma("unroll") for (int k = 0; k < 2; ++k) dst[m][k] = *(const PG8_LAS bf16x8*)(lds + PG8_SA(b, h) + aoff + m * 2048 + k * 1024); } while (0)
; #define PG8_LDB(dst, b, h) do { _Pragma("unroll") for (int n = 0; n < 2; ++n) _Pragma("unroll") for (int k = 0; k < 2; ++k) dst[n][k] = *(const PG8_LAS bf16x8*)(lds + PG8_SB(b, h) + boff + n * 2048 + k * 1024); } while (0)
; #define PG8_SCHED __builtin_amdgcn_sched_barrier(0)
; template <class Epi, class Sched, bool ALIGN_EPI = false, bool SP2 = false>
; __device__ __forceinline__ void gemm_phase(PG8_LAS unsigned char* lds, const Gemm g, const Sched& S, const Epi& E) {
;     ...
; #pragma unroll
;     for (int a = 0; a < 2; ++a)
; #pragma unroll
;         for (int b = 0; b < 2; ++b)
; #pragma unroll
;             for (int m = 0; m < 4; ++m)
; #pragma unroll
;                 for (int n = 0; n < 2; ++n) acc[a][b][m][n] = (f32x4){0.f, 0.f, 0.f, 0.f};
;     ...
;         const bool has_next = S.next(ui + 1, nxt);
;         const char* nA = has_next ? (const char*)g.A + (size_t)nxt.pm * tstep : cA; const char* nB = has_next ? (const char*)g.Bt + (size_t)nxt.pn * tstep : cB;
;         for (int t = 0; t < nt; t += 2) {
;             const bool last = (t == nt - 2);
;             const char* a1 = cA + (size_t)(t + 1) * kstep;
;             const char* a2 = last ? nA : cA + (size_t)(t + 2) * kstep; const char* b2 = last ? nB : cB + (size_t)(t + 2) * kstep;
;             const char* a3 = a2 + kstep; const char* b3 = b2 + kstep;
;             if (last && has_next) S.a_ready(nxt);
;             if constexpr (SP2) {
;             PG8_LDB(B0, 0, 0); PG8_LDB(B1, 0, 1); PG8_SCHED; PG8_LDA(At, 0, 0); PG8_STAGE(PG8_SA(1, 1), a1 + hstep, voffA);
.LBB0_508:
	s_ashr_i32 s51, s50, 31
	s_lshl_b64 s[52:53], s[50:51], 22
	s_add_u32 s52, s22, s52
	s_addc_u32 s53, s23, s53
	s_and_b64 s[54:55], s[6:7], exec
	s_cselect_b32 s11, s53, s59
	s_cselect_b32 s51, s52, s58
	s_ashr_i32 s49, s48, 31
	s_lshl_b64 s[54:55], s[48:49], 22
	s_add_u32 s54, s45, s54
	s_addc_u32 s55, s47, s55
	s_and_b64 s[62:63], s[6:7], exec
	s_cselect_b32 s49, s55, s61
	s_cselect_b32 s78, s54, s60
	s_add_u32 s58, s58, 0x200080
	s_addc_u32 s59, s59, 0
	s_add_u32 s79, s60, 0x100
	v_mov_b32_e32 v0, 0
	s_addc_u32 s80, s61, 0
	s_mov_b32 s81, -2
	v_mov_b32_e32 v1, v0
	s_waitcnt lgkmcnt(0)
	v_mov_b32_e32 v2, v0
	v_mov_b32_e32 v3, v0
	v_mov_b32_e32 v4, v0
	v_mov_b32_e32 v5, v0
	v_mov_b32_e32 v6, v0
	v_mov_b32_e32 v7, v0
	v_mov_b32_e32 v16, v0
	v_mov_b32_e32 v17, v0
	v_mov_b32_e32 v18, v0
	v_mov_b32_e32 v19, v0
	v_mov_b32_e32 v20, v0
	v_mov_b32_e32 v21, v0
	v_mov_b32_e32 v22, v0
	v_mov_b32_e32 v23, v0
	v_mov_b32_e32 v32, v0
	v_mov_b32_e32 v33, v0
	v_mov_b32_e32 v34, v0
	v_mov_b32_e32 v35, v0
	v_mov_b32_e32 v36, v0
	v_mov_b32_e32 v37, v0
	v_mov_b32_e32 v38, v0
	v_mov_b32_e32 v39, v0
	v_mov_b32_e32 v48, v0
	v_mov_b32_e32 v49, v0
	v_mov_b32_e32 v50, v0
	v_mov_b32_e32 v51, v0
	v_mov_b32_e32 v52, v0
	v_mov_b32_e32 v53, v0
	v_mov_b32_e32 v54, v0
	v_mov_b32_e32 v55, v0
	v_mov_b32_e32 v8, v0
	v_mov_b32_e32 v9, v0
	v_mov_b32_e32 v10, v0
	v_mov_b32_e32 v11, v0
	v_mov_b32_e32 v12, v0
	v_mov_b32_e32 v13, v0
	v_mov_b32_e32 v14, v0
	v_mov_b32_e32 v15, v0
	v_mov_b32_e32 v24, v0
	v_mov_b32_e32 v25, v0
	v_mov_b32_e32 v26, v0
	v_mov_b32_e32 v27, v0
	v_mov_b32_e32 v28, v0
	v_mov_b32_e32 v29, v0
	v_mov_b32_e32 v30, v0
	v_mov_b32_e32 v31, v0
	v_mov_b32_e32 v40, v0
	v_mov_b32_e32 v41, v0
	v_mov_b32_e32 v42, v0
	v_mov_b32_e32 v43, v0
	v_mov_b32_e32 v44, v0
	v_mov_b32_e32 v45, v0
	v_mov_b32_e32 v46, v0
	v_mov_b32_e32 v47, v0
	v_mov_b32_e32 v56, v0
	v_mov_b32_e32 v57, v0
	v_mov_b32_e32 v58, v0
	v_mov_b32_e32 v59, v0
	v_mov_b32_e32 v60, v0
	v_mov_b32_e32 v61, v0
	v_mov_b32_e32 v62, v0
	v_mov_b32_e32 v63, v0
	v_mov_b32_e32 v80, v0
	v_mov_b32_e32 v81, v0
	v_mov_b32_e32 v82, v0
	v_mov_b32_e32 v83, v0
	v_mov_b32_e32 v84, v0
	v_mov_b32_e32 v85, v0
	v_mov_b32_e32 v86, v0
	v_mov_b32_e32 v87, v0
	v_mov_b32_e32 v96, v0
	v_mov_b32_e32 v97, v0
	v_mov_b32_e32 v98, v0
	v_mov_b32_e32 v99, v0
	v_mov_b32_e32 v100, v0
	v_mov_b32_e32 v101, v0
	v_mov_b32_e32 v102, v0
	v_mov_b32_e32 v103, v0
	v_mov_b32_e32 v112, v0
	v_mov_b32_e32 v113, v0
	v_mov_b32_e32 v114, v0
	v_mov_b32_e32 v115, v0
	v_mov_b32_e32 v116, v0
	v_mov_b32_e32 v117, v0
	v_mov_b32_e32 v118, v0
	v_mov_b32_e32 v119, v0
	v_mov_b32_e32 v128, v0
	v_mov_b32_e32 v129, v0
	v_mov_b32_e32 v130, v0
	v_mov_b32_e32 v131, v0
	v_mov_b32_e32 v132, v0
	v_mov_b32_e32 v133, v0
	v_mov_b32_e32 v134, v0
	v_mov_b32_e32 v135, v0
	v_mov_b32_e32 v88, v0
	v_mov_b32_e32 v89, v0
	v_mov_b32_e32 v90, v0
	v_mov_b32_e32 v91, v0
	v_mov_b32_e32 v92, v0
	v_mov_b32_e32 v93, v0
	v_mov_b32_e32 v94, v0
	v_mov_b32_e32 v95, v0
	v_mov_b32_e32 v104, v0
	v_mov_b32_e32 v105, v0
	v_mov_b32_e32 v106, v0
	v_mov_b32_e32 v107, v0
	v_mov_b32_e32 v108, v0
	v_mov_b32_e32 v109, v0
	v_mov_b32_e32 v110, v0
	v_mov_b32_e32 v111, v0
	v_mov_b32_e32 v120, v0
	v_mov_b32_e32 v121, v0
	v_mov_b32_e32 v122, v0
	v_mov_b32_e32 v123, v0
	v_mov_b32_e32 v124, v0
	v_mov_b32_e32 v125, v0
	v_mov_b32_e32 v126, v0
	v_mov_b32_e32 v127, v0
	v_mov_b32_e32 v136, v0
	v_mov_b32_e32 v137, v0
	v_mov_b32_e32 v138, v0
	v_mov_b32_e32 v139, v0
	v_mov_b32_e32 v140, v0
	v_mov_b32_e32 v141, v0
	v_mov_b32_e32 v142, v0
	v_mov_b32_e32 v143, v0
	v_add_u32_e32 v253, 0x80, v164
	v_add_u32_e32 v252, 0x80, v160
	v_add_u32_e32 v251, 0x80, v166
	v_add_u32_e32 v250, 0x80, v162
.LBB0_509:
	ds_read_b128 v[64:67], v213
	ds_read_b128 v[68:71], v213 offset:1024
	ds_read_b128 v[72:75], v213 offset:2048
	ds_read_b128 v[76:79], v213 offset:3072
	ds_read_b128 v[144:147], v214
	ds_read_b128 v[148:151], v214 offset:1024
	ds_read_b128 v[152:155], v214 offset:2048
	ds_read_b128 v[156:159], v214 offset:3072
	s_add_u32 s60, s58, 0xffe00080
	s_addc_u32 s61, s59, -1
	s_cmpk_eq_i32 s81, 0x7c
	s_cselect_b32 s63, s11, s61
	s_cselect_b32 s62, s51, s60
	s_cselect_b32 s61, s49, s80
	s_cselect_b32 s60, s78, s79
	s_nop 0
	s_add_i32 m0, s57, 0xc000
	ds_read_b128 v[176:179], v215
	ds_read_b128 v[180:183], v215 offset:1024
	ds_read_b128 v[184:187], v215 offset:2048
	ds_read_b128 v[188:191], v215 offset:3072
	ds_read_b128 v[192:195], v215 offset:4096
	ds_read_b128 v[196:199], v215 offset:5120
	ds_read_b128 v[200:203], v215 offset:6144
	ds_read_b128 v[204:207], v215 offset:7168
	global_load_lds_dwordx4 v168, s[58:59]
	s_nop 0
	s_add_i32 m0, s57, 0xe000
	s_nop 0
	global_load_lds_dwordx4 v170, s[58:59]
	s_waitcnt vmcnt(8)
	s_waitcnt lgkmcnt(0)
	s_barrier
; #define PG8_STAGE(bufoff, gbase, voff) do { _Pragma("unroll") for (int _i = 0; _i < 2; ++_i) \
;         __builtin_amdgcn_global_load_lds((const unsigned*)((const char*)(gbase) + (voff)[_i]), (PG8_LAS unsigned*)(lds + (bufoff) + ldsw + _i * 8192), 16, 0, 0); } while (0)
; #define PG8_LDA(dst, b, h) do { _Pragma("unroll") for (int m = 0; m < 4; ++m) _Pragma("unroll") for (int k = 0; k < 2; ++k) dst[m][k] = *(const PG8_LAS bf16x8*)(lds + PG8_SA(b, h) + aoff + m * 2048 + k * 1024); } while (0)
; #define PG8_MMA(ai, bj, At, Bt) do { __builtin_amdgcn_s_setprio(1); _Pragma("unroll") for (int m = 0; m < 4; ++m) _Pragma("unroll") for (int n = 0; n < 2; ++n) _Pragma("unroll") for (int k = 0; k < 2; ++k) \
;         acc[ai][bj][m][n] = __builtin_amdgcn_mfma_f32_16x16x32_bf16(Bt[n][k], At[m][k], acc[ai][bj][m][n], 0, 0, 0); __builtin_amdgcn_s_setprio(0); } while (0)
; #define PG8_WAIT_V(n) asm volatile("s_waitcnt vmcnt(" #n ")" ::: "memory")
; #define PG8_WAIT_L(n) asm volatile("s_waitcnt lgkmcnt(" #n ")" ::: "memory")
; #define PG8_BAR __builtin_amdgcn_s_barrier()
; #define PG8_SCHED __builtin_amdgcn_sched_barrier(0)
; template <class Epi, class Sched, bool ALIGN_EPI = false, bool SP2 = false>
; __device__ __forceinline__ void gemm_phase(PG8_LAS unsigned char* lds, const Gemm g, const Sched& S, const Epi& E) {
;     ...
;             PG8_WAIT_V(8); PG8_WAIT_L(0); PG8_BAR; PG8_MMA(0, 0, At, B0); PG8_MMA(0, 1, At, B1); PG8_BAR; PG8_SCHED;
;             PG8_LDA(At, 0, 1); PG8_STAGE(PG8_SB(0, 0), b2, voffB); PG8_STAGE(PG8_SB(0, 1), b2 + hstep, voffB); PG8_STAGE(PG8_SA(0, 0), a2, voffA);
;             PG8_WAIT_V(8); PG8_WAIT_L(0); PG8_BAR; PG8_MMA(1, 0, At, B0); PG8_MMA(1, 1, At, B1); PG8_BAR; PG8_SCHED;
	s_setprio 1
	s_waitcnt lgkmcnt(0)
	v_mfma_f32_16x16x32_bf16 v[140:143], v[64:67], v[176:179], v[140:143]
	v_mfma_f32_16x16x32_bf16 v[136:139], v[72:75], v[176:179], v[136:139]
	v_mfma_f32_16x16x32_bf16 v[124:127], v[64:67], v[184:187], v[124:127]
	v_mfma_f32_16x16x32_bf16 v[120:123], v[72:75], v[184:187], v[120:123]
	v_mfma_f32_16x16x32_bf16 v[108:111], v[64:67], v[192:195], v[108:111]
	v_mfma_f32_16x16x32_bf16 v[104:107], v[72:75], v[192:195], v[104:107]
	v_mfma_f32_16x16x32_bf16 v[92:95], v[64:67], v[200:203], v[92:95]
	v_mfma_f32_16x16x32_bf16 v[88:91], v[72:75], v[200:203], v[88:91]
	v_mfma_f32_16x16x32_bf16 v[140:143], v[68:71], v[180:183], v[140:143]
	v_mfma_f32_16x16x32_bf16 v[136:139], v[76:79], v[180:183], v[136:139]
	v_mfma_f32_16x16x32_bf16 v[124:127], v[68:71], v[188:191], v[124:127]
	v_mfma_f32_16x16x32_bf16 v[120:123], v[76:79], v[188:191], v[120:123]
	v_mfma_f32_16x16x32_bf16 v[108:111], v[68:71], v[196:199], v[108:111]
	v_mfma_f32_16x16x32_bf16 v[104:107], v[76:79], v[196:199], v[104:107]
	v_mfma_f32_16x16x32_bf16 v[92:95], v[68:71], v[204:207], v[92:95]
	v_mfma_f32_16x16x32_bf16 v[88:91], v[76:79], v[204:207], v[88:91]
	s_setprio 0
	s_setprio 1
	v_mfma_f32_16x16x32_bf16 v[132:135], v[144:147], v[176:179], v[132:135]
	v_mfma_f32_16x16x32_bf16 v[128:131], v[152:155], v[176:179], v[128:131]
	v_mfma_f32_16x16x32_bf16 v[116:119], v[144:147], v[184:187], v[116:119]
	v_mfma_f32_16x16x32_bf16 v[112:115], v[152:155], v[184:187], v[112:115]
	v_mfma_f32_16x16x32_bf16 v[100:103], v[144:147], v[192:195], v[100:103]
	v_mfma_f32_16x16x32_bf16 v[96:99], v[152:155], v[192:195], v[96:99]
	v_mfma_f32_16x16x32_bf16 v[84:87], v[144:147], v[200:203], v[84:87]
	v_mfma_f32_16x16x32_bf16 v[80:83], v[152:155], v[200:203], v[80:83]
	v_mfma_f32_16x16x32_bf16 v[132:135], v[148:151], v[180:183], v[132:135]
	v_mfma_f32_16x16x32_bf16 v[128:131], v[156:159], v[180:183], v[128:131]
	v_mfma_f32_16x16x32_bf16 v[116:119], v[148:151], v[188:191], v[116:119]
	v_mfma_f32_16x16x32_bf16 v[112:115], v[156:159], v[188:191], v[112:115]
	v_mfma_f32_16x16x32_bf16 v[100:103], v[148:151], v[196:199], v[100:103]
	v_mfma_f32_16x16x32_bf16 v[96:99], v[156:159], v[196:199], v[96:99]
	v_mfma_f32_16x16x32_bf16 v[84:87], v[148:151], v[204:207], v[84:87]
	v_mfma_f32_16x16x32_bf16 v[80:83], v[156:159], v[204:207], v[80:83]
	s_setprio 0
	s_barrier
	s_add_i32 s82, s75, s64
	s_mov_b64 s[96:97], s[60:61]
	s_nop 0
	s_mov_b32 m0, s82
	ds_read_b128 v[176:179], v215 offset:16384
	ds_read_b128 v[180:183], v215 offset:17408
	ds_read_b128 v[184:187], v215 offset:18432
	ds_read_b128 v[188:191], v215 offset:19456
	ds_read_b128 v[192:195], v215 offset:20480
	ds_read_b128 v[196:199], v215 offset:21504
	ds_read_b128 v[200:203], v215 offset:22528
	ds_read_b128 v[204:207], v215 offset:23552
	global_load_lds_dwordx4 v162, s[60:61]
	s_add_i32 m0, s82, 0x2000
	s_add_u32 s82, s60, 0x200000
	s_nop 0
	s_addc_u32 s83, s61, 0
	s_add_i32 s84, s76, s64
	global_load_lds_dwordx4 v166, s[60:61]
	s_nop 0
	s_mov_b32 m0, s84
	s_nop 0
	global_load_lds_dwordx4 v162, s[82:83]
	s_nop 0
	s_add_i32 m0, s84, 0x2000
	s_nop 0
	global_load_lds_dwordx4 v166, s[82:83]
	s_mov_b64 s[98:99], s[62:63]
	s_nop 0
	s_mov_b32 m0, s57
	s_nop 0
	global_load_lds_dwordx4 v160, s[62:63]
	s_mov_b32 m0, s65
	s_nop 0
	global_load_lds_dwordx4 v164, s[62:63]
	s_waitcnt vmcnt(8)
	s_waitcnt lgkmcnt(0)
	s_barrier
	s_setprio 1
	s_waitcnt lgkmcnt(0)
	v_mfma_f32_16x16x32_bf16 v[60:63], v[64:67], v[176:179], v[60:63]
	v_mfma_f32_16x16x32_bf16 v[56:59], v[72:75], v[176:179], v[56:59]
	v_mfma_f32_16x16x32_bf16 v[44:47], v[64:67], v[184:187], v[44:47]
	v_mfma_f32_16x16x32_bf16 v[40:43], v[72:75], v[184:187], v[40:43]
	v_mfma_f32_16x16x32_bf16 v[28:31], v[64:67], v[192:195], v[28:31]
	v_mfma_f32_16x16x32_bf16 v[24:27], v[72:75], v[192:195], v[24:27]
	v_mfma_f32_16x16x32_bf16 v[12:15], v[64:67], v[200:203], v[12:15]
	v_mfma_f32_16x16x32_bf16 v[8:11], v[72:75], v[200:203], v[8:11]
	v_mfma_f32_16x16x32_bf16 v[60:63], v[68:71], v[180:183], v[60:63]
	v_mfma_f32_16x16x32_bf16 v[56:59], v[76:79], v[180:183], v[56:59]
	v_mfma_f32_16x16x32_bf16 v[44:47], v[68:71], v[188:191], v[44:47]
	v_mfma_f32_16x16x32_bf16 v[40:43], v[76:79], v[188:191], v[40:43]
	v_mfma_f32_16x16x32_bf16 v[28:31], v[68:71], v[196:199], v[28:31]
	v_mfma_f32_16x16x32_bf16 v[24:27], v[76:79], v[196:199], v[24:27]
	v_mfma_f32_16x16x32_bf16 v[12:15], v[68:71], v[204:207], v[12:15]
	v_mfma_f32_16x16x32_bf16 v[8:11], v[76:79], v[204:207], v[8:11]
	s_setprio 0
	s_setprio 1
	v_mfma_f32_16x16x32_bf16 v[52:55], v[144:147], v[176:179], v[52:55]
	v_mfma_f32_16x16x32_bf16 v[48:51], v[152:155], v[176:179], v[48:51]
	v_mfma_f32_16x16x32_bf16 v[36:39], v[144:147], v[184:187], v[36:39]
	v_mfma_f32_16x16x32_bf16 v[32:35], v[152:155], v[184:187], v[32:35]
	v_mfma_f32_16x16x32_bf16 v[20:23], v[144:147], v[192:195], v[20:23]
	v_mfma_f32_16x16x32_bf16 v[16:19], v[152:155], v[192:195], v[16:19]
	v_mfma_f32_16x16x32_bf16 v[4:7], v[144:147], v[200:203], v[4:7]
	v_mfma_f32_16x16x32_bf16 v[0:3], v[152:155], v[200:203], v[0:3]
	v_mfma_f32_16x16x32_bf16 v[52:55], v[148:151], v[180:183], v[52:55]
	v_mfma_f32_16x16x32_bf16 v[48:51], v[156:159], v[180:183], v[48:51]
	v_mfma_f32_16x16x32_bf16 v[36:39], v[148:151], v[188:191], v[36:39]
	v_mfma_f32_16x16x32_bf16 v[32:35], v[156:159], v[188:191], v[32:35]
	v_mfma_f32_16x16x32_bf16 v[20:23], v[148:151], v[196:199], v[20:23]
	v_mfma_f32_16x16x32_bf16 v[16:19], v[156:159], v[196:199], v[16:19]
	v_mfma_f32_16x16x32_bf16 v[4:7], v[148:151], v[204:207], v[4:7]
	v_mfma_f32_16x16x32_bf16 v[0:3], v[156:159], v[204:207], v[0:3]
	s_setprio 0
	s_barrier
; #define PG8_STAGE(bufoff, gbase, voff) do { _Pragma("unroll") for (int _i = 0; _i < 2; ++_i) \
;         __builtin_amdgcn_global_load_lds((const unsigned*)((const char*)(gbase) + (voff)[_i]), (PG8_LAS unsigned*)(lds + (bufoff) + ldsw + _i * 8192), 16, 0, 0); } while (0)
; #define PG8_LDA(dst, b, h) do { _Pragma("unroll") for (int m = 0; m < 4; ++m) _Pragma("unroll") for (int k = 0; k < 2; ++k) dst[m][k] = *(const PG8_LAS bf16x8*)(lds + PG8_SA(b, h) + aoff + m * 2048 + k * 1024); } while (0)
; #define PG8_LDB(dst, b, h) do { _Pragma("unroll") for (int n = 0; n < 2; ++n) _Pragma("unroll") for (int k = 0; k < 2; ++k) dst[n][k] = *(const PG8_LAS bf16x8*)(lds + PG8_SB(b, h) + boff + n * 2048 + k * 1024); } while (0)
; #define PG8_MMA(ai, bj, At, Bt) do { __builtin_amdgcn_s_setprio(1); _Pragma("unroll") for (int m = 0; m < 4; ++m) _Pragma("unroll") for (int n = 0; n < 2; ++n) _Pragma("unroll") for (int k = 0; k < 2; ++k) \
;         acc[ai][bj][m][n] = __builtin_amdgcn_mfma_f32_16x16x32_bf16(Bt[n][k], At[m][k], acc[ai][bj][m][n], 0, 0, 0); __builtin_amdgcn_s_setprio(0); } while (0)
; #define PG8_WAIT_V(n) asm volatile("s_waitcnt vmcnt(" #n ")" ::: "memory")
; #define PG8_WAIT_L(n) asm volatile("s_waitcnt lgkmcnt(" #n ")" ::: "memory")
; #define PG8_BAR __builtin_amdgcn_s_barrier()
; #define PG8_SCHED __builtin_amdgcn_sched_barrier(0)
; template <class Epi, class Sched, bool ALIGN_EPI = false, bool SP2 = false>
; __device__ __forceinline__ void gemm_phase(PG8_LAS unsigned char* lds, const Gemm g, const Sched& S, const Epi& E) {
;     ...
;             PG8_LDB(B0, 1, 0); PG8_LDB(B1, 1, 1); PG8_SCHED; PG8_LDA(At, 1, 0); PG8_STAGE(PG8_SA(0, 1), a2 + hstep, voffA);
;             PG8_WAIT_V(8); PG8_WAIT_L(0); PG8_BAR; PG8_MMA(0, 0, At, B0); PG8_MMA(0, 1, At, B1); PG8_BAR; PG8_SCHED;
;             PG8_LDA(At, 1, 1); PG8_STAGE(PG8_SB(1, 0), b3, voffB); PG8_STAGE(PG8_SB(1, 1), b3 + hstep, voffB); PG8_STAGE(PG8_SA(1, 0), a3, voffA);
;             PG8_WAIT_V(8); PG8_WAIT_L(0); PG8_BAR; PG8_MMA(1, 0, At, B0); PG8_MMA(1, 1, At, B1); PG8_BAR; PG8_SCHED;
	s_add_i32 s82, 0, 0x18000
	s_add_i32 s83, 0, 0x1c000
	v_add_u32_e32 v76, s82, v211
	v_add_u32_e32 v156, s83, v211
	ds_read_b128 v[64:67], v76
	ds_read_b128 v[68:71], v76 offset:1024
	ds_read_b128 v[72:75], v76 offset:2048
	ds_read_b128 v[76:79], v76 offset:3072
	ds_read_b128 v[144:147], v156
	ds_read_b128 v[148:151], v156 offset:1024
	ds_read_b128 v[152:155], v156 offset:2048
	ds_read_b128 v[156:159], v156 offset:3072
	s_add_u32 s62, s62, 0x200000
	s_addc_u32 s63, s63, 0
	s_mov_b32 m0, s67
	s_nop 0
	ds_read_b128 v[176:179], v215 offset:32768
	ds_read_b128 v[180:183], v215 offset:33792
	ds_read_b128 v[184:187], v215 offset:34816
	ds_read_b128 v[188:191], v215 offset:35840
	ds_read_b128 v[192:195], v215 offset:36864
	ds_read_b128 v[196:199], v215 offset:37888
	ds_read_b128 v[200:203], v215 offset:38912
	ds_read_b128 v[204:207], v215 offset:39936
	global_load_lds_dwordx4 v160, s[62:63]
	s_nop 0
	s_mov_b32 m0, s68
	s_nop 0
	global_load_lds_dwordx4 v164, s[62:63]
	s_waitcnt vmcnt(8)
	s_waitcnt lgkmcnt(0)
	s_barrier
	s_setprio 1
	s_waitcnt lgkmcnt(0)
	v_mfma_f32_16x16x32_bf16 v[140:143], v[64:67], v[176:179], v[140:143]
	v_mfma_f32_16x16x32_bf16 v[136:139], v[72:75], v[176:179], v[136:139]
	v_mfma_f32_16x16x32_bf16 v[124:127], v[64:67], v[184:187], v[124:127]
	v_mfma_f32_16x16x32_bf16 v[120:123], v[72:75], v[184:187], v[120:123]
	v_mfma_f32_16x16x32_bf16 v[108:111], v[64:67], v[192:195], v[108:111]
	v_mfma_f32_16x16x32_bf16 v[104:107], v[72:75], v[192:195], v[104:107]
	v_mfma_f32_16x16x32_bf16 v[92:95], v[64:67], v[200:203], v[92:95]
	v_mfma_f32_16x16x32_bf16 v[88:91], v[72:75], v[200:203], v[88:91]
	v_mfma_f32_16x16x32_bf16 v[140:143], v[68:71], v[180:183], v[140:143]
	v_mfma_f32_16x16x32_bf16 v[136:139], v[76:79], v[180:183], v[136:139]
	v_mfma_f32_16x16x32_bf16 v[124:127], v[68:71], v[188:191], v[124:127]
	v_mfma_f32_16x16x32_bf16 v[120:123], v[76:79], v[188:191], v[120:123]
	v_mfma_f32_16x16x32_bf16 v[108:111], v[68:71], v[196:199], v[108:111]
	v_mfma_f32_16x16x32_bf16 v[104:107], v[76:79], v[196:199], v[104:107]
	v_mfma_f32_16x16x32_bf16 v[92:95], v[68:71], v[204:207], v[92:95]
	v_mfma_f32_16x16x32_bf16 v[88:91], v[76:79], v[204:207], v[88:91]
	s_setprio 0
	s_setprio 1
	v_mfma_f32_16x16x32_bf16 v[132:135], v[144:147], v[176:179], v[132:135]
	v_mfma_f32_16x16x32_bf16 v[128:131], v[152:155], v[176:179], v[128:131]
	v_mfma_f32_16x16x32_bf16 v[116:119], v[144:147], v[184:187], v[116:119]
	v_mfma_f32_16x16x32_bf16 v[112:115], v[152:155], v[184:187], v[112:115]
	v_mfma_f32_16x16x32_bf16 v[100:103], v[144:147], v[192:195], v[100:103]
	v_mfma_f32_16x16x32_bf16 v[96:99], v[152:155], v[192:195], v[96:99]
	v_mfma_f32_16x16x32_bf16 v[84:87], v[144:147], v[200:203], v[84:87]
	v_mfma_f32_16x16x32_bf16 v[80:83], v[152:155], v[200:203], v[80:83]
	v_mfma_f32_16x16x32_bf16 v[132:135], v[148:151], v[180:183], v[132:135]
	v_mfma_f32_16x16x32_bf16 v[128:131], v[156:159], v[180:183], v[128:131]
	v_mfma_f32_16x16x32_bf16 v[116:119], v[148:151], v[188:191], v[116:119]
	v_mfma_f32_16x16x32_bf16 v[112:115], v[156:159], v[188:191], v[112:115]
	v_mfma_f32_16x16x32_bf16 v[100:103], v[148:151], v[196:199], v[100:103]
	v_mfma_f32_16x16x32_bf16 v[96:99], v[156:159], v[196:199], v[96:99]
	v_mfma_f32_16x16x32_bf16 v[84:87], v[148:151], v[204:207], v[84:87]
	v_mfma_f32_16x16x32_bf16 v[80:83], v[156:159], v[204:207], v[80:83]
	s_setprio 0
	s_barrier
	s_add_i32 s62, s82, s64
	s_nop 0
	s_mov_b32 m0, s62
	ds_read_b128 v[176:179], v215 offset:49152
	ds_read_b128 v[180:183], v215 offset:50176
	ds_read_b128 v[184:187], v215 offset:51200
	ds_read_b128 v[188:191], v215 offset:52224
	ds_read_b128 v[192:195], v215 offset:53248
	ds_read_b128 v[196:199], v215 offset:54272
	ds_read_b128 v[200:203], v215 offset:55296
	ds_read_b128 v[204:207], v215 offset:56320
	global_load_lds_dwordx4 v250, s[96:97]
	s_add_i32 m0, s62, 0x2000
	s_add_u32 s60, s60, 0x200080
	s_nop 0
	s_addc_u32 s61, s61, 0
	s_add_i32 s62, s83, s64
	global_load_lds_dwordx4 v251, s[96:97]
	s_nop 0
	s_mov_b32 m0, s62
	s_nop 0
	global_load_lds_dwordx4 v162, s[60:61]
	s_nop 0
	s_add_i32 m0, s62, 0x2000
	s_nop 0
	global_load_lds_dwordx4 v166, s[60:61]
	s_nop 0
	s_mov_b32 m0, s70
	s_nop 0
	global_load_lds_dwordx4 v252, s[98:99]
	s_nop 0
	s_mov_b32 m0, s71
	s_nop 0
	global_load_lds_dwordx4 v253, s[98:99]
	s_waitcnt vmcnt(8)
	s_waitcnt lgkmcnt(0)
	s_barrier
	s_setprio 1
	s_waitcnt lgkmcnt(0)
	v_mfma_f32_16x16x32_bf16 v[60:63], v[64:67], v[176:179], v[60:63]
	v_mfma_f32_16x16x32_bf16 v[56:59], v[72:75], v[176:179], v[56:59]
	v_mfma_f32_16x16x32_bf16 v[44:47], v[64:67], v[184:187], v[44:47]
	v_mfma_f32_16x16x32_bf16 v[40:43], v[72:75], v[184:187], v[40:43]
	v_mfma_f32_16x16x32_bf16 v[28:31], v[64:67], v[192:195], v[28:31]
	v_mfma_f32_16x16x32_bf16 v[24:27], v[72:75], v[192:195], v[24:27]
	v_mfma_f32_16x16x32_bf16 v[12:15], v[64:67], v[200:203], v[12:15]
	v_mfma_f32_16x16x32_bf16 v[8:11], v[72:75], v[200:203], v[8:11]
	v_mfma_f32_16x16x32_bf16 v[60:63], v[68:71], v[180:183], v[60:63]
	v_mfma_f32_16x16x32_bf16 v[56:59], v[76:79], v[180:183], v[56:59]
	v_mfma_f32_16x16x32_bf16 v[44:47], v[68:71], v[188:191], v[44:47]
	v_mfma_f32_16x16x32_bf16 v[40:43], v[76:79], v[188:191], v[40:43]
	v_mfma_f32_16x16x32_bf16 v[28:31], v[68:71], v[196:199], v[28:31]
	v_mfma_f32_16x16x32_bf16 v[24:27], v[76:79], v[196:199], v[24:27]
	v_mfma_f32_16x16x32_bf16 v[12:15], v[68:71], v[204:207], v[12:15]
	v_mfma_f32_16x16x32_bf16 v[8:11], v[76:79], v[204:207], v[8:11]
	s_setprio 0
	s_setprio 1
	v_mfma_f32_16x16x32_bf16 v[52:55], v[144:147], v[176:179], v[52:55]
	v_mfma_f32_16x16x32_bf16 v[48:51], v[152:155], v[176:179], v[48:51]
	v_mfma_f32_16x16x32_bf16 v[36:39], v[144:147], v[184:187], v[36:39]
	v_mfma_f32_16x16x32_bf16 v[32:35], v[152:155], v[184:187], v[32:35]
	v_mfma_f32_16x16x32_bf16 v[20:23], v[144:147], v[192:195], v[20:23]
	v_mfma_f32_16x16x32_bf16 v[16:19], v[152:155], v[192:195], v[16:19]
	v_mfma_f32_16x16x32_bf16 v[4:7], v[144:147], v[200:203], v[4:7]
	v_mfma_f32_16x16x32_bf16 v[0:3], v[152:155], v[200:203], v[0:3]
	v_mfma_f32_16x16x32_bf16 v[52:55], v[148:151], v[180:183], v[52:55]
	v_mfma_f32_16x16x32_bf16 v[48:51], v[156:159], v[180:183], v[48:51]
	v_mfma_f32_16x16x32_bf16 v[36:39], v[148:151], v[188:191], v[36:39]
	v_mfma_f32_16x16x32_bf16 v[32:35], v[156:159], v[188:191], v[32:35]
	v_mfma_f32_16x16x32_bf16 v[20:23], v[148:151], v[196:199], v[20:23]
	v_mfma_f32_16x16x32_bf16 v[16:19], v[156:159], v[196:199], v[16:19]
	v_mfma_f32_16x16x32_bf16 v[4:7], v[148:151], v[204:207], v[4:7]
	v_mfma_f32_16x16x32_bf16 v[0:3], v[156:159], v[204:207], v[0:3]
	s_setprio 0
	s_barrier
	s_add_i32 s81, s81, 2
	s_add_u32 s58, s58, 0x100
	s_addc_u32 s59, s59, 0
	s_add_u32 s79, s79, 0x100
	s_addc_u32 s80, s80, 0
	s_cmpk_gt_u32 s81, 0x7d
	s_cbranch_scc0 .LBB0_509
	s_and_b64 vcc, exec, s[42:43]
	s_cbranch_vccz .LBB0_512
	s_barrier

; #define PG8_STAGE(bufoff, gbase, voff) do { _Pragma("unroll") for (int _i = 0; _i < 2; ++_i) \
;         __builtin_amdgcn_global_load_lds((const unsigned*)((const char*)(gbase) + (voff)[_i]), (PG8_LAS unsigned*)(lds + (bufoff) + ldsw + _i * 8192), 16, 0, 0); } while (0)
; #define PG8_LDA(dst, b, h) do { _Pragma("unroll") for (int m = 0; m < 4; ++m) _Pragma("unroll") for (int k = 0; k < 2; ++k) dst[m][k] = *(const PG8_LAS bf16x8*)(lds + PG8_SA(b, h) + aoff + m * 2048 + k * 1024); } while (0)
; #define PG8_LDB(dst, b, h) do { _Pragma("unroll") for (int n = 0; n < 2; ++n) _Pragma("unroll") for (int k = 0; k < 2; ++k) dst[n][k] = *(const PG8_LAS bf16x8*)(lds + PG8_SB(b, h) + boff + n * 2048 + k * 1024); } while (0)
; #define PG8_WAIT_V(n) asm volatile("s_waitcnt vmcnt(" #n ")" ::: "memory")
; #define PG8_WAIT_L(n) asm volatile("s_waitcnt lgkmcnt(" #n ")" ::: "memory")
; #define PG8_BAR __builtin_amdgcn_s_barrier()
; #define PG8_SCHED __builtin_amdgcn_sched_barrier(0)
; template <class Epi, class Sched, bool ALIGN_EPI = false, bool SP2 = false>
; __device__ __forceinline__ void gemm_phase(PG8_LAS unsigned char* lds, const Gemm g, const Sched& S, const Epi& E) {
;     ...
;         const bool has_next = S.next(ui + 1, nxt);
;         const char* nA = has_next ? (const char*)g.A + (size_t)nxt.pm * tstep : cA; const char* nB = has_next ? (const char*)g.Bt + (size_t)nxt.pn * tstep : cB;
;         for (int t = 0; t < nt; t += 2) {
;             const bool last = (t == nt - 2);
;             const char* a1 = cA + (size_t)(t + 1) * kstep;
;             const char* a2 = last ? nA : cA + (size_t)(t + 2) * kstep; const char* b2 = last ? nB : cB + (size_t)(t + 2) * kstep;
;             const char* a3 = a2 + kstep; const char* b3 = b2 + kstep;
;             if (last && has_next) S.a_ready(nxt);
;             if constexpr (SP2) {
;             PG8_LDB(B0, 0, 0); PG8_LDB(B1, 0, 1); PG8_SCHED; PG8_LDA(At, 0, 0); PG8_STAGE(PG8_SA(1, 1), a1 + hstep, voffA);
;             PG8_WAIT_V(8); PG8_WAIT_L(0); PG8_BAR; PG8_MMA(0, 0, At, B0); PG8_MMA(0, 1, At, B1); PG8_BAR; PG8_SCHED;
;     ...
;         for (int a = 0; a < 2; ++a)
; #pragma unroll
;             for (int b = 0; b < 2; ++b)
; #pragma unroll
;                 for (int m = 0; m < 4; ++m)
; #pragma unroll
;                     for (int n = 0; n < 2; ++n) acc[a][b][m][n] = (f32x4){0.f, 0.f, 0.f, 0.f};
.LBB0_678:
	s_ashr_i32 s49, s48, 31
	s_lshl_b64 s[50:51], s[48:49], 20
	s_add_u32 s50, s24, s50
	s_addc_u32 s51, s25, s51
	s_and_b64 s[52:53], s[4:5], exec
	s_cselect_b32 s49, s51, s11
	s_cselect_b32 s74, s50, s10
	s_ashr_i32 s47, s46, 31
	s_lshl_b64 s[52:53], s[46:47], 20
	s_add_u32 s52, s45, s52
	s_addc_u32 s53, s56, s53
	s_and_b64 s[54:55], s[4:5], exec
	s_cselect_b32 s47, s53, s13
	s_cselect_b32 s75, s52, s12
	s_add_u32 s10, s10, 0x80080
	s_addc_u32 s11, s11, 0
	s_add_u32 s76, s12, 0x100
	v_mov_b32_e32 v0, 0
	s_addc_u32 s77, s13, 0
	s_mov_b32 s78, -2
	v_mov_b32_e32 v1, v0
	v_mov_b32_e32 v2, v0
	v_mov_b32_e32 v3, v0
	v_mov_b32_e32 v4, v0
	v_mov_b32_e32 v5, v0
	v_mov_b32_e32 v6, v0
	v_mov_b32_e32 v7, v0
	v_mov_b32_e32 v12, v0
	v_mov_b32_e32 v13, v0
	v_mov_b32_e32 v14, v0
	v_mov_b32_e32 v15, v0
	v_mov_b32_e32 v16, v0
	v_mov_b32_e32 v17, v0
	v_mov_b32_e32 v18, v0
	v_mov_b32_e32 v19, v0
	v_mov_b32_e32 v28, v0
	v_mov_b32_e32 v29, v0
	v_mov_b32_e32 v30, v0
	v_mov_b32_e32 v31, v0
	v_mov_b32_e32 v32, v0
	v_mov_b32_e32 v33, v0
	v_mov_b32_e32 v34, v0
	v_mov_b32_e32 v35, v0
	v_mov_b32_e32 v44, v0
	v_mov_b32_e32 v45, v0
	v_mov_b32_e32 v46, v0
	v_mov_b32_e32 v47, v0
	v_mov_b32_e32 v48, v0
	v_mov_b32_e32 v49, v0
	v_mov_b32_e32 v50, v0
	v_mov_b32_e32 v51, v0
	v_mov_b32_e32 v8, v0
	v_mov_b32_e32 v9, v0
	v_mov_b32_e32 v10, v0
	v_mov_b32_e32 v11, v0
	v_mov_b32_e32 v20, v0
	v_mov_b32_e32 v21, v0
	v_mov_b32_e32 v22, v0
	v_mov_b32_e32 v23, v0
	v_mov_b32_e32 v24, v0
	v_mov_b32_e32 v25, v0
	v_mov_b32_e32 v26, v0
	v_mov_b32_e32 v27, v0
	v_mov_b32_e32 v36, v0
	v_mov_b32_e32 v37, v0
	v_mov_b32_e32 v38, v0
	v_mov_b32_e32 v39, v0
	v_mov_b32_e32 v40, v0
	v_mov_b32_e32 v41, v0
	v_mov_b32_e32 v42, v0
	v_mov_b32_e32 v43, v0
	v_mov_b32_e32 v52, v0
	v_mov_b32_e32 v53, v0
	v_mov_b32_e32 v54, v0
	v_mov_b32_e32 v55, v0
	v_mov_b32_e32 v56, v0
	v_mov_b32_e32 v57, v0
	v_mov_b32_e32 v58, v0
	v_mov_b32_e32 v59, v0
	v_mov_b32_e32 v60, v0
	v_mov_b32_e32 v61, v0
	v_mov_b32_e32 v62, v0
	v_mov_b32_e32 v63, v0
	v_mov_b32_e32 v64, v0
	v_mov_b32_e32 v65, v0
	v_mov_b32_e32 v66, v0
	v_mov_b32_e32 v67, v0
	v_mov_b32_e32 v68, v0
	v_mov_b32_e32 v69, v0
	v_mov_b32_e32 v70, v0
	v_mov_b32_e32 v71, v0
	v_mov_b32_e32 v76, v0
	v_mov_b32_e32 v77, v0
	v_mov_b32_e32 v78, v0
	v_mov_b32_e32 v79, v0
	v_mov_b32_e32 v80, v0
	v_mov_b32_e32 v81, v0
	v_mov_b32_e32 v82, v0
	v_mov_b32_e32 v83, v0
	v_mov_b32_e32 v92, v0
	v_mov_b32_e32 v93, v0
	v_mov_b32_e32 v94, v0
	v_mov_b32_e32 v95, v0
	v_mov_b32_e32 v96, v0
	v_mov_b32_e32 v97, v0
	v_mov_b32_e32 v98, v0
	v_mov_b32_e32 v99, v0
	v_mov_b32_e32 v108, v0
	v_mov_b32_e32 v109, v0
	v_mov_b32_e32 v110, v0
	v_mov_b32_e32 v111, v0
	v_mov_b32_e32 v116, v0
	v_mov_b32_e32 v117, v0
	v_mov_b32_e32 v118, v0
	v_mov_b32_e32 v119, v0
	v_mov_b32_e32 v72, v0
	v_mov_b32_e32 v73, v0
	v_mov_b32_e32 v74, v0
	v_mov_b32_e32 v75, v0
	v_mov_b32_e32 v84, v0
	v_mov_b32_e32 v85, v0
	v_mov_b32_e32 v86, v0
	v_mov_b32_e32 v87, v0
	v_mov_b32_e32 v88, v0
	v_mov_b32_e32 v89, v0
	v_mov_b32_e32 v90, v0
	v_mov_b32_e32 v91, v0
	v_mov_b32_e32 v100, v0
	v_mov_b32_e32 v101, v0
	v_mov_b32_e32 v102, v0
	v_mov_b32_e32 v103, v0
	v_mov_b32_e32 v104, v0
	v_mov_b32_e32 v105, v0
	v_mov_b32_e32 v106, v0
	v_mov_b32_e32 v107, v0
	v_mov_b32_e32 v112, v0
	v_mov_b32_e32 v113, v0
	v_mov_b32_e32 v114, v0
	v_mov_b32_e32 v115, v0
	v_mov_b32_e32 v120, v0
	v_mov_b32_e32 v121, v0
	v_mov_b32_e32 v122, v0
	v_mov_b32_e32 v123, v0
	v_mov_b32_e32 v124, v0
	v_mov_b32_e32 v125, v0
	v_mov_b32_e32 v126, v0
	v_mov_b32_e32 v127, v0
	v_add_u32_e32 v253, 0x80, v162
	v_add_u32_e32 v252, 0x80, v166
	v_add_u32_e32 v251, 0x80, v160
	v_add_u32_e32 v250, 0x80, v164
.LBB0_679:
	ds_read_b128 v[128:131], v203
	ds_read_b128 v[132:135], v203 offset:1024
	ds_read_b128 v[136:139], v203 offset:2048
	ds_read_b128 v[140:143], v203 offset:3072
	ds_read_b128 v[144:147], v205
	ds_read_b128 v[148:151], v205 offset:1024
	ds_read_b128 v[152:155], v205 offset:2048
	ds_read_b128 v[156:159], v205 offset:3072
	s_add_u32 s12, s10, 0xfff80080
	s_addc_u32 s13, s11, -1
	s_cmp_eq_u32 s78, 28
	s_cselect_b32 s55, s49, s13
	s_cselect_b32 s54, s74, s12
	s_cselect_b32 s13, s47, s77
	s_cselect_b32 s12, s75, s76
	s_nop 0
	s_add_i32 m0, s60, 0xc000
	ds_read_b128 v[176:179], v207
	ds_read_b128 v[180:183], v207 offset:1024
	ds_read_b128 v[184:187], v207 offset:2048
	ds_read_b128 v[192:195], v207 offset:3072
	ds_read_b128 v[210:213], v207 offset:4096
	ds_read_b128 v[214:217], v207 offset:5120
	ds_read_b128 v[218:221], v207 offset:6144
	ds_read_b128 v[222:225], v207 offset:7168
	global_load_lds_dwordx4 v168, s[10:11]
	s_nop 0
	s_add_i32 m0, s60, 0xe000
	s_nop 0
	global_load_lds_dwordx4 v170, s[10:11]
	s_waitcnt vmcnt(8)
	s_waitcnt lgkmcnt(0)
	s_barrier
; #define PG8_STAGE(bufoff, gbase, voff) do { _Pragma("unroll") for (int _i = 0; _i < 2; ++_i) \
;         __builtin_amdgcn_global_load_lds((const unsigned*)((const char*)(gbase) + (voff)[_i]), (PG8_LAS unsigned*)(lds + (bufoff) + ldsw + _i * 8192), 16, 0, 0); } while (0)
; #define PG8_LDA(dst, b, h) do { _Pragma("unroll") for (int m = 0; m < 4; ++m) _Pragma("unroll") for (int k = 0; k < 2; ++k) dst[m][k] = *(const PG8_LAS bf16x8*)(lds + PG8_SA(b, h) + aoff + m * 2048 + k * 1024); } while (0)
; #define PG8_MMA(ai, bj, At, Bt) do { __builtin_amdgcn_s_setprio(1); _Pragma("unroll") for (int m = 0; m < 4; ++m) _Pragma("unroll") for (int n = 0; n < 2; ++n) _Pragma("unroll") for (int k = 0; k < 2; ++k) \
;         acc[ai][bj][m][n] = __builtin_amdgcn_mfma_f32_16x16x32_bf16(Bt[n][k], At[m][k], acc[ai][bj][m][n], 0, 0, 0); __builtin_amdgcn_s_setprio(0); } while (0)
; #define PG8_WAIT_V(n) asm volatile("s_waitcnt vmcnt(" #n ")" ::: "memory")
; #define PG8_WAIT_L(n) asm volatile("s_waitcnt lgkmcnt(" #n ")" ::: "memory")
; #define PG8_BAR __builtin_amdgcn_s_barrier()
; #define PG8_SCHED __builtin_amdgcn_sched_barrier(0)
; template <class Epi, class Sched, bool ALIGN_EPI = false, bool SP2 = false>
; __device__ __forceinline__ void gemm_phase(PG8_LAS unsigned char* lds, const Gemm g, const Sched& S, const Epi& E) {
;     ...
;             PG8_WAIT_V(8); PG8_WAIT_L(0); PG8_BAR; PG8_MMA(0, 0, At, B0); PG8_MMA(0, 1, At, B1); PG8_BAR; PG8_SCHED;
;             PG8_LDA(At, 0, 1); PG8_STAGE(PG8_SB(0, 0), b2, voffB); PG8_STAGE(PG8_SB(0, 1), b2 + hstep, voffB); PG8_STAGE(PG8_SA(0, 0), a2, voffA);
;             PG8_WAIT_V(8); PG8_WAIT_L(0); PG8_BAR; PG8_MMA(1, 0, At, B0); PG8_MMA(1, 1, At, B1); PG8_BAR; PG8_SCHED;
	s_setprio 1
	s_waitcnt lgkmcnt(0)
	v_mfma_f32_16x16x32_bf16 v[124:127], v[128:131], v[176:179], v[124:127]
	v_mfma_f32_16x16x32_bf16 v[120:123], v[136:139], v[176:179], v[120:123]
	v_mfma_f32_16x16x32_bf16 v[112:115], v[128:131], v[184:187], v[112:115]
	v_mfma_f32_16x16x32_bf16 v[104:107], v[136:139], v[184:187], v[104:107]
	v_mfma_f32_16x16x32_bf16 v[100:103], v[128:131], v[210:213], v[100:103]
	v_mfma_f32_16x16x32_bf16 v[88:91], v[136:139], v[210:213], v[88:91]
	v_mfma_f32_16x16x32_bf16 v[84:87], v[128:131], v[218:221], v[84:87]
	v_mfma_f32_16x16x32_bf16 v[72:75], v[136:139], v[218:221], v[72:75]
	v_mfma_f32_16x16x32_bf16 v[124:127], v[132:135], v[180:183], v[124:127]
	v_mfma_f32_16x16x32_bf16 v[120:123], v[140:143], v[180:183], v[120:123]
	v_mfma_f32_16x16x32_bf16 v[112:115], v[132:135], v[192:195], v[112:115]
	v_mfma_f32_16x16x32_bf16 v[104:107], v[140:143], v[192:195], v[104:107]
	v_mfma_f32_16x16x32_bf16 v[100:103], v[132:135], v[214:217], v[100:103]
	v_mfma_f32_16x16x32_bf16 v[88:91], v[140:143], v[214:217], v[88:91]
	v_mfma_f32_16x16x32_bf16 v[84:87], v[132:135], v[222:225], v[84:87]
	v_mfma_f32_16x16x32_bf16 v[72:75], v[140:143], v[222:225], v[72:75]
	s_setprio 0
	s_setprio 1
	v_mfma_f32_16x16x32_bf16 v[116:119], v[144:147], v[176:179], v[116:119]
	v_mfma_f32_16x16x32_bf16 v[108:111], v[152:155], v[176:179], v[108:111]
	v_mfma_f32_16x16x32_bf16 v[96:99], v[144:147], v[184:187], v[96:99]
	v_mfma_f32_16x16x32_bf16 v[92:95], v[152:155], v[184:187], v[92:95]
	v_mfma_f32_16x16x32_bf16 v[80:83], v[144:147], v[210:213], v[80:83]
	v_mfma_f32_16x16x32_bf16 v[76:79], v[152:155], v[210:213], v[76:79]
	v_mfma_f32_16x16x32_bf16 v[68:71], v[144:147], v[218:221], v[68:71]
	v_mfma_f32_16x16x32_bf16 v[64:67], v[152:155], v[218:221], v[64:67]
	v_mfma_f32_16x16x32_bf16 v[116:119], v[148:151], v[180:183], v[116:119]
	v_mfma_f32_16x16x32_bf16 v[108:111], v[156:159], v[180:183], v[108:111]
	v_mfma_f32_16x16x32_bf16 v[96:99], v[148:151], v[192:195], v[96:99]
	v_mfma_f32_16x16x32_bf16 v[92:95], v[156:159], v[192:195], v[92:95]
	v_mfma_f32_16x16x32_bf16 v[80:83], v[148:151], v[214:217], v[80:83]
	v_mfma_f32_16x16x32_bf16 v[76:79], v[156:159], v[214:217], v[76:79]
	v_mfma_f32_16x16x32_bf16 v[68:71], v[148:151], v[222:225], v[68:71]
	v_mfma_f32_16x16x32_bf16 v[64:67], v[156:159], v[222:225], v[64:67]
	s_setprio 0
	s_barrier
	s_add_i32 s79, s70, s57
	s_mov_b64 s[96:97], s[12:13]
	s_nop 0
	s_mov_b32 m0, s79
	ds_read_b128 v[176:179], v207 offset:16384
	ds_read_b128 v[180:183], v207 offset:17408
	ds_read_b128 v[184:187], v207 offset:18432
	ds_read_b128 v[192:195], v207 offset:19456
	ds_read_b128 v[210:213], v207 offset:20480
	ds_read_b128 v[214:217], v207 offset:21504
	ds_read_b128 v[218:221], v207 offset:22528
	ds_read_b128 v[222:225], v207 offset:23552
	global_load_lds_dwordx4 v164, s[12:13]
	s_add_i32 m0, s79, 0x2000
	s_add_u32 s80, s12, 0x80000
	s_nop 0
	s_addc_u32 s81, s13, 0
	s_add_i32 s79, s71, s57
	global_load_lds_dwordx4 v160, s[12:13]
	s_nop 0
	s_mov_b32 m0, s79
	s_nop 0
	global_load_lds_dwordx4 v164, s[80:81]
	s_nop 0
	s_add_i32 m0, s79, 0x2000
	s_nop 0
	global_load_lds_dwordx4 v160, s[80:81]
	s_mov_b64 s[98:99], s[54:55]
	s_nop 0
	s_mov_b32 m0, s60
	s_nop 0
	global_load_lds_dwordx4 v166, s[54:55]
	s_mov_b32 m0, s61
	s_nop 0
	global_load_lds_dwordx4 v162, s[54:55]
	s_waitcnt vmcnt(8)
	s_waitcnt lgkmcnt(0)
	s_barrier
	s_setprio 1
	s_waitcnt lgkmcnt(0)
	v_mfma_f32_16x16x32_bf16 v[60:63], v[128:131], v[176:179], v[60:63]
	v_mfma_f32_16x16x32_bf16 v[56:59], v[136:139], v[176:179], v[56:59]
	v_mfma_f32_16x16x32_bf16 v[52:55], v[128:131], v[184:187], v[52:55]
	v_mfma_f32_16x16x32_bf16 v[40:43], v[136:139], v[184:187], v[40:43]
	v_mfma_f32_16x16x32_bf16 v[36:39], v[128:131], v[210:213], v[36:39]
	v_mfma_f32_16x16x32_bf16 v[24:27], v[136:139], v[210:213], v[24:27]
	v_mfma_f32_16x16x32_bf16 v[20:23], v[128:131], v[218:221], v[20:23]
	v_mfma_f32_16x16x32_bf16 v[8:11], v[136:139], v[218:221], v[8:11]
	v_mfma_f32_16x16x32_bf16 v[60:63], v[132:135], v[180:183], v[60:63]
	v_mfma_f32_16x16x32_bf16 v[56:59], v[140:143], v[180:183], v[56:59]
	v_mfma_f32_16x16x32_bf16 v[52:55], v[132:135], v[192:195], v[52:55]
	v_mfma_f32_16x16x32_bf16 v[40:43], v[140:143], v[192:195], v[40:43]
	v_mfma_f32_16x16x32_bf16 v[36:39], v[132:135], v[214:217], v[36:39]
	v_mfma_f32_16x16x32_bf16 v[24:27], v[140:143], v[214:217], v[24:27]
	v_mfma_f32_16x16x32_bf16 v[20:23], v[132:135], v[222:225], v[20:23]
	v_mfma_f32_16x16x32_bf16 v[8:11], v[140:143], v[222:225], v[8:11]
	s_setprio 0
	s_setprio 1
	v_mfma_f32_16x16x32_bf16 v[48:51], v[144:147], v[176:179], v[48:51]
	v_mfma_f32_16x16x32_bf16 v[44:47], v[152:155], v[176:179], v[44:47]
	v_mfma_f32_16x16x32_bf16 v[32:35], v[144:147], v[184:187], v[32:35]
	v_mfma_f32_16x16x32_bf16 v[28:31], v[152:155], v[184:187], v[28:31]
	v_mfma_f32_16x16x32_bf16 v[16:19], v[144:147], v[210:213], v[16:19]
	v_mfma_f32_16x16x32_bf16 v[12:15], v[152:155], v[210:213], v[12:15]
	v_mfma_f32_16x16x32_bf16 v[4:7], v[144:147], v[218:221], v[4:7]
	v_mfma_f32_16x16x32_bf16 v[0:3], v[152:155], v[218:221], v[0:3]
	v_mfma_f32_16x16x32_bf16 v[48:51], v[148:151], v[180:183], v[48:51]
	v_mfma_f32_16x16x32_bf16 v[44:47], v[156:159], v[180:183], v[44:47]
	v_mfma_f32_16x16x32_bf16 v[32:35], v[148:151], v[192:195], v[32:35]
	v_mfma_f32_16x16x32_bf16 v[28:31], v[156:159], v[192:195], v[28:31]
	v_mfma_f32_16x16x32_bf16 v[16:19], v[148:151], v[214:217], v[16:19]
	v_mfma_f32_16x16x32_bf16 v[12:15], v[156:159], v[214:217], v[12:15]
	v_mfma_f32_16x16x32_bf16 v[4:7], v[148:151], v[222:225], v[4:7]
	v_mfma_f32_16x16x32_bf16 v[0:3], v[156:159], v[222:225], v[0:3]
	s_setprio 0
	s_barrier
; #define PG8_STAGE(bufoff, gbase, voff) do { _Pragma("unroll") for (int _i = 0; _i < 2; ++_i) \
;         __builtin_amdgcn_global_load_lds((const unsigned*)((const char*)(gbase) + (voff)[_i]), (PG8_LAS unsigned*)(lds + (bufoff) + ldsw + _i * 8192), 16, 0, 0); } while (0)
; #define PG8_LDA(dst, b, h) do { _Pragma("unroll") for (int m = 0; m < 4; ++m) _Pragma("unroll") for (int k = 0; k < 2; ++k) dst[m][k] = *(const PG8_LAS bf16x8*)(lds + PG8_SA(b, h) + aoff + m * 2048 + k * 1024); } while (0)
; #define PG8_LDB(dst, b, h) do { _Pragma("unroll") for (int n = 0; n < 2; ++n) _Pragma("unroll") for (int k = 0; k < 2; ++k) dst[n][k] = *(const PG8_LAS bf16x8*)(lds + PG8_SB(b, h) + boff + n * 2048 + k * 1024); } while (0)
; #define PG8_MMA(ai, bj, At, Bt) do { __builtin_amdgcn_s_setprio(1); _Pragma("unroll") for (int m = 0; m < 4; ++m) _Pragma("unroll") for (int n = 0; n < 2; ++n) _Pragma("unroll") for (int k = 0; k < 2; ++k) \
;         acc[ai][bj][m][n] = __builtin_amdgcn_mfma_f32_16x16x32_bf16(Bt[n][k], At[m][k], acc[ai][bj][m][n], 0, 0, 0); __builtin_amdgcn_s_setprio(0); } while (0)
; #define PG8_WAIT_V(n) asm volatile("s_waitcnt vmcnt(" #n ")" ::: "memory")
; #define PG8_WAIT_L(n) asm volatile("s_waitcnt lgkmcnt(" #n ")" ::: "memory")
; #define PG8_BAR __builtin_amdgcn_s_barrier()
; #define PG8_SCHED __builtin_amdgcn_sched_barrier(0)
; template <class Epi, class Sched, bool ALIGN_EPI = false, bool SP2 = false>
; __device__ __forceinline__ void gemm_phase(PG8_LAS unsigned char* lds, const Gemm g, const Sched& S, const Epi& E) {
;     ...
;             PG8_LDB(B0, 1, 0); PG8_LDB(B1, 1, 1); PG8_SCHED; PG8_LDA(At, 1, 0); PG8_STAGE(PG8_SA(0, 1), a2 + hstep, voffA);
;             PG8_WAIT_V(8); PG8_WAIT_L(0); PG8_BAR; PG8_MMA(0, 0, At, B0); PG8_MMA(0, 1, At, B1); PG8_BAR; PG8_SCHED;
;             PG8_LDA(At, 1, 1); PG8_STAGE(PG8_SB(1, 0), b3, voffB); PG8_STAGE(PG8_SB(1, 1), b3 + hstep, voffB); PG8_STAGE(PG8_SA(1, 0), a3, voffA);
;             PG8_WAIT_V(8); PG8_WAIT_L(0); PG8_BAR; PG8_MMA(1, 0, At, B0); PG8_MMA(1, 1, At, B1); PG8_BAR; PG8_SCHED;
	s_add_i32 s79, 0, 0x18000
	s_add_i32 s80, 0, 0x1c000
	v_add_u32_e32 v140, s79, v197
	v_add_u32_e32 v156, s80, v197
	ds_read_b128 v[128:131], v140
	ds_read_b128 v[132:135], v140 offset:1024
	ds_read_b128 v[136:139], v140 offset:2048
	ds_read_b128 v[140:143], v140 offset:3072
	ds_read_b128 v[144:147], v156
	ds_read_b128 v[148:151], v156 offset:1024
	ds_read_b128 v[152:155], v156 offset:2048
	ds_read_b128 v[156:159], v156 offset:3072
	s_add_u32 s54, s54, 0x80000
	s_addc_u32 s55, s55, 0
	s_mov_b32 m0, s62
	s_nop 0
	ds_read_b128 v[176:179], v207 offset:32768
	ds_read_b128 v[180:183], v207 offset:33792
	ds_read_b128 v[184:187], v207 offset:34816
	ds_read_b128 v[192:195], v207 offset:35840
	ds_read_b128 v[210:213], v207 offset:36864
	ds_read_b128 v[214:217], v207 offset:37888
	ds_read_b128 v[218:221], v207 offset:38912
	ds_read_b128 v[222:225], v207 offset:39936
	global_load_lds_dwordx4 v166, s[54:55]
	s_nop 0
	s_mov_b32 m0, s63
	s_nop 0
	global_load_lds_dwordx4 v162, s[54:55]
	s_waitcnt vmcnt(8)
	s_waitcnt lgkmcnt(0)
	s_barrier
	s_setprio 1
	s_waitcnt lgkmcnt(0)
	v_mfma_f32_16x16x32_bf16 v[124:127], v[128:131], v[176:179], v[124:127]
	v_mfma_f32_16x16x32_bf16 v[120:123], v[136:139], v[176:179], v[120:123]
	v_mfma_f32_16x16x32_bf16 v[112:115], v[128:131], v[184:187], v[112:115]
	v_mfma_f32_16x16x32_bf16 v[104:107], v[136:139], v[184:187], v[104:107]
	v_mfma_f32_16x16x32_bf16 v[100:103], v[128:131], v[210:213], v[100:103]
	v_mfma_f32_16x16x32_bf16 v[88:91], v[136:139], v[210:213], v[88:91]
	v_mfma_f32_16x16x32_bf16 v[84:87], v[128:131], v[218:221], v[84:87]
	v_mfma_f32_16x16x32_bf16 v[72:75], v[136:139], v[218:221], v[72:75]
	v_mfma_f32_16x16x32_bf16 v[124:127], v[132:135], v[180:183], v[124:127]
	v_mfma_f32_16x16x32_bf16 v[120:123], v[140:143], v[180:183], v[120:123]
	v_mfma_f32_16x16x32_bf16 v[112:115], v[132:135], v[192:195], v[112:115]
	v_mfma_f32_16x16x32_bf16 v[104:107], v[140:143], v[192:195], v[104:107]
	v_mfma_f32_16x16x32_bf16 v[100:103], v[132:135], v[214:217], v[100:103]
	v_mfma_f32_16x16x32_bf16 v[88:91], v[140:143], v[214:217], v[88:91]
	v_mfma_f32_16x16x32_bf16 v[84:87], v[132:135], v[222:225], v[84:87]
	v_mfma_f32_16x16x32_bf16 v[72:75], v[140:143], v[222:225], v[72:75]
	s_setprio 0
	s_setprio 1
	v_mfma_f32_16x16x32_bf16 v[116:119], v[144:147], v[176:179], v[116:119]
	v_mfma_f32_16x16x32_bf16 v[108:111], v[152:155], v[176:179], v[108:111]
	v_mfma_f32_16x16x32_bf16 v[96:99], v[144:147], v[184:187], v[96:99]
	v_mfma_f32_16x16x32_bf16 v[92:95], v[152:155], v[184:187], v[92:95]
	v_mfma_f32_16x16x32_bf16 v[80:83], v[144:147], v[210:213], v[80:83]
	v_mfma_f32_16x16x32_bf16 v[76:79], v[152:155], v[210:213], v[76:79]
	v_mfma_f32_16x16x32_bf16 v[68:71], v[144:147], v[218:221], v[68:71]
	v_mfma_f32_16x16x32_bf16 v[64:67], v[152:155], v[218:221], v[64:67]
	v_mfma_f32_16x16x32_bf16 v[116:119], v[148:151], v[180:183], v[116:119]
	v_mfma_f32_16x16x32_bf16 v[108:111], v[156:159], v[180:183], v[108:111]
	v_mfma_f32_16x16x32_bf16 v[96:99], v[148:151], v[192:195], v[96:99]
	v_mfma_f32_16x16x32_bf16 v[92:95], v[156:159], v[192:195], v[92:95]
	v_mfma_f32_16x16x32_bf16 v[80:83], v[148:151], v[214:217], v[80:83]
	v_mfma_f32_16x16x32_bf16 v[76:79], v[156:159], v[214:217], v[76:79]
	v_mfma_f32_16x16x32_bf16 v[68:71], v[148:151], v[222:225], v[68:71]
	v_mfma_f32_16x16x32_bf16 v[64:67], v[156:159], v[222:225], v[64:67]
	s_setprio 0
	s_barrier
	s_add_i32 s54, s79, s57
	s_nop 0
	s_mov_b32 m0, s54
	ds_read_b128 v[176:179], v207 offset:49152
	ds_read_b128 v[180:183], v207 offset:50176
	ds_read_b128 v[184:187], v207 offset:51200
	ds_read_b128 v[192:195], v207 offset:52224
	ds_read_b128 v[210:213], v207 offset:53248
	ds_read_b128 v[214:217], v207 offset:54272
	ds_read_b128 v[218:221], v207 offset:55296
	ds_read_b128 v[222:225], v207 offset:56320
	global_load_lds_dwordx4 v250, s[96:97]
	s_add_i32 m0, s54, 0x2000
	s_add_u32 s12, s12, 0x80080
	s_nop 0
	s_addc_u32 s13, s13, 0
	s_add_i32 s54, s80, s57
	global_load_lds_dwordx4 v251, s[96:97]
	s_nop 0
	s_mov_b32 m0, s54
	s_nop 0
	global_load_lds_dwordx4 v164, s[12:13]
	s_nop 0
	s_add_i32 m0, s54, 0x2000
	s_nop 0
	global_load_lds_dwordx4 v160, s[12:13]
	s_nop 0
	s_mov_b32 m0, s65
	s_nop 0
	global_load_lds_dwordx4 v252, s[98:99]
	s_nop 0
	s_mov_b32 m0, s67
	s_nop 0
	global_load_lds_dwordx4 v253, s[98:99]
	s_waitcnt vmcnt(8)
	s_waitcnt lgkmcnt(0)
	s_barrier
	s_setprio 1
	s_waitcnt lgkmcnt(0)
	v_mfma_f32_16x16x32_bf16 v[60:63], v[128:131], v[176:179], v[60:63]
	v_mfma_f32_16x16x32_bf16 v[56:59], v[136:139], v[176:179], v[56:59]
	v_mfma_f32_16x16x32_bf16 v[52:55], v[128:131], v[184:187], v[52:55]
	v_mfma_f32_16x16x32_bf16 v[40:43], v[136:139], v[184:187], v[40:43]
	v_mfma_f32_16x16x32_bf16 v[36:39], v[128:131], v[210:213], v[36:39]
	v_mfma_f32_16x16x32_bf16 v[24:27], v[136:139], v[210:213], v[24:27]
	v_mfma_f32_16x16x32_bf16 v[20:23], v[128:131], v[218:221], v[20:23]
	v_mfma_f32_16x16x32_bf16 v[8:11], v[136:139], v[218:221], v[8:11]
	v_mfma_f32_16x16x32_bf16 v[60:63], v[132:135], v[180:183], v[60:63]
	v_mfma_f32_16x16x32_bf16 v[56:59], v[140:143], v[180:183], v[56:59]
	v_mfma_f32_16x16x32_bf16 v[52:55], v[132:135], v[192:195], v[52:55]
	v_mfma_f32_16x16x32_bf16 v[40:43], v[140:143], v[192:195], v[40:43]
	v_mfma_f32_16x16x32_bf16 v[36:39], v[132:135], v[214:217], v[36:39]
	v_mfma_f32_16x16x32_bf16 v[24:27], v[140:143], v[214:217], v[24:27]
	v_mfma_f32_16x16x32_bf16 v[20:23], v[132:135], v[222:225], v[20:23]
	v_mfma_f32_16x16x32_bf16 v[8:11], v[140:143], v[222:225], v[8:11]
	s_setprio 0
	s_setprio 1
	v_mfma_f32_16x16x32_bf16 v[48:51], v[144:147], v[176:179], v[48:51]
	v_mfma_f32_16x16x32_bf16 v[44:47], v[152:155], v[176:179], v[44:47]
	v_mfma_f32_16x16x32_bf16 v[32:35], v[144:147], v[184:187], v[32:35]
	v_mfma_f32_16x16x32_bf16 v[28:31], v[152:155], v[184:187], v[28:31]
	v_mfma_f32_16x16x32_bf16 v[16:19], v[144:147], v[210:213], v[16:19]
	v_mfma_f32_16x16x32_bf16 v[12:15], v[152:155], v[210:213], v[12:15]
	v_mfma_f32_16x16x32_bf16 v[4:7], v[144:147], v[218:221], v[4:7]
	v_mfma_f32_16x16x32_bf16 v[0:3], v[152:155], v[218:221], v[0:3]
	v_mfma_f32_16x16x32_bf16 v[48:51], v[148:151], v[180:183], v[48:51]
	v_mfma_f32_16x16x32_bf16 v[44:47], v[156:159], v[180:183], v[44:47]
	v_mfma_f32_16x16x32_bf16 v[32:35], v[148:151], v[192:195], v[32:35]
	v_mfma_f32_16x16x32_bf16 v[28:31], v[156:159], v[192:195], v[28:31]
	v_mfma_f32_16x16x32_bf16 v[16:19], v[148:151], v[214:217], v[16:19]
	v_mfma_f32_16x16x32_bf16 v[12:15], v[156:159], v[214:217], v[12:15]
	v_mfma_f32_16x16x32_bf16 v[4:7], v[148:151], v[222:225], v[4:7]
	v_mfma_f32_16x16x32_bf16 v[0:3], v[156:159], v[222:225], v[0:3]
	s_setprio 0
	s_barrier
	s_add_i32 s78, s78, 2
	s_add_u32 s10, s10, 0x100
	s_addc_u32 s11, s11, 0
	s_add_u32 s76, s76, 0x100
	s_addc_u32 s77, s77, 0
	s_cmp_gt_u32 s78, 29
	s_cbranch_scc0 .LBB0_679
	s_and_b64 vcc, exec, s[42:43]
	s_cbranch_vccz .LBB0_682
	s_barrier

; #define PG8_STAGE(bufoff, gbase, voff) do { _Pragma("unroll") for (int _i = 0; _i < 2; ++_i) \
;         __builtin_amdgcn_global_load_lds((const unsigned*)((const char*)(gbase) + (voff)[_i]), (PG8_LAS unsigned*)(lds + (bufoff) + ldsw + _i * 8192), 16, 0, 0); } while (0)
; #define PG8_LDA(dst, b, h) do { _Pragma("unroll") for (int m = 0; m < 4; ++m) _Pragma("unroll") for (int k = 0; k < 2; ++k) dst[m][k] = *(const PG8_LAS bf16x8*)(lds + PG8_SA(b, h) + aoff + m * 2048 + k * 1024); } while (0)
; #define PG8_LDB(dst, b, h) do { _Pragma("unroll") for (int n = 0; n < 2; ++n) _Pragma("unroll") for (int k = 0; k < 2; ++k) dst[n][k] = *(const PG8_LAS bf16x8*)(lds + PG8_SB(b, h) + boff + n * 2048 + k * 1024); } while (0)
; #define PG8_MMA(ai, bj, At, Bt) do { __builtin_amdgcn_s_setprio(1); _Pragma("unroll") for (int m = 0; m < 4; ++m) _Pragma("unroll") for (int n = 0; n < 2; ++n) _Pragma("unroll") for (int k = 0; k < 2; ++k) \
;         acc[ai][bj][m][n] = __builtin_amdgcn_mfma_f32_16x16x32_bf16(Bt[n][k], At[m][k], acc[ai][bj][m][n], 0, 0, 0); __builtin_amdgcn_s_setprio(0); } while (0)
; #define PG8_WAIT_V(n) asm volatile("s_waitcnt vmcnt(" #n ")" ::: "memory")
; #define PG8_WAIT_L(n) asm volatile("s_waitcnt lgkmcnt(" #n ")" ::: "memory")
; #define PG8_BAR __builtin_amdgcn_s_barrier()
; #define PG8_SCHED __builtin_amdgcn_sched_barrier(0)
; template <class Epi, class Sched, bool ALIGN_EPI = false, bool SP2 = false>
; __device__ __forceinline__ void gemm_phase(PG8_LAS unsigned char* lds, const Gemm g, const Sched& S, const Epi& E) {
;     ...
;             PG8_LDB(B0, 0, 0); PG8_LDB(B1, 0, 1); PG8_SCHED; PG8_LDA(At, 0, 0); PG8_STAGE(PG8_SA(1, 1), a1 + hstep, voffA);
;             PG8_WAIT_V(8); PG8_WAIT_L(0); PG8_BAR; PG8_MMA(0, 0, At, B0); PG8_MMA(0, 1, At, B1); PG8_BAR; PG8_SCHED;
;             PG8_LDA(At, 0, 1); PG8_STAGE(PG8_SB(0, 0), b2, voffB); PG8_STAGE(PG8_SB(0, 1), b2 + hstep, voffB); PG8_STAGE(PG8_SA(0, 0), a2, voffA);
;             PG8_WAIT_V(8); PG8_WAIT_L(0); PG8_BAR; PG8_MMA(1, 0, At, B0); PG8_MMA(1, 1, At, B1); PG8_BAR; PG8_SCHED;
.LBB0_939:
	ds_read_b128 v[64:67], v213
	ds_read_b128 v[68:71], v213 offset:1024
	ds_read_b128 v[72:75], v213 offset:2048
	ds_read_b128 v[76:79], v213 offset:3072
	ds_read_b128 v[144:147], v214
	ds_read_b128 v[148:151], v214 offset:1024
	ds_read_b128 v[152:155], v214 offset:2048
	ds_read_b128 v[156:159], v214 offset:3072
	s_add_u32 s60, s58, 0xfff80080
	s_addc_u32 s61, s59, -1
	s_cmp_eq_u32 s81, 28
	s_cselect_b32 s63, s11, s61
	s_cselect_b32 s62, s51, s60
	s_cselect_b32 s61, s49, s80
	s_cselect_b32 s60, s78, s79
	s_nop 0
	s_add_i32 m0, s57, 0xc000
	ds_read_b128 v[176:179], v215
	ds_read_b128 v[180:183], v215 offset:1024
	ds_read_b128 v[184:187], v215 offset:2048
	ds_read_b128 v[188:191], v215 offset:3072
	ds_read_b128 v[192:195], v215 offset:4096
	ds_read_b128 v[196:199], v215 offset:5120
	ds_read_b128 v[200:203], v215 offset:6144
	ds_read_b128 v[204:207], v215 offset:7168
	global_load_lds_dwordx4 v168, s[58:59]
	s_nop 0
	s_add_i32 m0, s57, 0xe000
	s_nop 0
	global_load_lds_dwordx4 v170, s[58:59]
	s_waitcnt vmcnt(8)
	s_waitcnt lgkmcnt(0)
	s_barrier
	s_setprio 1
	s_waitcnt lgkmcnt(0)
	v_mfma_f32_16x16x32_bf16 v[140:143], v[64:67], v[176:179], v[140:143]
	v_mfma_f32_16x16x32_bf16 v[136:139], v[72:75], v[176:179], v[136:139]
	v_mfma_f32_16x16x32_bf16 v[124:127], v[64:67], v[184:187], v[124:127]
	v_mfma_f32_16x16x32_bf16 v[120:123], v[72:75], v[184:187], v[120:123]
	v_mfma_f32_16x16x32_bf16 v[108:111], v[64:67], v[192:195], v[108:111]
	v_mfma_f32_16x16x32_bf16 v[104:107], v[72:75], v[192:195], v[104:107]
	v_mfma_f32_16x16x32_bf16 v[92:95], v[64:67], v[200:203], v[92:95]
	v_mfma_f32_16x16x32_bf16 v[88:91], v[72:75], v[200:203], v[88:91]
	v_mfma_f32_16x16x32_bf16 v[140:143], v[68:71], v[180:183], v[140:143]
	v_mfma_f32_16x16x32_bf16 v[136:139], v[76:79], v[180:183], v[136:139]
	v_mfma_f32_16x16x32_bf16 v[124:127], v[68:71], v[188:191], v[124:127]
	v_mfma_f32_16x16x32_bf16 v[120:123], v[76:79], v[188:191], v[120:123]
	v_mfma_f32_16x16x32_bf16 v[108:111], v[68:71], v[196:199], v[108:111]
	v_mfma_f32_16x16x32_bf16 v[104:107], v[76:79], v[196:199], v[104:107]
	v_mfma_f32_16x16x32_bf16 v[92:95], v[68:71], v[204:207], v[92:95]
	v_mfma_f32_16x16x32_bf16 v[88:91], v[76:79], v[204:207], v[88:91]
	s_setprio 0
	s_setprio 1
	v_mfma_f32_16x16x32_bf16 v[132:135], v[144:147], v[176:179], v[132:135]
	v_mfma_f32_16x16x32_bf16 v[128:131], v[152:155], v[176:179], v[128:131]
	v_mfma_f32_16x16x32_bf16 v[116:119], v[144:147], v[184:187], v[116:119]
	v_mfma_f32_16x16x32_bf16 v[112:115], v[152:155], v[184:187], v[112:115]
	v_mfma_f32_16x16x32_bf16 v[100:103], v[144:147], v[192:195], v[100:103]
	v_mfma_f32_16x16x32_bf16 v[96:99], v[152:155], v[192:195], v[96:99]
	v_mfma_f32_16x16x32_bf16 v[84:87], v[144:147], v[200:203], v[84:87]
	v_mfma_f32_16x16x32_bf16 v[80:83], v[152:155], v[200:203], v[80:83]
	v_mfma_f32_16x16x32_bf16 v[132:135], v[148:151], v[180:183], v[132:135]
	v_mfma_f32_16x16x32_bf16 v[128:131], v[156:159], v[180:183], v[128:131]
	v_mfma_f32_16x16x32_bf16 v[116:119], v[148:151], v[188:191], v[116:119]
	v_mfma_f32_16x16x32_bf16 v[112:115], v[156:159], v[188:191], v[112:115]
	v_mfma_f32_16x16x32_bf16 v[100:103], v[148:151], v[196:199], v[100:103]
	v_mfma_f32_16x16x32_bf16 v[96:99], v[156:159], v[196:199], v[96:99]
	v_mfma_f32_16x16x32_bf16 v[84:87], v[148:151], v[204:207], v[84:87]
	v_mfma_f32_16x16x32_bf16 v[80:83], v[156:159], v[204:207], v[80:83]
	s_setprio 0
	s_barrier
	s_add_i32 s82, s75, s64
	s_mov_b64 s[96:97], s[60:61]
	s_nop 0
	s_mov_b32 m0, s82
	ds_read_b128 v[176:179], v215 offset:16384
	ds_read_b128 v[180:183], v215 offset:17408
	ds_read_b128 v[184:187], v215 offset:18432
	ds_read_b128 v[188:191], v215 offset:19456
	ds_read_b128 v[192:195], v215 offset:20480
	ds_read_b128 v[196:199], v215 offset:21504
	ds_read_b128 v[200:203], v215 offset:22528
	ds_read_b128 v[204:207], v215 offset:23552
	global_load_lds_dwordx4 v162, s[60:61]
	s_add_i32 m0, s82, 0x2000
	s_add_u32 s82, s60, 0x80000
	s_nop 0
	s_addc_u32 s83, s61, 0
	s_add_i32 s84, s76, s64
	global_load_lds_dwordx4 v166, s[60:61]
	s_nop 0
	s_mov_b32 m0, s84
	s_nop 0
	global_load_lds_dwordx4 v162, s[82:83]
	s_nop 0
	s_add_i32 m0, s84, 0x2000
	s_nop 0
	global_load_lds_dwordx4 v166, s[82:83]
	s_mov_b64 s[98:99], s[62:63]
	s_nop 0
	s_mov_b32 m0, s57
	s_nop 0
	global_load_lds_dwordx4 v160, s[62:63]
	s_mov_b32 m0, s65
	s_nop 0
	global_load_lds_dwordx4 v164, s[62:63]
	s_waitcnt vmcnt(8)
	s_waitcnt lgkmcnt(0)
	s_barrier
	s_setprio 1
	s_waitcnt lgkmcnt(0)
	v_mfma_f32_16x16x32_bf16 v[60:63], v[64:67], v[176:179], v[60:63]
	v_mfma_f32_16x16x32_bf16 v[56:59], v[72:75], v[176:179], v[56:59]
	v_mfma_f32_16x16x32_bf16 v[44:47], v[64:67], v[184:187], v[44:47]
	v_mfma_f32_16x16x32_bf16 v[40:43], v[72:75], v[184:187], v[40:43]
	v_mfma_f32_16x16x32_bf16 v[28:31], v[64:67], v[192:195], v[28:31]
	v_mfma_f32_16x16x32_bf16 v[24:27], v[72:75], v[192:195], v[24:27]
	v_mfma_f32_16x16x32_bf16 v[12:15], v[64:67], v[200:203], v[12:15]
	v_mfma_f32_16x16x32_bf16 v[8:11], v[72:75], v[200:203], v[8:11]
	v_mfma_f32_16x16x32_bf16 v[60:63], v[68:71], v[180:183], v[60:63]
	v_mfma_f32_16x16x32_bf16 v[56:59], v[76:79], v[180:183], v[56:59]
	v_mfma_f32_16x16x32_bf16 v[44:47], v[68:71], v[188:191], v[44:47]
	v_mfma_f32_16x16x32_bf16 v[40:43], v[76:79], v[188:191], v[40:43]
	v_mfma_f32_16x16x32_bf16 v[28:31], v[68:71], v[196:199], v[28:31]
	v_mfma_f32_16x16x32_bf16 v[24:27], v[76:79], v[196:199], v[24:27]
	v_mfma_f32_16x16x32_bf16 v[12:15], v[68:71], v[204:207], v[12:15]
	v_mfma_f32_16x16x32_bf16 v[8:11], v[76:79], v[204:207], v[8:11]
	s_setprio 0
	s_setprio 1
	v_mfma_f32_16x16x32_bf16 v[52:55], v[144:147], v[176:179], v[52:55]
	v_mfma_f32_16x16x32_bf16 v[48:51], v[152:155], v[176:179], v[48:51]
	v_mfma_f32_16x16x32_bf16 v[36:39], v[144:147], v[184:187], v[36:39]
	v_mfma_f32_16x16x32_bf16 v[32:35], v[152:155], v[184:187], v[32:35]
	v_mfma_f32_16x16x32_bf16 v[20:23], v[144:147], v[192:195], v[20:23]
	v_mfma_f32_16x16x32_bf16 v[16:19], v[152:155], v[192:195], v[16:19]
	v_mfma_f32_16x16x32_bf16 v[4:7], v[144:147], v[200:203], v[4:7]
	v_mfma_f32_16x16x32_bf16 v[0:3], v[152:155], v[200:203], v[0:3]
	v_mfma_f32_16x16x32_bf16 v[52:55], v[148:151], v[180:183], v[52:55]
	v_mfma_f32_16x16x32_bf16 v[48:51], v[156:159], v[180:183], v[48:51]
	v_mfma_f32_16x16x32_bf16 v[36:39], v[148:151], v[188:191], v[36:39]
	v_mfma_f32_16x16x32_bf16 v[32:35], v[156:159], v[188:191], v[32:35]
	v_mfma_f32_16x16x32_bf16 v[20:23], v[148:151], v[196:199], v[20:23]
	v_mfma_f32_16x16x32_bf16 v[16:19], v[156:159], v[196:199], v[16:19]
	v_mfma_f32_16x16x32_bf16 v[4:7], v[148:151], v[204:207], v[4:7]
	v_mfma_f32_16x16x32_bf16 v[0:3], v[156:159], v[204:207], v[0:3]
	s_setprio 0
	s_barrier
; #define PG8_STAGE(bufoff, gbase, voff) do { _Pragma("unroll") for (int _i = 0; _i < 2; ++_i) \
;         __builtin_amdgcn_global_load_lds((const unsigned*)((const char*)(gbase) + (voff)[_i]), (PG8_LAS unsigned*)(lds + (bufoff) + ldsw + _i * 8192), 16, 0, 0); } while (0)
; #define PG8_LDA(dst, b, h) do { _Pragma("unroll") for (int m = 0; m < 4; ++m) _Pragma("unroll") for (int k = 0; k < 2; ++k) dst[m][k] = *(const PG8_LAS bf16x8*)(lds + PG8_SA(b, h) + aoff + m * 2048 + k * 1024); } while (0)
; #define PG8_LDB(dst, b, h) do { _Pragma("unroll") for (int n = 0; n < 2; ++n) _Pragma("unroll") for (int k = 0; k < 2; ++k) dst[n][k] = *(const PG8_LAS bf16x8*)(lds + PG8_SB(b, h) + boff + n * 2048 + k * 1024); } while (0)
; #define PG8_MMA(ai, bj, At, Bt) do { __builtin_amdgcn_s_setprio(1); _Pragma("unroll") for (int m = 0; m < 4; ++m) _Pragma("unroll") for (int n = 0; n < 2; ++n) _Pragma("unroll") for (int k = 0; k < 2; ++k) \
;         acc[ai][bj][m][n] = __builtin_amdgcn_mfma_f32_16x16x32_bf16(Bt[n][k], At[m][k], acc[ai][bj][m][n], 0, 0, 0); __builtin_amdgcn_s_setprio(0); } while (0)
; #define PG8_WAIT_V(n) asm volatile("s_waitcnt vmcnt(" #n ")" ::: "memory")
; #define PG8_WAIT_L(n) asm volatile("s_waitcnt lgkmcnt(" #n ")" ::: "memory")
; #define PG8_BAR __builtin_amdgcn_s_barrier()
; #define PG8_SCHED __builtin_amdgcn_sched_barrier(0)
; template <class Epi, class Sched, bool ALIGN_EPI = false, bool SP2 = false>
; __device__ __forceinline__ void gemm_phase(PG8_LAS unsigned char* lds, const Gemm g, const Sched& S, const Epi& E) {
;     ...
;             PG8_LDB(B0, 1, 0); PG8_LDB(B1, 1, 1); PG8_SCHED; PG8_LDA(At, 1, 0); PG8_STAGE(PG8_SA(0, 1), a2 + hstep, voffA);
;             PG8_WAIT_V(8); PG8_WAIT_L(0); PG8_BAR; PG8_MMA(0, 0, At, B0); PG8_MMA(0, 1, At, B1); PG8_BAR; PG8_SCHED;
;             PG8_LDA(At, 1, 1); PG8_STAGE(PG8_SB(1, 0), b3, voffB); PG8_STAGE(PG8_SB(1, 1), b3 + hstep, voffB); PG8_STAGE(PG8_SA(1, 0), a3, voffA);
;             PG8_WAIT_V(8); PG8_WAIT_L(0); PG8_BAR; PG8_MMA(1, 0, At, B0); PG8_MMA(1, 1, At, B1); PG8_BAR; PG8_SCHED;
	s_add_i32 s82, 0, 0x18000
	s_add_i32 s83, 0, 0x1c000
	v_add_u32_e32 v76, s82, v211
	v_add_u32_e32 v156, s83, v211
	ds_read_b128 v[64:67], v76
	ds_read_b128 v[68:71], v76 offset:1024
	ds_read_b128 v[72:75], v76 offset:2048
	ds_read_b128 v[76:79], v76 offset:3072
	ds_read_b128 v[144:147], v156
	ds_read_b128 v[148:151], v156 offset:1024
	ds_read_b128 v[152:155], v156 offset:2048
	ds_read_b128 v[156:159], v156 offset:3072
	s_add_u32 s62, s62, 0x80000
	s_addc_u32 s63, s63, 0
	s_mov_b32 m0, s67
	s_nop 0
	ds_read_b128 v[176:179], v215 offset:32768
	ds_read_b128 v[180:183], v215 offset:33792
	ds_read_b128 v[184:187], v215 offset:34816
	ds_read_b128 v[188:191], v215 offset:35840
	ds_read_b128 v[192:195], v215 offset:36864
	ds_read_b128 v[196:199], v215 offset:37888
	ds_read_b128 v[200:203], v215 offset:38912
	ds_read_b128 v[204:207], v215 offset:39936
	global_load_lds_dwordx4 v160, s[62:63]
	s_nop 0
	s_mov_b32 m0, s68
	s_nop 0
	global_load_lds_dwordx4 v164, s[62:63]
	s_waitcnt vmcnt(8)
	s_waitcnt lgkmcnt(0)
	s_barrier
	s_setprio 1
	s_waitcnt lgkmcnt(0)
	v_mfma_f32_16x16x32_bf16 v[140:143], v[64:67], v[176:179], v[140:143]
	v_mfma_f32_16x16x32_bf16 v[136:139], v[72:75], v[176:179], v[136:139]
	v_mfma_f32_16x16x32_bf16 v[124:127], v[64:67], v[184:187], v[124:127]
	v_mfma_f32_16x16x32_bf16 v[120:123], v[72:75], v[184:187], v[120:123]
	v_mfma_f32_16x16x32_bf16 v[108:111], v[64:67], v[192:195], v[108:111]
	v_mfma_f32_16x16x32_bf16 v[104:107], v[72:75], v[192:195], v[104:107]
	v_mfma_f32_16x16x32_bf16 v[92:95], v[64:67], v[200:203], v[92:95]
	v_mfma_f32_16x16x32_bf16 v[88:91], v[72:75], v[200:203], v[88:91]
	v_mfma_f32_16x16x32_bf16 v[140:143], v[68:71], v[180:183], v[140:143]
	v_mfma_f32_16x16x32_bf16 v[136:139], v[76:79], v[180:183], v[136:139]
	v_mfma_f32_16x16x32_bf16 v[124:127], v[68:71], v[188:191], v[124:127]
	v_mfma_f32_16x16x32_bf16 v[120:123], v[76:79], v[188:191], v[120:123]
	v_mfma_f32_16x16x32_bf16 v[108:111], v[68:71], v[196:199], v[108:111]
	v_mfma_f32_16x16x32_bf16 v[104:107], v[76:79], v[196:199], v[104:107]
	v_mfma_f32_16x16x32_bf16 v[92:95], v[68:71], v[204:207], v[92:95]
	v_mfma_f32_16x16x32_bf16 v[88:91], v[76:79], v[204:207], v[88:91]
	s_setprio 0
	s_setprio 1
	v_mfma_f32_16x16x32_bf16 v[132:135], v[144:147], v[176:179], v[132:135]
	v_mfma_f32_16x16x32_bf16 v[128:131], v[152:155], v[176:179], v[128:131]
	v_mfma_f32_16x16x32_bf16 v[116:119], v[144:147], v[184:187], v[116:119]
	v_mfma_f32_16x16x32_bf16 v[112:115], v[152:155], v[184:187], v[112:115]
	v_mfma_f32_16x16x32_bf16 v[100:103], v[144:147], v[192:195], v[100:103]
	v_mfma_f32_16x16x32_bf16 v[96:99], v[152:155], v[192:195], v[96:99]
	v_mfma_f32_16x16x32_bf16 v[84:87], v[144:147], v[200:203], v[84:87]
	v_mfma_f32_16x16x32_bf16 v[80:83], v[152:155], v[200:203], v[80:83]
	v_mfma_f32_16x16x32_bf16 v[132:135], v[148:151], v[180:183], v[132:135]
	v_mfma_f32_16x16x32_bf16 v[128:131], v[156:159], v[180:183], v[128:131]
	v_mfma_f32_16x16x32_bf16 v[116:119], v[148:151], v[188:191], v[116:119]
	v_mfma_f32_16x16x32_bf16 v[112:115], v[156:159], v[188:191], v[112:115]
	v_mfma_f32_16x16x32_bf16 v[100:103], v[148:151], v[196:199], v[100:103]
	v_mfma_f32_16x16x32_bf16 v[96:99], v[156:159], v[196:199], v[96:99]
	v_mfma_f32_16x16x32_bf16 v[84:87], v[148:151], v[204:207], v[84:87]
	v_mfma_f32_16x16x32_bf16 v[80:83], v[156:159], v[204:207], v[80:83]
	s_setprio 0
	s_barrier
	s_add_i32 s62, s82, s64
	s_nop 0
	s_mov_b32 m0, s62
	ds_read_b128 v[176:179], v215 offset:49152
	ds_read_b128 v[180:183], v215 offset:50176
	ds_read_b128 v[184:187], v215 offset:51200
	ds_read_b128 v[188:191], v215 offset:52224
	ds_read_b128 v[192:195], v215 offset:53248
	ds_read_b128 v[196:199], v215 offset:54272
	ds_read_b128 v[200:203], v215 offset:55296
	ds_read_b128 v[204:207], v215 offset:56320
	global_load_lds_dwordx4 v250, s[96:97]
	s_add_i32 m0, s62, 0x2000
	s_add_u32 s60, s60, 0x80080
	s_nop 0
	s_addc_u32 s61, s61, 0
	s_add_i32 s62, s83, s64
	global_load_lds_dwordx4 v251, s[96:97]
	s_nop 0
	s_mov_b32 m0, s62
	s_nop 0
	global_load_lds_dwordx4 v162, s[60:61]
	s_nop 0
	s_add_i32 m0, s62, 0x2000
	s_nop 0
	global_load_lds_dwordx4 v166, s[60:61]
	s_nop 0
	s_mov_b32 m0, s70
	s_nop 0
	global_load_lds_dwordx4 v252, s[98:99]
	s_nop 0
	s_mov_b32 m0, s71
	s_nop 0
	global_load_lds_dwordx4 v253, s[98:99]
	s_waitcnt vmcnt(8)
	s_waitcnt lgkmcnt(0)
	s_barrier
	s_setprio 1
	s_waitcnt lgkmcnt(0)
	v_mfma_f32_16x16x32_bf16 v[60:63], v[64:67], v[176:179], v[60:63]
	v_mfma_f32_16x16x32_bf16 v[56:59], v[72:75], v[176:179], v[56:59]
	v_mfma_f32_16x16x32_bf16 v[44:47], v[64:67], v[184:187], v[44:47]
	v_mfma_f32_16x16x32_bf16 v[40:43], v[72:75], v[184:187], v[40:43]
	v_mfma_f32_16x16x32_bf16 v[28:31], v[64:67], v[192:195], v[28:31]
	v_mfma_f32_16x16x32_bf16 v[24:27], v[72:75], v[192:195], v[24:27]
	v_mfma_f32_16x16x32_bf16 v[12:15], v[64:67], v[200:203], v[12:15]
	v_mfma_f32_16x16x32_bf16 v[8:11], v[72:75], v[200:203], v[8:11]
	v_mfma_f32_16x16x32_bf16 v[60:63], v[68:71], v[180:183], v[60:63]
	v_mfma_f32_16x16x32_bf16 v[56:59], v[76:79], v[180:183], v[56:59]
	v_mfma_f32_16x16x32_bf16 v[44:47], v[68:71], v[188:191], v[44:47]
	v_mfma_f32_16x16x32_bf16 v[40:43], v[76:79], v[188:191], v[40:43]
	v_mfma_f32_16x16x32_bf16 v[28:31], v[68:71], v[196:199], v[28:31]
	v_mfma_f32_16x16x32_bf16 v[24:27], v[76:79], v[196:199], v[24:27]
	v_mfma_f32_16x16x32_bf16 v[12:15], v[68:71], v[204:207], v[12:15]
	v_mfma_f32_16x16x32_bf16 v[8:11], v[76:79], v[204:207], v[8:11]
	s_setprio 0
	s_setprio 1
	v_mfma_f32_16x16x32_bf16 v[52:55], v[144:147], v[176:179], v[52:55]
	v_mfma_f32_16x16x32_bf16 v[48:51], v[152:155], v[176:179], v[48:51]
	v_mfma_f32_16x16x32_bf16 v[36:39], v[144:147], v[184:187], v[36:39]
	v_mfma_f32_16x16x32_bf16 v[32:35], v[152:155], v[184:187], v[32:35]
	v_mfma_f32_16x16x32_bf16 v[20:23], v[144:147], v[192:195], v[20:23]
	v_mfma_f32_16x16x32_bf16 v[16:19], v[152:155], v[192:195], v[16:19]
	v_mfma_f32_16x16x32_bf16 v[4:7], v[144:147], v[200:203], v[4:7]
	v_mfma_f32_16x16x32_bf16 v[0:3], v[152:155], v[200:203], v[0:3]
	v_mfma_f32_16x16x32_bf16 v[52:55], v[148:151], v[180:183], v[52:55]
	v_mfma_f32_16x16x32_bf16 v[48:51], v[156:159], v[180:183], v[48:51]
	v_mfma_f32_16x16x32_bf16 v[36:39], v[148:151], v[188:191], v[36:39]
	v_mfma_f32_16x16x32_bf16 v[32:35], v[156:159], v[188:191], v[32:35]
	v_mfma_f32_16x16x32_bf16 v[20:23], v[148:151], v[196:199], v[20:23]
	v_mfma_f32_16x16x32_bf16 v[16:19], v[156:159], v[196:199], v[16:19]
	v_mfma_f32_16x16x32_bf16 v[4:7], v[148:151], v[204:207], v[4:7]
	v_mfma_f32_16x16x32_bf16 v[0:3], v[156:159], v[204:207], v[0:3]
	s_setprio 0
	s_barrier
	s_add_i32 s81, s81, 2
	s_add_u32 s58, s58, 0x100
	s_addc_u32 s59, s59, 0
	s_add_u32 s79, s79, 0x100
	s_addc_u32 s80, s80, 0
	s_cmp_gt_u32 s81, 29
	s_cbranch_scc0 .LBB0_939
	s_and_b64 vcc, exec, s[42:43]
	s_cbranch_vccz .LBB0_942
	s_barrier

; #define PG8_STAGE(bufoff, gbase, voff) do { _Pragma("unroll") for (int _i = 0; _i < 2; ++_i) \
;         __builtin_amdgcn_global_load_lds((const unsigned*)((const char*)(gbase) + (voff)[_i]), (PG8_LAS unsigned*)(lds + (bufoff) + ldsw + _i * 8192), 16, 0, 0); } while (0)
; #define PG8_LDA(dst, b, h) do { _Pragma("unroll") for (int m = 0; m < 4; ++m) _Pragma("unroll") for (int k = 0; k < 2; ++k) dst[m][k] = *(const PG8_LAS bf16x8*)(lds + PG8_SA(b, h) + aoff + m * 2048 + k * 1024); } while (0)
; #define PG8_LDB(dst, b, h) do { _Pragma("unroll") for (int n = 0; n < 2; ++n) _Pragma("unroll") for (int k = 0; k < 2; ++k) dst[n][k] = *(const PG8_LAS bf16x8*)(lds + PG8_SB(b, h) + boff + n * 2048 + k * 1024); } while (0)
; #define PG8_WAIT_V(n) asm volatile("s_waitcnt vmcnt(" #n ")" ::: "memory")
; #define PG8_WAIT_L(n) asm volatile("s_waitcnt lgkmcnt(" #n ")" ::: "memory")
; #define PG8_BAR __builtin_amdgcn_s_barrier()
; #define PG8_SCHED __builtin_amdgcn_sched_barrier(0)
; template <class Epi, class Sched, bool ALIGN_EPI = false, bool SP2 = false>
; __device__ __forceinline__ void gemm_phase(PG8_LAS unsigned char* lds, const Gemm g, const Sched& S, const Epi& E) {
;     ...
;         const bool has_next = S.next(ui + 1, nxt);
;         const char* nA = has_next ? (const char*)g.A + (size_t)nxt.pm * tstep : cA; const char* nB = has_next ? (const char*)g.Bt + (size_t)nxt.pn * tstep : cB;
;         for (int t = 0; t < nt; t += 2) {
;             const bool last = (t == nt - 2);
;             const char* a1 = cA + (size_t)(t + 1) * kstep;
;             const char* a2 = last ? nA : cA + (size_t)(t + 2) * kstep; const char* b2 = last ? nB : cB + (size_t)(t + 2) * kstep;
;             const char* a3 = a2 + kstep; const char* b3 = b2 + kstep;
;             if (last && has_next) S.a_ready(nxt);
;             if constexpr (SP2) {
;             PG8_LDB(B0, 0, 0); PG8_LDB(B1, 0, 1); PG8_SCHED; PG8_LDA(At, 0, 0); PG8_STAGE(PG8_SA(1, 1), a1 + hstep, voffA);
;             PG8_WAIT_V(8); PG8_WAIT_L(0); PG8_BAR; PG8_MMA(0, 0, At, B0); PG8_MMA(0, 1, At, B1); PG8_BAR; PG8_SCHED;
;     ...
;         for (int a = 0; a < 2; ++a)
; #pragma unroll
;             for (int b = 0; b < 2; ++b)
; #pragma unroll
;                 for (int m = 0; m < 4; ++m)
; #pragma unroll
;                     for (int n = 0; n < 2; ++n) acc[a][b][m][n] = (f32x4){0.f, 0.f, 0.f, 0.f};
.LBB0_1033:
	s_ashr_i32 s53, s52, 31
	s_lshl_b64 s[54:55], s[52:53], 20
	s_add_u32 s54, s24, s54
	s_addc_u32 s55, s25, s55
	s_and_b64 s[56:57], s[4:5], exec
	s_cselect_b32 s53, s55, s11
	s_cselect_b32 s79, s54, s10
	s_ashr_i32 s51, s50, 31
	s_lshl_b64 s[56:57], s[50:51], 20
	s_add_u32 s56, s60, s56
	s_addc_u32 s57, s61, s57
	s_and_b64 s[58:59], s[4:5], exec
	s_cselect_b32 s51, s57, s13
	s_cselect_b32 s80, s56, s12
	s_add_u32 s10, s10, 0x80080
	s_addc_u32 s11, s11, 0
	s_add_u32 s81, s12, 0x100
	v_mov_b32_e32 v0, 0
	s_addc_u32 s82, s13, 0
	s_mov_b32 s83, -2
	v_mov_b32_e32 v1, v0
	v_mov_b32_e32 v2, v0
	v_mov_b32_e32 v3, v0
	v_mov_b32_e32 v4, v0
	v_mov_b32_e32 v5, v0
	v_mov_b32_e32 v6, v0
	v_mov_b32_e32 v7, v0
	v_mov_b32_e32 v16, v0
	v_mov_b32_e32 v17, v0
	v_mov_b32_e32 v18, v0
	v_mov_b32_e32 v19, v0
	v_mov_b32_e32 v20, v0
	v_mov_b32_e32 v21, v0
	v_mov_b32_e32 v22, v0
	v_mov_b32_e32 v23, v0
	v_mov_b32_e32 v32, v0
	v_mov_b32_e32 v33, v0
	v_mov_b32_e32 v34, v0
	v_mov_b32_e32 v35, v0
	v_mov_b32_e32 v36, v0
	v_mov_b32_e32 v37, v0
	v_mov_b32_e32 v38, v0
	v_mov_b32_e32 v39, v0
	v_mov_b32_e32 v48, v0
	v_mov_b32_e32 v49, v0
	v_mov_b32_e32 v50, v0
	v_mov_b32_e32 v51, v0
	v_mov_b32_e32 v52, v0
	v_mov_b32_e32 v53, v0
	v_mov_b32_e32 v54, v0
	v_mov_b32_e32 v55, v0
	v_mov_b32_e32 v8, v0
	v_mov_b32_e32 v9, v0
	v_mov_b32_e32 v10, v0
	v_mov_b32_e32 v11, v0
	v_mov_b32_e32 v12, v0
	v_mov_b32_e32 v13, v0
	v_mov_b32_e32 v14, v0
	v_mov_b32_e32 v15, v0
	v_mov_b32_e32 v24, v0
	v_mov_b32_e32 v25, v0
	v_mov_b32_e32 v26, v0
	v_mov_b32_e32 v27, v0
	v_mov_b32_e32 v28, v0
	v_mov_b32_e32 v29, v0
	v_mov_b32_e32 v30, v0
	v_mov_b32_e32 v31, v0
	v_mov_b32_e32 v40, v0
	v_mov_b32_e32 v41, v0
	v_mov_b32_e32 v42, v0
	v_mov_b32_e32 v43, v0
	v_mov_b32_e32 v44, v0
	v_mov_b32_e32 v45, v0
	v_mov_b32_e32 v46, v0
	v_mov_b32_e32 v47, v0
	v_mov_b32_e32 v56, v0
	v_mov_b32_e32 v57, v0
	v_mov_b32_e32 v58, v0
	v_mov_b32_e32 v59, v0
	v_mov_b32_e32 v60, v0
	v_mov_b32_e32 v61, v0
	v_mov_b32_e32 v62, v0
	v_mov_b32_e32 v63, v0
	v_mov_b32_e32 v64, v0
	v_mov_b32_e32 v65, v0
	v_mov_b32_e32 v66, v0
	v_mov_b32_e32 v67, v0
	v_mov_b32_e32 v68, v0
	v_mov_b32_e32 v69, v0
	v_mov_b32_e32 v70, v0
	v_mov_b32_e32 v71, v0
	v_mov_b32_e32 v80, v0
	v_mov_b32_e32 v81, v0
	v_mov_b32_e32 v82, v0
	v_mov_b32_e32 v83, v0
	v_mov_b32_e32 v84, v0
	v_mov_b32_e32 v85, v0
	v_mov_b32_e32 v86, v0
	v_mov_b32_e32 v87, v0
	v_mov_b32_e32 v96, v0
	v_mov_b32_e32 v97, v0
	v_mov_b32_e32 v98, v0
	v_mov_b32_e32 v99, v0
	v_mov_b32_e32 v100, v0
	v_mov_b32_e32 v101, v0
	v_mov_b32_e32 v102, v0
	v_mov_b32_e32 v103, v0
	v_mov_b32_e32 v112, v0
	v_mov_b32_e32 v113, v0
	v_mov_b32_e32 v114, v0
	v_mov_b32_e32 v115, v0
	v_mov_b32_e32 v116, v0
	v_mov_b32_e32 v117, v0
	v_mov_b32_e32 v118, v0
	v_mov_b32_e32 v119, v0
	v_mov_b32_e32 v72, v0
	v_mov_b32_e32 v73, v0
	v_mov_b32_e32 v74, v0
	v_mov_b32_e32 v75, v0
	v_mov_b32_e32 v76, v0
	v_mov_b32_e32 v77, v0
	v_mov_b32_e32 v78, v0
	v_mov_b32_e32 v79, v0
	v_mov_b32_e32 v88, v0
	v_mov_b32_e32 v89, v0
	v_mov_b32_e32 v90, v0
	v_mov_b32_e32 v91, v0
	v_mov_b32_e32 v92, v0
	v_mov_b32_e32 v93, v0
	v_mov_b32_e32 v94, v0
	v_mov_b32_e32 v95, v0
	v_mov_b32_e32 v104, v0
	v_mov_b32_e32 v105, v0
	v_mov_b32_e32 v106, v0
	v_mov_b32_e32 v107, v0
	v_mov_b32_e32 v108, v0
	v_mov_b32_e32 v109, v0
	v_mov_b32_e32 v110, v0
	v_mov_b32_e32 v111, v0
	v_mov_b32_e32 v120, v0
	v_mov_b32_e32 v121, v0
	v_mov_b32_e32 v122, v0
	v_mov_b32_e32 v123, v0
	v_mov_b32_e32 v124, v0
	v_mov_b32_e32 v125, v0
	v_mov_b32_e32 v126, v0
	v_mov_b32_e32 v127, v0
	v_add_u32_e32 v253, 0x80, v164
	v_add_u32_e32 v252, 0x80, v160
	v_add_u32_e32 v251, 0x80, v166
	v_add_u32_e32 v250, 0x80, v162
.LBB0_1034:
	ds_read_b128 v[128:131], v201
	ds_read_b128 v[132:135], v201 offset:1024
	ds_read_b128 v[136:139], v201 offset:2048
	ds_read_b128 v[140:143], v201 offset:3072
	ds_read_b128 v[144:147], v205
	ds_read_b128 v[148:151], v205 offset:1024
	ds_read_b128 v[152:155], v205 offset:2048
	ds_read_b128 v[156:159], v205 offset:3072
	s_add_u32 s12, s10, 0xfff80080
	s_addc_u32 s13, s11, -1
	s_cmp_eq_u32 s83, 28
	s_cselect_b32 s59, s53, s13
	s_cselect_b32 s58, s79, s12
	s_cselect_b32 s13, s51, s82
	s_cselect_b32 s12, s80, s81
	s_nop 0
	s_add_i32 m0, s63, 0xc000
	ds_read_b128 v[176:179], v207
	ds_read_b128 v[184:187], v207 offset:1024
	ds_read_b128 v[190:193], v207 offset:2048
	ds_read_b128 v[210:213], v207 offset:3072
	ds_read_b128 v[214:217], v207 offset:4096
	ds_read_b128 v[218:221], v207 offset:5120
	ds_read_b128 v[222:225], v207 offset:6144
	ds_read_b128 v[226:229], v207 offset:7168
	global_load_lds_dwordx4 v168, s[10:11]
	s_nop 0
	s_add_i32 m0, s63, 0xe000
	s_nop 0
	global_load_lds_dwordx4 v170, s[10:11]
	s_waitcnt vmcnt(8)
	s_waitcnt lgkmcnt(0)
	s_barrier
; #define PG8_STAGE(bufoff, gbase, voff) do { _Pragma("unroll") for (int _i = 0; _i < 2; ++_i) \
;         __builtin_amdgcn_global_load_lds((const unsigned*)((const char*)(gbase) + (voff)[_i]), (PG8_LAS unsigned*)(lds + (bufoff) + ldsw + _i * 8192), 16, 0, 0); } while (0)
; #define PG8_LDA(dst, b, h) do { _Pragma("unroll") for (int m = 0; m < 4; ++m) _Pragma("unroll") for (int k = 0; k < 2; ++k) dst[m][k] = *(const PG8_LAS bf16x8*)(lds + PG8_SA(b, h) + aoff + m * 2048 + k * 1024); } while (0)
; #define PG8_MMA(ai, bj, At, Bt) do { __builtin_amdgcn_s_setprio(1); _Pragma("unroll") for (int m = 0; m < 4; ++m) _Pragma("unroll") for (int n = 0; n < 2; ++n) _Pragma("unroll") for (int k = 0; k < 2; ++k) \
;         acc[ai][bj][m][n] = __builtin_amdgcn_mfma_f32_16x16x32_bf16(Bt[n][k], At[m][k], acc[ai][bj][m][n], 0, 0, 0); __builtin_amdgcn_s_setprio(0); } while (0)
; #define PG8_WAIT_V(n) asm volatile("s_waitcnt vmcnt(" #n ")" ::: "memory")
; #define PG8_WAIT_L(n) asm volatile("s_waitcnt lgkmcnt(" #n ")" ::: "memory")
; #define PG8_BAR __builtin_amdgcn_s_barrier()
; #define PG8_SCHED __builtin_amdgcn_sched_barrier(0)
; template <class Epi, class Sched, bool ALIGN_EPI = false, bool SP2 = false>
; __device__ __forceinline__ void gemm_phase(PG8_LAS unsigned char* lds, const Gemm g, const Sched& S, const Epi& E) {
;     ...
;             PG8_WAIT_V(8); PG8_WAIT_L(0); PG8_BAR; PG8_MMA(0, 0, At, B0); PG8_MMA(0, 1, At, B1); PG8_BAR; PG8_SCHED;
;             PG8_LDA(At, 0, 1); PG8_STAGE(PG8_SB(0, 0), b2, voffB); PG8_STAGE(PG8_SB(0, 1), b2 + hstep, voffB); PG8_STAGE(PG8_SA(0, 0), a2, voffA);
;             PG8_WAIT_V(8); PG8_WAIT_L(0); PG8_BAR; PG8_MMA(1, 0, At, B0); PG8_MMA(1, 1, At, B1); PG8_BAR; PG8_SCHED;
	s_setprio 1
	s_waitcnt lgkmcnt(0)
	v_mfma_f32_16x16x32_bf16 v[124:127], v[128:131], v[176:179], v[124:127]
	v_mfma_f32_16x16x32_bf16 v[120:123], v[136:139], v[176:179], v[120:123]
	v_mfma_f32_16x16x32_bf16 v[108:111], v[128:131], v[190:193], v[108:111]
	v_mfma_f32_16x16x32_bf16 v[104:107], v[136:139], v[190:193], v[104:107]
	v_mfma_f32_16x16x32_bf16 v[92:95], v[128:131], v[214:217], v[92:95]
	v_mfma_f32_16x16x32_bf16 v[88:91], v[136:139], v[214:217], v[88:91]
	v_mfma_f32_16x16x32_bf16 v[76:79], v[128:131], v[222:225], v[76:79]
	v_mfma_f32_16x16x32_bf16 v[72:75], v[136:139], v[222:225], v[72:75]
	v_mfma_f32_16x16x32_bf16 v[124:127], v[132:135], v[184:187], v[124:127]
	v_mfma_f32_16x16x32_bf16 v[120:123], v[140:143], v[184:187], v[120:123]
	v_mfma_f32_16x16x32_bf16 v[108:111], v[132:135], v[210:213], v[108:111]
	v_mfma_f32_16x16x32_bf16 v[104:107], v[140:143], v[210:213], v[104:107]
	v_mfma_f32_16x16x32_bf16 v[92:95], v[132:135], v[218:221], v[92:95]
	v_mfma_f32_16x16x32_bf16 v[88:91], v[140:143], v[218:221], v[88:91]
	v_mfma_f32_16x16x32_bf16 v[76:79], v[132:135], v[226:229], v[76:79]
	v_mfma_f32_16x16x32_bf16 v[72:75], v[140:143], v[226:229], v[72:75]
	s_setprio 0
	s_setprio 1
	v_mfma_f32_16x16x32_bf16 v[116:119], v[144:147], v[176:179], v[116:119]
	v_mfma_f32_16x16x32_bf16 v[112:115], v[152:155], v[176:179], v[112:115]
	v_mfma_f32_16x16x32_bf16 v[100:103], v[144:147], v[190:193], v[100:103]
	v_mfma_f32_16x16x32_bf16 v[96:99], v[152:155], v[190:193], v[96:99]
	v_mfma_f32_16x16x32_bf16 v[84:87], v[144:147], v[214:217], v[84:87]
	v_mfma_f32_16x16x32_bf16 v[80:83], v[152:155], v[214:217], v[80:83]
	v_mfma_f32_16x16x32_bf16 v[68:71], v[144:147], v[222:225], v[68:71]
	v_mfma_f32_16x16x32_bf16 v[64:67], v[152:155], v[222:225], v[64:67]
	v_mfma_f32_16x16x32_bf16 v[116:119], v[148:151], v[184:187], v[116:119]
	v_mfma_f32_16x16x32_bf16 v[112:115], v[156:159], v[184:187], v[112:115]
	v_mfma_f32_16x16x32_bf16 v[100:103], v[148:151], v[210:213], v[100:103]
	v_mfma_f32_16x16x32_bf16 v[96:99], v[156:159], v[210:213], v[96:99]
	v_mfma_f32_16x16x32_bf16 v[84:87], v[148:151], v[218:221], v[84:87]
	v_mfma_f32_16x16x32_bf16 v[80:83], v[156:159], v[218:221], v[80:83]
	v_mfma_f32_16x16x32_bf16 v[68:71], v[148:151], v[226:229], v[68:71]
	v_mfma_f32_16x16x32_bf16 v[64:67], v[156:159], v[226:229], v[64:67]
	s_setprio 0
	s_barrier
	s_add_i32 s84, s73, s62
	s_mov_b64 s[96:97], s[12:13]
	s_nop 0
	s_mov_b32 m0, s84
	ds_read_b128 v[176:179], v207 offset:16384
	ds_read_b128 v[184:187], v207 offset:17408
	ds_read_b128 v[190:193], v207 offset:18432
	ds_read_b128 v[210:213], v207 offset:19456
	ds_read_b128 v[214:217], v207 offset:20480
	ds_read_b128 v[218:221], v207 offset:21504
	ds_read_b128 v[222:225], v207 offset:22528
	ds_read_b128 v[226:229], v207 offset:23552
	global_load_lds_dwordx4 v162, s[12:13]
	s_add_i32 m0, s84, 0x2000
	s_add_u32 s84, s12, 0x80000
	s_nop 0
	s_addc_u32 s85, s13, 0
	s_add_i32 s86, s74, s62
	global_load_lds_dwordx4 v166, s[12:13]
	s_nop 0
	s_mov_b32 m0, s86
	s_nop 0
	global_load_lds_dwordx4 v162, s[84:85]
	s_nop 0
	s_add_i32 m0, s86, 0x2000
	s_nop 0
	global_load_lds_dwordx4 v166, s[84:85]
	s_mov_b64 s[98:99], s[58:59]
	s_nop 0
	s_mov_b32 m0, s63
	s_nop 0
	global_load_lds_dwordx4 v160, s[58:59]
	s_mov_b32 m0, s64
	s_nop 0
	global_load_lds_dwordx4 v164, s[58:59]
	s_waitcnt vmcnt(8)
	s_waitcnt lgkmcnt(0)
	s_barrier
	s_setprio 1
	s_waitcnt lgkmcnt(0)
	v_mfma_f32_16x16x32_bf16 v[60:63], v[128:131], v[176:179], v[60:63]
	v_mfma_f32_16x16x32_bf16 v[56:59], v[136:139], v[176:179], v[56:59]
	v_mfma_f32_16x16x32_bf16 v[44:47], v[128:131], v[190:193], v[44:47]
	v_mfma_f32_16x16x32_bf16 v[40:43], v[136:139], v[190:193], v[40:43]
	v_mfma_f32_16x16x32_bf16 v[28:31], v[128:131], v[214:217], v[28:31]
	v_mfma_f32_16x16x32_bf16 v[24:27], v[136:139], v[214:217], v[24:27]
	v_mfma_f32_16x16x32_bf16 v[12:15], v[128:131], v[222:225], v[12:15]
	v_mfma_f32_16x16x32_bf16 v[8:11], v[136:139], v[222:225], v[8:11]
	v_mfma_f32_16x16x32_bf16 v[60:63], v[132:135], v[184:187], v[60:63]
	v_mfma_f32_16x16x32_bf16 v[56:59], v[140:143], v[184:187], v[56:59]
	v_mfma_f32_16x16x32_bf16 v[44:47], v[132:135], v[210:213], v[44:47]
	v_mfma_f32_16x16x32_bf16 v[40:43], v[140:143], v[210:213], v[40:43]
	v_mfma_f32_16x16x32_bf16 v[28:31], v[132:135], v[218:221], v[28:31]
	v_mfma_f32_16x16x32_bf16 v[24:27], v[140:143], v[218:221], v[24:27]
	v_mfma_f32_16x16x32_bf16 v[12:15], v[132:135], v[226:229], v[12:15]
	v_mfma_f32_16x16x32_bf16 v[8:11], v[140:143], v[226:229], v[8:11]
	s_setprio 0
	s_setprio 1
	v_mfma_f32_16x16x32_bf16 v[52:55], v[144:147], v[176:179], v[52:55]
	v_mfma_f32_16x16x32_bf16 v[48:51], v[152:155], v[176:179], v[48:51]
	v_mfma_f32_16x16x32_bf16 v[36:39], v[144:147], v[190:193], v[36:39]
	v_mfma_f32_16x16x32_bf16 v[32:35], v[152:155], v[190:193], v[32:35]
	v_mfma_f32_16x16x32_bf16 v[20:23], v[144:147], v[214:217], v[20:23]
	v_mfma_f32_16x16x32_bf16 v[16:19], v[152:155], v[214:217], v[16:19]
	v_mfma_f32_16x16x32_bf16 v[4:7], v[144:147], v[222:225], v[4:7]
	v_mfma_f32_16x16x32_bf16 v[0:3], v[152:155], v[222:225], v[0:3]
	v_mfma_f32_16x16x32_bf16 v[52:55], v[148:151], v[184:187], v[52:55]
	v_mfma_f32_16x16x32_bf16 v[48:51], v[156:159], v[184:187], v[48:51]
	v_mfma_f32_16x16x32_bf16 v[36:39], v[148:151], v[210:213], v[36:39]
	v_mfma_f32_16x16x32_bf16 v[32:35], v[156:159], v[210:213], v[32:35]
	v_mfma_f32_16x16x32_bf16 v[20:23], v[148:151], v[218:221], v[20:23]
	v_mfma_f32_16x16x32_bf16 v[16:19], v[156:159], v[218:221], v[16:19]
	v_mfma_f32_16x16x32_bf16 v[4:7], v[148:151], v[226:229], v[4:7]
	v_mfma_f32_16x16x32_bf16 v[0:3], v[156:159], v[226:229], v[0:3]
	s_setprio 0
	s_barrier
; #define PG8_STAGE(bufoff, gbase, voff) do { _Pragma("unroll") for (int _i = 0; _i < 2; ++_i) \
;         __builtin_amdgcn_global_load_lds((const unsigned*)((const char*)(gbase) + (voff)[_i]), (PG8_LAS unsigned*)(lds + (bufoff) + ldsw + _i * 8192), 16, 0, 0); } while (0)
; #define PG8_LDA(dst, b, h) do { _Pragma("unroll") for (int m = 0; m < 4; ++m) _Pragma("unroll") for (int k = 0; k < 2; ++k) dst[m][k] = *(const PG8_LAS bf16x8*)(lds + PG8_SA(b, h) + aoff + m * 2048 + k * 1024); } while (0)
; #define PG8_LDB(dst, b, h) do { _Pragma("unroll") for (int n = 0; n < 2; ++n) _Pragma("unroll") for (int k = 0; k < 2; ++k) dst[n][k] = *(const PG8_LAS bf16x8*)(lds + PG8_SB(b, h) + boff + n * 2048 + k * 1024); } while (0)
; #define PG8_MMA(ai, bj, At, Bt) do { __builtin_amdgcn_s_setprio(1); _Pragma("unroll") for (int m = 0; m < 4; ++m) _Pragma("unroll") for (int n = 0; n < 2; ++n) _Pragma("unroll") for (int k = 0; k < 2; ++k) \
;         acc[ai][bj][m][n] = __builtin_amdgcn_mfma_f32_16x16x32_bf16(Bt[n][k], At[m][k], acc[ai][bj][m][n], 0, 0, 0); __builtin_amdgcn_s_setprio(0); } while (0)
; #define PG8_WAIT_V(n) asm volatile("s_waitcnt vmcnt(" #n ")" ::: "memory")
; #define PG8_WAIT_L(n) asm volatile("s_waitcnt lgkmcnt(" #n ")" ::: "memory")
; #define PG8_BAR __builtin_amdgcn_s_barrier()
; #define PG8_SCHED __builtin_amdgcn_sched_barrier(0)
; template <class Epi, class Sched, bool ALIGN_EPI = false, bool SP2 = false>
; __device__ __forceinline__ void gemm_phase(PG8_LAS unsigned char* lds, const Gemm g, const Sched& S, const Epi& E) {
;     ...
;             PG8_LDB(B0, 1, 0); PG8_LDB(B1, 1, 1); PG8_SCHED; PG8_LDA(At, 1, 0); PG8_STAGE(PG8_SA(0, 1), a2 + hstep, voffA);
;             PG8_WAIT_V(8); PG8_WAIT_L(0); PG8_BAR; PG8_MMA(0, 0, At, B0); PG8_MMA(0, 1, At, B1); PG8_BAR; PG8_SCHED;
;             PG8_LDA(At, 1, 1); PG8_STAGE(PG8_SB(1, 0), b3, voffB); PG8_STAGE(PG8_SB(1, 1), b3 + hstep, voffB); PG8_STAGE(PG8_SA(1, 0), a3, voffA);
;             PG8_WAIT_V(8); PG8_WAIT_L(0); PG8_BAR; PG8_MMA(1, 0, At, B0); PG8_MMA(1, 1, At, B1); PG8_BAR; PG8_SCHED;
	s_add_i32 s84, 0, 0x18000
	s_add_i32 s85, 0, 0x1c000
	v_add_u32_e32 v140, s84, v189
	v_add_u32_e32 v156, s85, v189
	ds_read_b128 v[128:131], v140
	ds_read_b128 v[132:135], v140 offset:1024
	ds_read_b128 v[136:139], v140 offset:2048
	ds_read_b128 v[140:143], v140 offset:3072
	ds_read_b128 v[144:147], v156
	ds_read_b128 v[148:151], v156 offset:1024
	ds_read_b128 v[152:155], v156 offset:2048
	ds_read_b128 v[156:159], v156 offset:3072
	s_add_u32 s58, s58, 0x80000
	s_addc_u32 s59, s59, 0
	s_mov_b32 m0, s65
	s_nop 0
	ds_read_b128 v[176:179], v207 offset:32768
	ds_read_b128 v[184:187], v207 offset:33792
	ds_read_b128 v[190:193], v207 offset:34816
	ds_read_b128 v[210:213], v207 offset:35840
	ds_read_b128 v[214:217], v207 offset:36864
	ds_read_b128 v[218:221], v207 offset:37888
	ds_read_b128 v[222:225], v207 offset:38912
	ds_read_b128 v[226:229], v207 offset:39936
	global_load_lds_dwordx4 v160, s[58:59]
	s_nop 0
	s_mov_b32 m0, s67
	s_nop 0
	global_load_lds_dwordx4 v164, s[58:59]
	s_waitcnt vmcnt(8)
	s_waitcnt lgkmcnt(0)
	s_barrier
	s_setprio 1
	s_waitcnt lgkmcnt(0)
	v_mfma_f32_16x16x32_bf16 v[124:127], v[128:131], v[176:179], v[124:127]
	v_mfma_f32_16x16x32_bf16 v[120:123], v[136:139], v[176:179], v[120:123]
	v_mfma_f32_16x16x32_bf16 v[108:111], v[128:131], v[190:193], v[108:111]
	v_mfma_f32_16x16x32_bf16 v[104:107], v[136:139], v[190:193], v[104:107]
	v_mfma_f32_16x16x32_bf16 v[92:95], v[128:131], v[214:217], v[92:95]
	v_mfma_f32_16x16x32_bf16 v[88:91], v[136:139], v[214:217], v[88:91]
	v_mfma_f32_16x16x32_bf16 v[76:79], v[128:131], v[222:225], v[76:79]
	v_mfma_f32_16x16x32_bf16 v[72:75], v[136:139], v[222:225], v[72:75]
	v_mfma_f32_16x16x32_bf16 v[124:127], v[132:135], v[184:187], v[124:127]
	v_mfma_f32_16x16x32_bf16 v[120:123], v[140:143], v[184:187], v[120:123]
	v_mfma_f32_16x16x32_bf16 v[108:111], v[132:135], v[210:213], v[108:111]
	v_mfma_f32_16x16x32_bf16 v[104:107], v[140:143], v[210:213], v[104:107]
	v_mfma_f32_16x16x32_bf16 v[92:95], v[132:135], v[218:221], v[92:95]
	v_mfma_f32_16x16x32_bf16 v[88:91], v[140:143], v[218:221], v[88:91]
	v_mfma_f32_16x16x32_bf16 v[76:79], v[132:135], v[226:229], v[76:79]
	v_mfma_f32_16x16x32_bf16 v[72:75], v[140:143], v[226:229], v[72:75]
	s_setprio 0
	s_setprio 1
	v_mfma_f32_16x16x32_bf16 v[116:119], v[144:147], v[176:179], v[116:119]
	v_mfma_f32_16x16x32_bf16 v[112:115], v[152:155], v[176:179], v[112:115]
	v_mfma_f32_16x16x32_bf16 v[100:103], v[144:147], v[190:193], v[100:103]
	v_mfma_f32_16x16x32_bf16 v[96:99], v[152:155], v[190:193], v[96:99]
	v_mfma_f32_16x16x32_bf16 v[84:87], v[144:147], v[214:217], v[84:87]
	v_mfma_f32_16x16x32_bf16 v[80:83], v[152:155], v[214:217], v[80:83]
	v_mfma_f32_16x16x32_bf16 v[68:71], v[144:147], v[222:225], v[68:71]
	v_mfma_f32_16x16x32_bf16 v[64:67], v[152:155], v[222:225], v[64:67]
	v_mfma_f32_16x16x32_bf16 v[116:119], v[148:151], v[184:187], v[116:119]
	v_mfma_f32_16x16x32_bf16 v[112:115], v[156:159], v[184:187], v[112:115]
	v_mfma_f32_16x16x32_bf16 v[100:103], v[148:151], v[210:213], v[100:103]
	v_mfma_f32_16x16x32_bf16 v[96:99], v[156:159], v[210:213], v[96:99]
	v_mfma_f32_16x16x32_bf16 v[84:87], v[148:151], v[218:221], v[84:87]
	v_mfma_f32_16x16x32_bf16 v[80:83], v[156:159], v[218:221], v[80:83]
	v_mfma_f32_16x16x32_bf16 v[68:71], v[148:151], v[226:229], v[68:71]
	v_mfma_f32_16x16x32_bf16 v[64:67], v[156:159], v[226:229], v[64:67]
	s_setprio 0
	s_barrier
	s_add_i32 s58, s84, s62
	s_nop 0
	s_mov_b32 m0, s58
	ds_read_b128 v[176:179], v207 offset:49152
	ds_read_b128 v[184:187], v207 offset:50176
	ds_read_b128 v[190:193], v207 offset:51200
	ds_read_b128 v[210:213], v207 offset:52224
	ds_read_b128 v[214:217], v207 offset:53248
	ds_read_b128 v[218:221], v207 offset:54272
	ds_read_b128 v[222:225], v207 offset:55296
	ds_read_b128 v[226:229], v207 offset:56320
	global_load_lds_dwordx4 v250, s[96:97]
	s_add_i32 m0, s58, 0x2000
	s_add_u32 s12, s12, 0x80080
	s_nop 0
	s_addc_u32 s13, s13, 0
	s_add_i32 s58, s85, s62
	global_load_lds_dwordx4 v251, s[96:97]
	s_nop 0
	s_mov_b32 m0, s58
	s_nop 0
	global_load_lds_dwordx4 v162, s[12:13]
	s_nop 0
	s_add_i32 m0, s58, 0x2000
	s_nop 0
	global_load_lds_dwordx4 v166, s[12:13]
	s_nop 0
	s_mov_b32 m0, s69
	s_nop 0
	global_load_lds_dwordx4 v252, s[98:99]
	s_nop 0
	s_mov_b32 m0, s70
	s_nop 0
	global_load_lds_dwordx4 v253, s[98:99]
	s_waitcnt vmcnt(8)
	s_waitcnt lgkmcnt(0)
	s_barrier
	s_setprio 1
	s_waitcnt lgkmcnt(0)
	v_mfma_f32_16x16x32_bf16 v[60:63], v[128:131], v[176:179], v[60:63]
	v_mfma_f32_16x16x32_bf16 v[56:59], v[136:139], v[176:179], v[56:59]
	v_mfma_f32_16x16x32_bf16 v[44:47], v[128:131], v[190:193], v[44:47]
	v_mfma_f32_16x16x32_bf16 v[40:43], v[136:139], v[190:193], v[40:43]
	v_mfma_f32_16x16x32_bf16 v[28:31], v[128:131], v[214:217], v[28:31]
	v_mfma_f32_16x16x32_bf16 v[24:27], v[136:139], v[214:217], v[24:27]
	v_mfma_f32_16x16x32_bf16 v[12:15], v[128:131], v[222:225], v[12:15]
	v_mfma_f32_16x16x32_bf16 v[8:11], v[136:139], v[222:225], v[8:11]
	v_mfma_f32_16x16x32_bf16 v[60:63], v[132:135], v[184:187], v[60:63]
	v_mfma_f32_16x16x32_bf16 v[56:59], v[140:143], v[184:187], v[56:59]
	v_mfma_f32_16x16x32_bf16 v[44:47], v[132:135], v[210:213], v[44:47]
	v_mfma_f32_16x16x32_bf16 v[40:43], v[140:143], v[210:213], v[40:43]
	v_mfma_f32_16x16x32_bf16 v[28:31], v[132:135], v[218:221], v[28:31]
	v_mfma_f32_16x16x32_bf16 v[24:27], v[140:143], v[218:221], v[24:27]
	v_mfma_f32_16x16x32_bf16 v[12:15], v[132:135], v[226:229], v[12:15]
	v_mfma_f32_16x16x32_bf16 v[8:11], v[140:143], v[226:229], v[8:11]
	s_setprio 0
	s_setprio 1
	v_mfma_f32_16x16x32_bf16 v[52:55], v[144:147], v[176:179], v[52:55]
	v_mfma_f32_16x16x32_bf16 v[48:51], v[152:155], v[176:179], v[48:51]
	v_mfma_f32_16x16x32_bf16 v[36:39], v[144:147], v[190:193], v[36:39]
	v_mfma_f32_16x16x32_bf16 v[32:35], v[152:155], v[190:193], v[32:35]
	v_mfma_f32_16x16x32_bf16 v[20:23], v[144:147], v[214:217], v[20:23]
	v_mfma_f32_16x16x32_bf16 v[16:19], v[152:155], v[214:217], v[16:19]
	v_mfma_f32_16x16x32_bf16 v[4:7], v[144:147], v[222:225], v[4:7]
	v_mfma_f32_16x16x32_bf16 v[0:3], v[152:155], v[222:225], v[0:3]
	v_mfma_f32_16x16x32_bf16 v[52:55], v[148:151], v[184:187], v[52:55]
	v_mfma_f32_16x16x32_bf16 v[48:51], v[156:159], v[184:187], v[48:51]
	v_mfma_f32_16x16x32_bf16 v[36:39], v[148:151], v[210:213], v[36:39]
	v_mfma_f32_16x16x32_bf16 v[32:35], v[156:159], v[210:213], v[32:35]
	v_mfma_f32_16x16x32_bf16 v[20:23], v[148:151], v[218:221], v[20:23]
	v_mfma_f32_16x16x32_bf16 v[16:19], v[156:159], v[218:221], v[16:19]
	v_mfma_f32_16x16x32_bf16 v[4:7], v[148:151], v[226:229], v[4:7]
	v_mfma_f32_16x16x32_bf16 v[0:3], v[156:159], v[226:229], v[0:3]
	s_setprio 0
	s_barrier
	s_add_i32 s83, s83, 2
	s_add_u32 s10, s10, 0x100
	s_addc_u32 s11, s11, 0
	s_add_u32 s81, s81, 0x100
	s_addc_u32 s82, s82, 0
	s_cmp_gt_u32 s83, 29
	s_cbranch_scc0 .LBB0_1034
	s_and_b64 vcc, exec, s[40:41]
	s_cbranch_vccz .LBB0_1037
	s_barrier

; #define PG8_STAGE(bufoff, gbase, voff) do { _Pragma("unroll") for (int _i = 0; _i < 2; ++_i) \
;         __builtin_amdgcn_global_load_lds((const unsigned*)((const char*)(gbase) + (voff)[_i]), (PG8_LAS unsigned*)(lds + (bufoff) + ldsw + _i * 8192), 16, 0, 0); } while (0)
; #define PG8_LDA(dst, b, h) do { _Pragma("unroll") for (int m = 0; m < 4; ++m) _Pragma("unroll") for (int k = 0; k < 2; ++k) dst[m][k] = *(const PG8_LAS bf16x8*)(lds + PG8_SA(b, h) + aoff + m * 2048 + k * 1024); } while (0)
; #define PG8_LDB(dst, b, h) do { _Pragma("unroll") for (int n = 0; n < 2; ++n) _Pragma("unroll") for (int k = 0; k < 2; ++k) dst[n][k] = *(const PG8_LAS bf16x8*)(lds + PG8_SB(b, h) + boff + n * 2048 + k * 1024); } while (0)
; #define PG8_WAIT_V(n) asm volatile("s_waitcnt vmcnt(" #n ")" ::: "memory")
; #define PG8_WAIT_L(n) asm volatile("s_waitcnt lgkmcnt(" #n ")" ::: "memory")
; #define PG8_BAR __builtin_amdgcn_s_barrier()
; #define PG8_SCHED __builtin_amdgcn_sched_barrier(0)
; template <class Epi, class Sched, bool ALIGN_EPI = false, bool SP2 = false>
; __device__ __forceinline__ void gemm_phase(PG8_LAS unsigned char* lds, const Gemm g, const Sched& S, const Epi& E) {
;     ...
;         const bool has_next = S.next(ui + 1, nxt);
;         const char* nA = has_next ? (const char*)g.A + (size_t)nxt.pm * tstep : cA; const char* nB = has_next ? (const char*)g.Bt + (size_t)nxt.pn * tstep : cB;
;         for (int t = 0; t < nt; t += 2) {
;             const bool last = (t == nt - 2);
;             const char* a1 = cA + (size_t)(t + 1) * kstep;
;             const char* a2 = last ? nA : cA + (size_t)(t + 2) * kstep; const char* b2 = last ? nB : cB + (size_t)(t + 2) * kstep;
;             const char* a3 = a2 + kstep; const char* b3 = b2 + kstep;
;             if (last && has_next) S.a_ready(nxt);
;             if constexpr (SP2) {
;             PG8_LDB(B0, 0, 0); PG8_LDB(B1, 0, 1); PG8_SCHED; PG8_LDA(At, 0, 0); PG8_STAGE(PG8_SA(1, 1), a1 + hstep, voffA);
;             PG8_WAIT_V(8); PG8_WAIT_L(0); PG8_BAR; PG8_MMA(0, 0, At, B0); PG8_MMA(0, 1, At, B1); PG8_BAR; PG8_SCHED;
;     ...
;         for (int a = 0; a < 2; ++a)
; #pragma unroll
;             for (int b = 0; b < 2; ++b)
; #pragma unroll
;                 for (int m = 0; m < 4; ++m)
; #pragma unroll
;                     for (int n = 0; n < 2; ++n) acc[a][b][m][n] = (f32x4){0.f, 0.f, 0.f, 0.f};
.LBB0_1113:
	s_ashr_i32 s43, s42, 31
	s_lshl_b64 s[44:45], s[42:43], 22
	s_add_u32 s44, s22, s44
	s_addc_u32 s45, s23, s45
	s_and_b64 s[46:47], s[4:5], exec
	s_cselect_b32 s43, s45, s49
	s_cselect_b32 s69, s44, s48
	s_ashr_i32 s41, s40, 31
	s_lshl_b64 s[46:47], s[40:41], 22
	s_add_u32 s46, s39, s46
	s_addc_u32 s47, s54, s47
	s_and_b64 s[52:53], s[4:5], exec
	s_cselect_b32 s41, s47, s51
	s_cselect_b32 s70, s46, s50
	s_add_u32 s48, s48, 0x200080
	s_addc_u32 s49, s49, 0
	s_add_u32 s71, s50, 0x100
	v_mov_b32_e32 v0, 0
	s_addc_u32 s72, s51, 0
	s_mov_b32 s73, -2
	v_mov_b32_e32 v1, v0
	v_mov_b32_e32 v2, v0
	v_mov_b32_e32 v3, v0
	v_mov_b32_e32 v4, v0
	v_mov_b32_e32 v5, v0
	v_mov_b32_e32 v6, v0
	v_mov_b32_e32 v7, v0
	v_mov_b32_e32 v16, v0
	v_mov_b32_e32 v17, v0
	v_mov_b32_e32 v18, v0
	v_mov_b32_e32 v19, v0
	v_mov_b32_e32 v20, v0
	v_mov_b32_e32 v21, v0
	v_mov_b32_e32 v22, v0
	v_mov_b32_e32 v23, v0
	v_mov_b32_e32 v32, v0
	v_mov_b32_e32 v33, v0
	v_mov_b32_e32 v34, v0
	v_mov_b32_e32 v35, v0
	v_mov_b32_e32 v36, v0
	v_mov_b32_e32 v37, v0
	v_mov_b32_e32 v38, v0
	v_mov_b32_e32 v39, v0
	v_mov_b32_e32 v48, v0
	v_mov_b32_e32 v49, v0
	v_mov_b32_e32 v50, v0
	v_mov_b32_e32 v51, v0
	v_mov_b32_e32 v52, v0
	v_mov_b32_e32 v53, v0
	v_mov_b32_e32 v54, v0
	v_mov_b32_e32 v55, v0
	v_mov_b32_e32 v8, v0
	v_mov_b32_e32 v9, v0
	v_mov_b32_e32 v10, v0
	v_mov_b32_e32 v11, v0
	v_mov_b32_e32 v12, v0
	v_mov_b32_e32 v13, v0
	v_mov_b32_e32 v14, v0
	v_mov_b32_e32 v15, v0
	v_mov_b32_e32 v24, v0
	v_mov_b32_e32 v25, v0
	v_mov_b32_e32 v26, v0
	v_mov_b32_e32 v27, v0
	v_mov_b32_e32 v28, v0
	v_mov_b32_e32 v29, v0
	v_mov_b32_e32 v30, v0
	v_mov_b32_e32 v31, v0
	v_mov_b32_e32 v40, v0
	v_mov_b32_e32 v41, v0
	v_mov_b32_e32 v42, v0
	v_mov_b32_e32 v43, v0
	v_mov_b32_e32 v44, v0
	v_mov_b32_e32 v45, v0
	v_mov_b32_e32 v46, v0
	v_mov_b32_e32 v47, v0
	v_mov_b32_e32 v56, v0
	v_mov_b32_e32 v57, v0
	v_mov_b32_e32 v58, v0
	v_mov_b32_e32 v59, v0
	v_mov_b32_e32 v60, v0
	v_mov_b32_e32 v61, v0
	v_mov_b32_e32 v62, v0
	v_mov_b32_e32 v63, v0
	v_mov_b32_e32 v64, v0
	v_mov_b32_e32 v65, v0
	v_mov_b32_e32 v66, v0
	v_mov_b32_e32 v67, v0
	v_mov_b32_e32 v68, v0
	v_mov_b32_e32 v69, v0
	v_mov_b32_e32 v70, v0
	v_mov_b32_e32 v71, v0
	v_mov_b32_e32 v80, v0
	v_mov_b32_e32 v81, v0
	v_mov_b32_e32 v82, v0
	v_mov_b32_e32 v83, v0
	v_mov_b32_e32 v84, v0
	v_mov_b32_e32 v85, v0
	v_mov_b32_e32 v86, v0
	v_mov_b32_e32 v87, v0
	v_mov_b32_e32 v108, v0
	v_mov_b32_e32 v109, v0
	v_mov_b32_e32 v110, v0
	v_mov_b32_e32 v111, v0
	v_mov_b32_e32 v116, v0
	v_mov_b32_e32 v117, v0
	v_mov_b32_e32 v118, v0
	v_mov_b32_e32 v119, v0
	v_mov_b32_e32 v128, v0
	v_mov_b32_e32 v129, v0
	v_mov_b32_e32 v130, v0
	v_mov_b32_e32 v131, v0
	v_mov_b32_e32 v132, v0
	v_mov_b32_e32 v133, v0
	v_mov_b32_e32 v134, v0
	v_mov_b32_e32 v135, v0
	v_mov_b32_e32 v72, v0
	v_mov_b32_e32 v73, v0
	v_mov_b32_e32 v74, v0
	v_mov_b32_e32 v75, v0
	v_mov_b32_e32 v76, v0
	v_mov_b32_e32 v77, v0
	v_mov_b32_e32 v78, v0
	v_mov_b32_e32 v79, v0
	v_mov_b32_e32 v88, v0
	v_mov_b32_e32 v89, v0
	v_mov_b32_e32 v90, v0
	v_mov_b32_e32 v91, v0
	v_mov_b32_e32 v92, v0
	v_mov_b32_e32 v93, v0
	v_mov_b32_e32 v94, v0
	v_mov_b32_e32 v95, v0
	v_mov_b32_e32 v120, v0
	v_mov_b32_e32 v121, v0
	v_mov_b32_e32 v122, v0
	v_mov_b32_e32 v123, v0
	v_mov_b32_e32 v124, v0
	v_mov_b32_e32 v125, v0
	v_mov_b32_e32 v126, v0
	v_mov_b32_e32 v127, v0
	v_mov_b32_e32 v136, v0
	v_mov_b32_e32 v137, v0
	v_mov_b32_e32 v138, v0
	v_mov_b32_e32 v139, v0
	v_mov_b32_e32 v140, v0
	v_mov_b32_e32 v141, v0
	v_mov_b32_e32 v142, v0
	v_mov_b32_e32 v143, v0
	v_add_u32_e32 v253, 0x80, v160
	v_add_u32_e32 v252, 0x80, v156
	v_add_u32_e32 v251, 0x80, v162
	v_add_u32_e32 v250, 0x80, v158
.LBB0_1114:
	ds_read_b128 v[96:99], v197
	ds_read_b128 v[100:103], v197 offset:1024
	ds_read_b128 v[104:107], v197 offset:2048
	ds_read_b128 v[112:115], v197 offset:3072
	ds_read_b128 v[144:147], v198
	ds_read_b128 v[148:151], v198 offset:1024
	ds_read_b128 v[152:155], v198 offset:2048
	ds_read_b128 v[172:175], v198 offset:3072
	s_add_u32 s50, s48, 0xffe00080
	s_addc_u32 s51, s49, -1
	s_cmpk_eq_i32 s73, 0x7c
	s_cselect_b32 s53, s43, s51
	s_cselect_b32 s52, s69, s50
	s_cselect_b32 s51, s41, s72
	s_cselect_b32 s50, s70, s71
	s_nop 0
	s_add_i32 m0, s56, 0xc000
	ds_read_b128 v[176:179], v199
	ds_read_b128 v[180:183], v199 offset:1024
	ds_read_b128 v[184:187], v199 offset:2048
	ds_read_b128 v[188:191], v199 offset:3072
	ds_read_b128 v[202:205], v199 offset:4096
	ds_read_b128 v[206:209], v199 offset:5120
	ds_read_b128 v[210:213], v199 offset:6144
	ds_read_b128 v[214:217], v199 offset:7168
	global_load_lds_dwordx4 v164, s[48:49]
	s_nop 0
	s_add_i32 m0, s56, 0xe000
	s_nop 0
	global_load_lds_dwordx4 v166, s[48:49]
	s_waitcnt vmcnt(8)
	s_waitcnt lgkmcnt(0)
	s_barrier
; #define PG8_STAGE(bufoff, gbase, voff) do { _Pragma("unroll") for (int _i = 0; _i < 2; ++_i) \
;         __builtin_amdgcn_global_load_lds((const unsigned*)((const char*)(gbase) + (voff)[_i]), (PG8_LAS unsigned*)(lds + (bufoff) + ldsw + _i * 8192), 16, 0, 0); } while (0)
; #define PG8_LDA(dst, b, h) do { _Pragma("unroll") for (int m = 0; m < 4; ++m) _Pragma("unroll") for (int k = 0; k < 2; ++k) dst[m][k] = *(const PG8_LAS bf16x8*)(lds + PG8_SA(b, h) + aoff + m * 2048 + k * 1024); } while (0)
; #define PG8_MMA(ai, bj, At, Bt) do { __builtin_amdgcn_s_setprio(1); _Pragma("unroll") for (int m = 0; m < 4; ++m) _Pragma("unroll") for (int n = 0; n < 2; ++n) _Pragma("unroll") for (int k = 0; k < 2; ++k) \
;         acc[ai][bj][m][n] = __builtin_amdgcn_mfma_f32_16x16x32_bf16(Bt[n][k], At[m][k], acc[ai][bj][m][n], 0, 0, 0); __builtin_amdgcn_s_setprio(0); } while (0)
; #define PG8_WAIT_V(n) asm volatile("s_waitcnt vmcnt(" #n ")" ::: "memory")
; #define PG8_WAIT_L(n) asm volatile("s_waitcnt lgkmcnt(" #n ")" ::: "memory")
; #define PG8_BAR __builtin_amdgcn_s_barrier()
; #define PG8_SCHED __builtin_amdgcn_sched_barrier(0)
; template <class Epi, class Sched, bool ALIGN_EPI = false, bool SP2 = false>
; __device__ __forceinline__ void gemm_phase(PG8_LAS unsigned char* lds, const Gemm g, const Sched& S, const Epi& E) {
;     ...
;             PG8_WAIT_V(8); PG8_WAIT_L(0); PG8_BAR; PG8_MMA(0, 0, At, B0); PG8_MMA(0, 1, At, B1); PG8_BAR; PG8_SCHED;
;             PG8_LDA(At, 0, 1); PG8_STAGE(PG8_SB(0, 0), b2, voffB); PG8_STAGE(PG8_SB(0, 1), b2 + hstep, voffB); PG8_STAGE(PG8_SA(0, 0), a2, voffA);
;             PG8_WAIT_V(8); PG8_WAIT_L(0); PG8_BAR; PG8_MMA(1, 0, At, B0); PG8_MMA(1, 1, At, B1); PG8_BAR; PG8_SCHED;
	s_setprio 1
	s_waitcnt lgkmcnt(0)
	v_mfma_f32_16x16x32_bf16 v[140:143], v[96:99], v[176:179], v[140:143]
	v_mfma_f32_16x16x32_bf16 v[136:139], v[104:107], v[176:179], v[136:139]
	v_mfma_f32_16x16x32_bf16 v[124:127], v[96:99], v[184:187], v[124:127]
	v_mfma_f32_16x16x32_bf16 v[120:123], v[104:107], v[184:187], v[120:123]
	v_mfma_f32_16x16x32_bf16 v[92:95], v[96:99], v[202:205], v[92:95]
	v_mfma_f32_16x16x32_bf16 v[88:91], v[104:107], v[202:205], v[88:91]
	v_mfma_f32_16x16x32_bf16 v[76:79], v[96:99], v[210:213], v[76:79]
	v_mfma_f32_16x16x32_bf16 v[72:75], v[104:107], v[210:213], v[72:75]
	v_mfma_f32_16x16x32_bf16 v[140:143], v[100:103], v[180:183], v[140:143]
	v_mfma_f32_16x16x32_bf16 v[136:139], v[112:115], v[180:183], v[136:139]
	v_mfma_f32_16x16x32_bf16 v[124:127], v[100:103], v[188:191], v[124:127]
	v_mfma_f32_16x16x32_bf16 v[120:123], v[112:115], v[188:191], v[120:123]
	v_mfma_f32_16x16x32_bf16 v[92:95], v[100:103], v[206:209], v[92:95]
	v_mfma_f32_16x16x32_bf16 v[88:91], v[112:115], v[206:209], v[88:91]
	v_mfma_f32_16x16x32_bf16 v[76:79], v[100:103], v[214:217], v[76:79]
	v_mfma_f32_16x16x32_bf16 v[72:75], v[112:115], v[214:217], v[72:75]
	s_setprio 0
	s_setprio 1
	v_mfma_f32_16x16x32_bf16 v[132:135], v[144:147], v[176:179], v[132:135]
	v_mfma_f32_16x16x32_bf16 v[128:131], v[152:155], v[176:179], v[128:131]
	v_mfma_f32_16x16x32_bf16 v[116:119], v[144:147], v[184:187], v[116:119]
	v_mfma_f32_16x16x32_bf16 v[108:111], v[152:155], v[184:187], v[108:111]
	v_mfma_f32_16x16x32_bf16 v[84:87], v[144:147], v[202:205], v[84:87]
	v_mfma_f32_16x16x32_bf16 v[80:83], v[152:155], v[202:205], v[80:83]
	v_mfma_f32_16x16x32_bf16 v[68:71], v[144:147], v[210:213], v[68:71]
	v_mfma_f32_16x16x32_bf16 v[64:67], v[152:155], v[210:213], v[64:67]
	v_mfma_f32_16x16x32_bf16 v[132:135], v[148:151], v[180:183], v[132:135]
	v_mfma_f32_16x16x32_bf16 v[128:131], v[172:175], v[180:183], v[128:131]
	v_mfma_f32_16x16x32_bf16 v[116:119], v[148:151], v[188:191], v[116:119]
	v_mfma_f32_16x16x32_bf16 v[108:111], v[172:175], v[188:191], v[108:111]
	v_mfma_f32_16x16x32_bf16 v[84:87], v[148:151], v[206:209], v[84:87]
	v_mfma_f32_16x16x32_bf16 v[80:83], v[172:175], v[206:209], v[80:83]
	v_mfma_f32_16x16x32_bf16 v[68:71], v[148:151], v[214:217], v[68:71]
	v_mfma_f32_16x16x32_bf16 v[64:67], v[172:175], v[214:217], v[64:67]
	s_setprio 0
	s_barrier
	s_add_i32 s74, s65, s55
	s_mov_b64 s[96:97], s[50:51]
	s_nop 0
	s_mov_b32 m0, s74
	ds_read_b128 v[176:179], v199 offset:16384
	ds_read_b128 v[180:183], v199 offset:17408
	ds_read_b128 v[184:187], v199 offset:18432
	ds_read_b128 v[188:191], v199 offset:19456
	ds_read_b128 v[202:205], v199 offset:20480
	ds_read_b128 v[206:209], v199 offset:21504
	ds_read_b128 v[210:213], v199 offset:22528
	ds_read_b128 v[214:217], v199 offset:23552
	global_load_lds_dwordx4 v158, s[50:51]
	s_add_i32 m0, s74, 0x2000
	s_add_u32 s74, s50, 0x200000
	s_nop 0
	s_addc_u32 s75, s51, 0
	s_add_i32 s76, s67, s55
	global_load_lds_dwordx4 v162, s[50:51]
	s_nop 0
	s_mov_b32 m0, s76
	s_nop 0
	global_load_lds_dwordx4 v158, s[74:75]
	s_nop 0
	s_add_i32 m0, s76, 0x2000
	s_nop 0
	global_load_lds_dwordx4 v162, s[74:75]
	s_mov_b64 s[98:99], s[52:53]
	s_nop 0
	s_mov_b32 m0, s56
	s_nop 0
	global_load_lds_dwordx4 v156, s[52:53]
	s_mov_b32 m0, s57
	s_nop 0
	global_load_lds_dwordx4 v160, s[52:53]
	s_waitcnt vmcnt(8)
	s_waitcnt lgkmcnt(0)
	s_barrier
	s_setprio 1
	s_waitcnt lgkmcnt(0)
	v_mfma_f32_16x16x32_bf16 v[60:63], v[96:99], v[176:179], v[60:63]
	v_mfma_f32_16x16x32_bf16 v[56:59], v[104:107], v[176:179], v[56:59]
	v_mfma_f32_16x16x32_bf16 v[44:47], v[96:99], v[184:187], v[44:47]
	v_mfma_f32_16x16x32_bf16 v[40:43], v[104:107], v[184:187], v[40:43]
	v_mfma_f32_16x16x32_bf16 v[28:31], v[96:99], v[202:205], v[28:31]
	v_mfma_f32_16x16x32_bf16 v[24:27], v[104:107], v[202:205], v[24:27]
	v_mfma_f32_16x16x32_bf16 v[12:15], v[96:99], v[210:213], v[12:15]
	v_mfma_f32_16x16x32_bf16 v[8:11], v[104:107], v[210:213], v[8:11]
	v_mfma_f32_16x16x32_bf16 v[60:63], v[100:103], v[180:183], v[60:63]
	v_mfma_f32_16x16x32_bf16 v[56:59], v[112:115], v[180:183], v[56:59]
	v_mfma_f32_16x16x32_bf16 v[44:47], v[100:103], v[188:191], v[44:47]
	v_mfma_f32_16x16x32_bf16 v[40:43], v[112:115], v[188:191], v[40:43]
	v_mfma_f32_16x16x32_bf16 v[28:31], v[100:103], v[206:209], v[28:31]
	v_mfma_f32_16x16x32_bf16 v[24:27], v[112:115], v[206:209], v[24:27]
	v_mfma_f32_16x16x32_bf16 v[12:15], v[100:103], v[214:217], v[12:15]
	v_mfma_f32_16x16x32_bf16 v[8:11], v[112:115], v[214:217], v[8:11]
	s_setprio 0
	s_setprio 1
	v_mfma_f32_16x16x32_bf16 v[52:55], v[144:147], v[176:179], v[52:55]
	v_mfma_f32_16x16x32_bf16 v[48:51], v[152:155], v[176:179], v[48:51]
	v_mfma_f32_16x16x32_bf16 v[36:39], v[144:147], v[184:187], v[36:39]
	v_mfma_f32_16x16x32_bf16 v[32:35], v[152:155], v[184:187], v[32:35]
	v_mfma_f32_16x16x32_bf16 v[20:23], v[144:147], v[202:205], v[20:23]
	v_mfma_f32_16x16x32_bf16 v[16:19], v[152:155], v[202:205], v[16:19]
	v_mfma_f32_16x16x32_bf16 v[4:7], v[144:147], v[210:213], v[4:7]
	v_mfma_f32_16x16x32_bf16 v[0:3], v[152:155], v[210:213], v[0:3]
	v_mfma_f32_16x16x32_bf16 v[52:55], v[148:151], v[180:183], v[52:55]
	v_mfma_f32_16x16x32_bf16 v[48:51], v[172:175], v[180:183], v[48:51]
	v_mfma_f32_16x16x32_bf16 v[36:39], v[148:151], v[188:191], v[36:39]
	v_mfma_f32_16x16x32_bf16 v[32:35], v[172:175], v[188:191], v[32:35]
	v_mfma_f32_16x16x32_bf16 v[20:23], v[148:151], v[206:209], v[20:23]
	v_mfma_f32_16x16x32_bf16 v[16:19], v[172:175], v[206:209], v[16:19]
	v_mfma_f32_16x16x32_bf16 v[4:7], v[148:151], v[214:217], v[4:7]
	v_mfma_f32_16x16x32_bf16 v[0:3], v[172:175], v[214:217], v[0:3]
	s_setprio 0
	s_barrier
; #define PG8_STAGE(bufoff, gbase, voff) do { _Pragma("unroll") for (int _i = 0; _i < 2; ++_i) \
;         __builtin_amdgcn_global_load_lds((const unsigned*)((const char*)(gbase) + (voff)[_i]), (PG8_LAS unsigned*)(lds + (bufoff) + ldsw + _i * 8192), 16, 0, 0); } while (0)
; #define PG8_LDA(dst, b, h) do { _Pragma("unroll") for (int m = 0; m < 4; ++m) _Pragma("unroll") for (int k = 0; k < 2; ++k) dst[m][k] = *(const PG8_LAS bf16x8*)(lds + PG8_SA(b, h) + aoff + m * 2048 + k * 1024); } while (0)
; #define PG8_LDB(dst, b, h) do { _Pragma("unroll") for (int n = 0; n < 2; ++n) _Pragma("unroll") for (int k = 0; k < 2; ++k) dst[n][k] = *(const PG8_LAS bf16x8*)(lds + PG8_SB(b, h) + boff + n * 2048 + k * 1024); } while (0)
; #define PG8_MMA(ai, bj, At, Bt) do { __builtin_amdgcn_s_setprio(1); _Pragma("unroll") for (int m = 0; m < 4; ++m) _Pragma("unroll") for (int n = 0; n < 2; ++n) _Pragma("unroll") for (int k = 0; k < 2; ++k) \
;         acc[ai][bj][m][n] = __builtin_amdgcn_mfma_f32_16x16x32_bf16(Bt[n][k], At[m][k], acc[ai][bj][m][n], 0, 0, 0); __builtin_amdgcn_s_setprio(0); } while (0)
; #define PG8_WAIT_V(n) asm volatile("s_waitcnt vmcnt(" #n ")" ::: "memory")
; #define PG8_WAIT_L(n) asm volatile("s_waitcnt lgkmcnt(" #n ")" ::: "memory")
; #define PG8_BAR __builtin_amdgcn_s_barrier()
; #define PG8_SCHED __builtin_amdgcn_sched_barrier(0)
; template <class Epi, class Sched, bool ALIGN_EPI = false, bool SP2 = false>
; __device__ __forceinline__ void gemm_phase(PG8_LAS unsigned char* lds, const Gemm g, const Sched& S, const Epi& E) {
;     ...
;             PG8_LDB(B0, 1, 0); PG8_LDB(B1, 1, 1); PG8_SCHED; PG8_LDA(At, 1, 0); PG8_STAGE(PG8_SA(0, 1), a2 + hstep, voffA);
;             PG8_WAIT_V(8); PG8_WAIT_L(0); PG8_BAR; PG8_MMA(0, 0, At, B0); PG8_MMA(0, 1, At, B1); PG8_BAR; PG8_SCHED;
;             PG8_LDA(At, 1, 1); PG8_STAGE(PG8_SB(1, 0), b3, voffB); PG8_STAGE(PG8_SB(1, 1), b3 + hstep, voffB); PG8_STAGE(PG8_SA(1, 0), a3, voffA);
;             PG8_WAIT_V(8); PG8_WAIT_L(0); PG8_BAR; PG8_MMA(1, 0, At, B0); PG8_MMA(1, 1, At, B1); PG8_BAR; PG8_SCHED;
	s_add_i32 s74, 0, 0x18000
	s_add_i32 s75, 0, 0x1c000
	v_add_u32_e32 v112, s74, v195
	v_add_u32_e32 v172, s75, v195
	ds_read_b128 v[96:99], v112
	ds_read_b128 v[100:103], v112 offset:1024
	ds_read_b128 v[104:107], v112 offset:2048
	ds_read_b128 v[112:115], v112 offset:3072
	ds_read_b128 v[144:147], v172
	ds_read_b128 v[148:151], v172 offset:1024
	ds_read_b128 v[152:155], v172 offset:2048
	ds_read_b128 v[172:175], v172 offset:3072
	s_add_u32 s52, s52, 0x200000
	s_addc_u32 s53, s53, 0
	s_mov_b32 m0, s58
	s_nop 0
	ds_read_b128 v[176:179], v199 offset:32768
	ds_read_b128 v[180:183], v199 offset:33792
	ds_read_b128 v[184:187], v199 offset:34816
	ds_read_b128 v[188:191], v199 offset:35840
	ds_read_b128 v[202:205], v199 offset:36864
	ds_read_b128 v[206:209], v199 offset:37888
	ds_read_b128 v[210:213], v199 offset:38912
	ds_read_b128 v[214:217], v199 offset:39936
	global_load_lds_dwordx4 v156, s[52:53]
	s_nop 0
	s_mov_b32 m0, s59
	s_nop 0
	global_load_lds_dwordx4 v160, s[52:53]
	s_waitcnt vmcnt(8)
	s_waitcnt lgkmcnt(0)
	s_barrier
	s_setprio 1
	s_waitcnt lgkmcnt(0)
	v_mfma_f32_16x16x32_bf16 v[140:143], v[96:99], v[176:179], v[140:143]
	v_mfma_f32_16x16x32_bf16 v[136:139], v[104:107], v[176:179], v[136:139]
	v_mfma_f32_16x16x32_bf16 v[124:127], v[96:99], v[184:187], v[124:127]
	v_mfma_f32_16x16x32_bf16 v[120:123], v[104:107], v[184:187], v[120:123]
	v_mfma_f32_16x16x32_bf16 v[92:95], v[96:99], v[202:205], v[92:95]
	v_mfma_f32_16x16x32_bf16 v[88:91], v[104:107], v[202:205], v[88:91]
	v_mfma_f32_16x16x32_bf16 v[76:79], v[96:99], v[210:213], v[76:79]
	v_mfma_f32_16x16x32_bf16 v[72:75], v[104:107], v[210:213], v[72:75]
	v_mfma_f32_16x16x32_bf16 v[140:143], v[100:103], v[180:183], v[140:143]
	v_mfma_f32_16x16x32_bf16 v[136:139], v[112:115], v[180:183], v[136:139]
	v_mfma_f32_16x16x32_bf16 v[124:127], v[100:103], v[188:191], v[124:127]
	v_mfma_f32_16x16x32_bf16 v[120:123], v[112:115], v[188:191], v[120:123]
	v_mfma_f32_16x16x32_bf16 v[92:95], v[100:103], v[206:209], v[92:95]
	v_mfma_f32_16x16x32_bf16 v[88:91], v[112:115], v[206:209], v[88:91]
	v_mfma_f32_16x16x32_bf16 v[76:79], v[100:103], v[214:217], v[76:79]
	v_mfma_f32_16x16x32_bf16 v[72:75], v[112:115], v[214:217], v[72:75]
	s_setprio 0
	s_setprio 1
	v_mfma_f32_16x16x32_bf16 v[132:135], v[144:147], v[176:179], v[132:135]
	v_mfma_f32_16x16x32_bf16 v[128:131], v[152:155], v[176:179], v[128:131]
	v_mfma_f32_16x16x32_bf16 v[116:119], v[144:147], v[184:187], v[116:119]
	v_mfma_f32_16x16x32_bf16 v[108:111], v[152:155], v[184:187], v[108:111]
	v_mfma_f32_16x16x32_bf16 v[84:87], v[144:147], v[202:205], v[84:87]
	v_mfma_f32_16x16x32_bf16 v[80:83], v[152:155], v[202:205], v[80:83]
	v_mfma_f32_16x16x32_bf16 v[68:71], v[144:147], v[210:213], v[68:71]
	v_mfma_f32_16x16x32_bf16 v[64:67], v[152:155], v[210:213], v[64:67]
	v_mfma_f32_16x16x32_bf16 v[132:135], v[148:151], v[180:183], v[132:135]
	v_mfma_f32_16x16x32_bf16 v[128:131], v[172:175], v[180:183], v[128:131]
	v_mfma_f32_16x16x32_bf16 v[116:119], v[148:151], v[188:191], v[116:119]
	v_mfma_f32_16x16x32_bf16 v[108:111], v[172:175], v[188:191], v[108:111]
	v_mfma_f32_16x16x32_bf16 v[84:87], v[148:151], v[206:209], v[84:87]
	v_mfma_f32_16x16x32_bf16 v[80:83], v[172:175], v[206:209], v[80:83]
	v_mfma_f32_16x16x32_bf16 v[68:71], v[148:151], v[214:217], v[68:71]
	v_mfma_f32_16x16x32_bf16 v[64:67], v[172:175], v[214:217], v[64:67]
	s_setprio 0
	s_barrier
	s_add_i32 s52, s74, s55
	s_nop 0
	s_mov_b32 m0, s52
	ds_read_b128 v[176:179], v199 offset:49152
	ds_read_b128 v[180:183], v199 offset:50176
	ds_read_b128 v[184:187], v199 offset:51200
	ds_read_b128 v[188:191], v199 offset:52224
	ds_read_b128 v[202:205], v199 offset:53248
	ds_read_b128 v[206:209], v199 offset:54272
	ds_read_b128 v[210:213], v199 offset:55296
	ds_read_b128 v[214:217], v199 offset:56320
	global_load_lds_dwordx4 v250, s[96:97]
	s_add_i32 m0, s52, 0x2000
	s_add_u32 s50, s50, 0x200080
	s_nop 0
	s_addc_u32 s51, s51, 0
	s_add_i32 s52, s75, s55
	global_load_lds_dwordx4 v251, s[96:97]
	s_nop 0
	s_mov_b32 m0, s52
	s_nop 0
	global_load_lds_dwordx4 v158, s[50:51]
	s_nop 0
	s_add_i32 m0, s52, 0x2000
	s_nop 0
	global_load_lds_dwordx4 v162, s[50:51]
	s_nop 0
	s_mov_b32 m0, s61
	s_nop 0
	global_load_lds_dwordx4 v252, s[98:99]
	s_nop 0
	s_mov_b32 m0, s62
	s_nop 0
	global_load_lds_dwordx4 v253, s[98:99]
	s_waitcnt vmcnt(8)
	s_waitcnt lgkmcnt(0)
	s_barrier
	s_setprio 1
	s_waitcnt lgkmcnt(0)
	v_mfma_f32_16x16x32_bf16 v[60:63], v[96:99], v[176:179], v[60:63]
	v_mfma_f32_16x16x32_bf16 v[56:59], v[104:107], v[176:179], v[56:59]
	v_mfma_f32_16x16x32_bf16 v[44:47], v[96:99], v[184:187], v[44:47]
	v_mfma_f32_16x16x32_bf16 v[40:43], v[104:107], v[184:187], v[40:43]
	v_mfma_f32_16x16x32_bf16 v[28:31], v[96:99], v[202:205], v[28:31]
	v_mfma_f32_16x16x32_bf16 v[24:27], v[104:107], v[202:205], v[24:27]
	v_mfma_f32_16x16x32_bf16 v[12:15], v[96:99], v[210:213], v[12:15]
	v_mfma_f32_16x16x32_bf16 v[8:11], v[104:107], v[210:213], v[8:11]
	v_mfma_f32_16x16x32_bf16 v[60:63], v[100:103], v[180:183], v[60:63]
	v_mfma_f32_16x16x32_bf16 v[56:59], v[112:115], v[180:183], v[56:59]
	v_mfma_f32_16x16x32_bf16 v[44:47], v[100:103], v[188:191], v[44:47]
	v_mfma_f32_16x16x32_bf16 v[40:43], v[112:115], v[188:191], v[40:43]
	v_mfma_f32_16x16x32_bf16 v[28:31], v[100:103], v[206:209], v[28:31]
	v_mfma_f32_16x16x32_bf16 v[24:27], v[112:115], v[206:209], v[24:27]
	v_mfma_f32_16x16x32_bf16 v[12:15], v[100:103], v[214:217], v[12:15]
	v_mfma_f32_16x16x32_bf16 v[8:11], v[112:115], v[214:217], v[8:11]
	s_setprio 0
	s_setprio 1
	v_mfma_f32_16x16x32_bf16 v[52:55], v[144:147], v[176:179], v[52:55]
	v_mfma_f32_16x16x32_bf16 v[48:51], v[152:155], v[176:179], v[48:51]
	v_mfma_f32_16x16x32_bf16 v[36:39], v[144:147], v[184:187], v[36:39]
	v_mfma_f32_16x16x32_bf16 v[32:35], v[152:155], v[184:187], v[32:35]
	v_mfma_f32_16x16x32_bf16 v[20:23], v[144:147], v[202:205], v[20:23]
	v_mfma_f32_16x16x32_bf16 v[16:19], v[152:155], v[202:205], v[16:19]
	v_mfma_f32_16x16x32_bf16 v[4:7], v[144:147], v[210:213], v[4:7]
	v_mfma_f32_16x16x32_bf16 v[0:3], v[152:155], v[210:213], v[0:3]
	v_mfma_f32_16x16x32_bf16 v[52:55], v[148:151], v[180:183], v[52:55]
	v_mfma_f32_16x16x32_bf16 v[48:51], v[172:175], v[180:183], v[48:51]
	v_mfma_f32_16x16x32_bf16 v[36:39], v[148:151], v[188:191], v[36:39]
	v_mfma_f32_16x16x32_bf16 v[32:35], v[172:175], v[188:191], v[32:35]
	v_mfma_f32_16x16x32_bf16 v[20:23], v[148:151], v[206:209], v[20:23]
	v_mfma_f32_16x16x32_bf16 v[16:19], v[172:175], v[206:209], v[16:19]
	v_mfma_f32_16x16x32_bf16 v[4:7], v[148:151], v[214:217], v[4:7]
	v_mfma_f32_16x16x32_bf16 v[0:3], v[172:175], v[214:217], v[0:3]
	s_setprio 0
	s_barrier
	s_add_i32 s73, s73, 2
	s_add_u32 s48, s48, 0x100
	s_addc_u32 s49, s49, 0
	s_add_u32 s71, s71, 0x100
	s_addc_u32 s72, s72, 0
	s_cmpk_gt_u32 s73, 0x7d
	s_cbranch_scc0 .LBB0_1114
	s_and_b64 vcc, exec, s[34:35]
	s_cbranch_vccz .LBB0_1117
	s_barrier

; __global__ void __launch_bounds__(512, 2) fwd_mega(Args a) {
	.amdhsa_kernel _Z8fwd_mega4Args
		.amdhsa_group_segment_fixed_size 0
		.amdhsa_private_segment_fixed_size 0
		.amdhsa_kernarg_size 424
		.amdhsa_user_sgpr_count 2
		.amdhsa_user_sgpr_dispatch_ptr 0
		.amdhsa_user_sgpr_queue_ptr 0
		.amdhsa_user_sgpr_kernarg_segment_ptr 1
		.amdhsa_user_sgpr_dispatch_id 0
		.amdhsa_user_sgpr_kernarg_preload_length 0
		.amdhsa_user_sgpr_kernarg_preload_offset 0
		.amdhsa_user_sgpr_private_segment_size 0
		.amdhsa_uses_dynamic_stack 0
		.amdhsa_enable_private_segment 0
		.amdhsa_system_sgpr_workgroup_id_x 1
		.amdhsa_system_sgpr_workgroup_id_y 0
		.amdhsa_system_sgpr_workgroup_id_z 0
		.amdhsa_system_sgpr_workgroup_info 0
		.amdhsa_system_vgpr_workitem_id 2
		.amdhsa_next_free_vgpr 254
		.amdhsa_next_free_sgpr 102
		.amdhsa_accum_offset 256
		.amdhsa_reserve_vcc 1
		.amdhsa_float_round_mode_32 0
		.amdhsa_float_round_mode_16_64 0
		.amdhsa_float_denorm_mode_32 3
		.amdhsa_float_denorm_mode_16_64 3
		.amdhsa_dx10_clamp 1
		.amdhsa_ieee_mode 1
		.amdhsa_fp16_overflow 0
		.amdhsa_tg_split 0
		.amdhsa_exception_fp_ieee_invalid_op 0
		.amdhsa_exception_fp_denorm_src 0
		.amdhsa_exception_fp_ieee_div_zero 0
		.amdhsa_exception_fp_ieee_overflow 0
		.amdhsa_exception_fp_ieee_underflow 0
		.amdhsa_exception_fp_ieee_inexact 0
		.amdhsa_exception_int_div_zero 0
	.end_amdhsa_kernel

; __device__ __forceinline__ CArgs* kargs() { CArgs* p = (CArgs*)__builtin_amdgcn_kernarg_segment_ptr(); asm volatile("" : "+s"(p)); return p; }
; __global__ void __launch_bounds__(512, 2) fwd_mega(Args a) {
amdhsa.kernels:
  - .agpr_count:     0
    .args:
      - .offset:         0
        .size:           168
        .value_kind:     by_value
      - .offset:         168
        .size:           4
        .value_kind:     hidden_block_count_x
      - .offset:         172
        .size:           4
        .value_kind:     hidden_block_count_y
      - .offset:         176
        .size:           4
        .value_kind:     hidden_block_count_z
      - .offset:         180
        .size:           2
        .value_kind:     hidden_group_size_x
      - .offset:         182
        .size:           2
        .value_kind:     hidden_group_size_y
      - .offset:         184
        .size:           2
        .value_kind:     hidden_group_size_z
      - .offset:         186
        .size:           2
        .value_kind:     hidden_remainder_x
      - .offset:         188
        .size:           2
        .value_kind:     hidden_remainder_y
      - .offset:         190
        .size:           2
        .value_kind:     hidden_remainder_z
      - .offset:         208
        .size:           8
        .value_kind:     hidden_global_offset_x
      - .offset:         216
        .size:           8
        .value_kind:     hidden_global_offset_y
      - .offset:         224
        .size:           8
        .value_kind:     hidden_global_offset_z
      - .offset:         232
        .size:           2
        .value_kind:     hidden_grid_dims
      - .offset:         256
        .size:           8
        .value_kind:     hidden_multigrid_sync_arg
      - .offset:         288
        .size:           4
        .value_kind:     hidden_dynamic_lds_size
    .group_segment_fixed_size: 0
    .kernarg_segment_align: 8
    .kernarg_segment_size: 424
    .language:       OpenCL C
    .language_version:
      - 2
      - 0
    .max_flat_workgroup_size: 512
    .name:           _Z8fwd_mega4Args
    .private_segment_fixed_size: 0
    .sgpr_count:     108
    .sgpr_spill_count: 0
    .symbol:         _Z8fwd_mega4Args.kd
    .uniform_work_group_size: 1
    .uses_dynamic_stack: false
    .vgpr_count:     254
    .vgpr_spill_count: 0
    .wavefront_size: 64
